# barrier waiters poll the cross-XCD generation directly; K-loop fragment reads with progressive waits; all 8 DMA pieces in post-barrier run
# speedup vs baseline: 1.0017x; 1.0017x over previous
.LBB0_148:
	s_or_b64 exec, exec, s[8:9]
	v_cvt_f32_u32_e32 v4, v2
	s_waitcnt vmcnt(0)
	v_readfirstlane_b32 s6, v3
	v_sub_u32_e32 v3, 0, v2
	v_rcp_iflag_f32_e32 v4, v4
	v_add_u32_e32 v5, s6, v1
	v_mul_f32_e32 v4, 0x4f7ffffe, v4
	v_cvt_u32_f32_e32 v4, v4
	v_mul_lo_u32 v1, v3, v4
	v_mul_hi_u32 v1, v4, v1
	v_add_u32_e32 v1, v4, v1
	v_mul_hi_u32 v1, v5, v1
	v_mul_lo_u32 v3, v1, v2
	v_sub_u32_e32 v3, v5, v3
	v_add_u32_e32 v4, 1, v1
	v_cmp_ge_u32_e32 vcc, v3, v2
	s_nop 1
	v_cndmask_b32_e32 v1, v1, v4, vcc
	v_sub_u32_e32 v4, v3, v2
	v_cndmask_b32_e32 v3, v3, v4, vcc
	v_add_u32_e32 v4, 1, v1
	v_cmp_ge_u32_e32 vcc, v3, v2
	v_add_u32_e32 v3, 1, v5
	s_nop 0
	v_cndmask_b32_e32 v1, v1, v4, vcc
	v_mul_lo_u32 v4, v2, v1
	v_add_u32_e32 v2, v4, v2
	v_cmp_ne_u32_e32 vcc, v3, v2
	s_and_saveexec_b64 s[6:7], vcc
	s_xor_b64 s[6:7], exec, s[6:7]
	s_cbranch_execz .LBB0_162
	s_waitcnt lgkmcnt(0)
	buffer_inv sc1
	v_mov_b32_e32 v0, 0
	v_mov_b32_e32 v1, 0
	s_add_u32 s12, s86, 0xe7b4500
	s_addc_u32 s13, s87, 0
	global_load_dword v0, v0, s[12:13] sc1
	s_waitcnt vmcnt(0)
	v_cmp_eq_u32_e32 vcc, v0, v1
	s_and_saveexec_b64 s[8:9], vcc
	s_cbranch_execz .LBB0_161
	s_add_u32 s10, s86, 0xe7b1200
	s_addc_u32 s11, s87, 0
	s_mov_b32 s26, 1
	s_mov_b64 s[14:15], 0
	v_mov_b32_e32 v0, 0
	s_branch .LBB0_152

.LBB0_211:
	s_or_b64 exec, exec, s[8:9]
	v_cvt_f32_u32_e32 v4, v2
	s_waitcnt vmcnt(0)
	v_readfirstlane_b32 s6, v3
	v_sub_u32_e32 v3, 0, v2
	v_rcp_iflag_f32_e32 v4, v4
	v_add_u32_e32 v5, s6, v1
	v_mul_f32_e32 v4, 0x4f7ffffe, v4
	v_cvt_u32_f32_e32 v4, v4
	v_mul_lo_u32 v1, v3, v4
	v_mul_hi_u32 v1, v4, v1
	v_add_u32_e32 v1, v4, v1
	v_mul_hi_u32 v1, v5, v1
	v_mul_lo_u32 v3, v1, v2
	v_sub_u32_e32 v3, v5, v3
	v_add_u32_e32 v4, 1, v1
	v_cmp_ge_u32_e32 vcc, v3, v2
	s_nop 1
	v_cndmask_b32_e32 v1, v1, v4, vcc
	v_sub_u32_e32 v4, v3, v2
	v_cndmask_b32_e32 v3, v3, v4, vcc
	v_add_u32_e32 v4, 1, v1
	v_cmp_ge_u32_e32 vcc, v3, v2
	v_add_u32_e32 v3, 1, v5
	s_nop 0
	v_cndmask_b32_e32 v1, v1, v4, vcc
	v_mul_lo_u32 v4, v2, v1
	v_add_u32_e32 v2, v4, v2
	v_cmp_ne_u32_e32 vcc, v3, v2
	s_and_saveexec_b64 s[6:7], vcc
	s_xor_b64 s[6:7], exec, s[6:7]
	s_cbranch_execz .LBB0_225
	s_waitcnt lgkmcnt(0)
	buffer_inv sc1
	v_mov_b32_e32 v0, 0
	v_mov_b32_e32 v1, 1
	s_add_u32 s12, s86, 0xe7b4500
	s_addc_u32 s13, s87, 0
	global_load_dword v0, v0, s[12:13] sc1
	s_waitcnt vmcnt(0)
	v_cmp_eq_u32_e32 vcc, v0, v1
	s_and_saveexec_b64 s[8:9], vcc
	s_cbranch_execz .LBB0_224
	s_add_u32 s10, s86, 0xe7b1200
	s_addc_u32 s11, s87, 0
	s_mov_b32 s26, 1
	s_mov_b64 s[14:15], 0
	v_mov_b32_e32 v0, 0
	s_branch .LBB0_215

.LBB0_248:
	s_mul_hi_i32 s0, s30, 0x38e38e39
	s_lshr_b32 s1, s0, 31
	s_ashr_i32 s31, s0, 4
	s_add_i32 s31, s31, s1
	v_readfirstlane_b32 s5, v128
	s_mul_i32 s0, s31, 0x48
	s_lshr_b32 s16, s5, 1
	s_sub_i32 s4, s30, s0
	s_and_b32 s16, s16, 0x1ffff80
	s_lshl_b32 s0, s4, 19
	v_or_b32_e32 v8, s16, v189
	s_and_b32 s16, s5, 0xc0
	s_lshl_b32 s5, s5, 4
	v_add_u32_e32 v0, s0, v134
	v_lshlrev_b32_e32 v153, 7, v8
	v_or_b32_e32 v8, s16, v189
	s_and_b32 s5, s5, 0x7ffffc00
	v_add_u32_e32 v1, s0, v138
	v_lshl_or_b32 v155, v8, 7, v139
	v_and_b32_e32 v8, 0xfffff870, v0
	s_mov_b32 m0, s5
	v_add_u32_e32 v2, s0, v140
	global_load_lds_dwordx4 v8, s[86:87]
	v_and_b32_e32 v1, 0xfffff870, v1
	s_add_i32 m0, s5, 0x2000
	s_lshl_b32 s1, s31, 19
	v_add_u32_e32 v3, s0, v142
	global_load_lds_dwordx4 v1, s[86:87]
	v_and_b32_e32 v1, 0xfffff870, v2
	s_add_i32 m0, s5, 0x4000
	v_add_u32_e32 v4, s1, v144
	s_add_i32 s16, s5, 0x8000
	global_load_lds_dwordx4 v1, s[86:87]
	v_and_b32_e32 v1, 0xfffff870, v3
	s_add_i32 m0, s5, 0x6000
	v_add_u32_e32 v5, s1, v146
	global_load_lds_dwordx4 v1, s[86:87]
	v_and_b32_e32 v1, 0xfffff870, v4
	s_mov_b32 m0, s16
	v_add_u32_e32 v6, s1, v148
	global_load_lds_dwordx4 v1, s[86:87]
	v_and_b32_e32 v1, 0xfffff870, v5
	s_add_i32 m0, s5, 0xa000
	v_add_u32_e32 v7, s1, v150
	global_load_lds_dwordx4 v1, s[86:87]
	v_and_b32_e32 v1, 0xfffff870, v6
	s_add_i32 m0, s5, 0xc000
	v_and_b32_e32 v136, -16, v0
	global_load_lds_dwordx4 v1, s[86:87]
	v_and_b32_e32 v1, 0xfffff870, v7
	s_add_i32 m0, s5, 0xe000
	v_add_u32_e32 v0, s0, v152
	global_load_lds_dwordx4 v1, s[86:87]
	v_lshl_add_u64 v[162:163], s[14:15], 0, v[136:137]
	v_and_b32_e32 v136, -16, v0
	v_add_u32_e32 v0, s0, v154
	v_lshl_add_u64 v[164:165], s[14:15], 0, v[136:137]
	v_and_b32_e32 v136, -16, v0
	v_add_u32_e32 v0, s0, v156
	v_lshl_add_u64 v[166:167], s[14:15], 0, v[136:137]
	v_and_b32_e32 v136, -16, v0
	v_lshl_add_u64 v[168:169], s[14:15], 0, v[136:137]
	v_and_b32_e32 v136, -16, v4
	v_add_u32_e32 v0, s1, v158
	v_lshl_add_u64 v[170:171], s[14:15], 0, v[136:137]
	v_and_b32_e32 v136, -16, v0
	s_waitcnt vmcnt(0)
	v_lshl_add_u64 v[172:173], s[14:15], 0, v[136:137]
	v_and_b32_e32 v136, -16, v6
	v_add_u32_e32 v0, s1, v160
	v_lshl_add_u64 v[174:175], s[14:15], 0, v[136:137]
	v_and_b32_e32 v136, -16, v0
	v_lshl_add_u64 v[176:177], s[14:15], 0, v[136:137]
	s_mov_b64 s[0:1], 0
	s_mov_b32 s16, s91
	v_mov_b32_e32 v56, v137
	v_mov_b32_e32 v57, v137
	v_mov_b32_e32 v58, v137
	v_mov_b32_e32 v59, v137
	v_mov_b32_e32 v0, v137
	v_mov_b32_e32 v1, v137
	v_mov_b32_e32 v2, v137
	v_mov_b32_e32 v3, v137
	v_mov_b32_e32 v64, v137
	v_mov_b32_e32 v65, v137
	v_mov_b32_e32 v66, v137
	v_mov_b32_e32 v67, v137
	v_mov_b32_e32 v68, v137
	v_mov_b32_e32 v69, v137
	v_mov_b32_e32 v70, v137
	v_mov_b32_e32 v71, v137
	v_mov_b32_e32 v4, v137
	v_mov_b32_e32 v5, v137
	v_mov_b32_e32 v6, v137
	v_mov_b32_e32 v7, v137
	v_mov_b32_e32 v8, v137
	v_mov_b32_e32 v9, v137
	v_mov_b32_e32 v10, v137
	v_mov_b32_e32 v11, v137
	v_mov_b32_e32 v72, v137
	v_mov_b32_e32 v73, v137
	v_mov_b32_e32 v74, v137
	v_mov_b32_e32 v75, v137
	v_mov_b32_e32 v76, v137
	v_mov_b32_e32 v77, v137
	v_mov_b32_e32 v78, v137
	v_mov_b32_e32 v79, v137
	v_mov_b32_e32 v12, v137
	v_mov_b32_e32 v13, v137
	v_mov_b32_e32 v14, v137
	v_mov_b32_e32 v15, v137
	v_mov_b32_e32 v16, v137
	v_mov_b32_e32 v17, v137
	v_mov_b32_e32 v18, v137
	v_mov_b32_e32 v19, v137
	v_mov_b32_e32 v80, v137
	v_mov_b32_e32 v81, v137
	v_mov_b32_e32 v82, v137
	v_mov_b32_e32 v83, v137
	v_mov_b32_e32 v84, v137
	v_mov_b32_e32 v85, v137
	v_mov_b32_e32 v86, v137
	v_mov_b32_e32 v87, v137
	v_mov_b32_e32 v20, v137
	v_mov_b32_e32 v21, v137
	v_mov_b32_e32 v22, v137
	v_mov_b32_e32 v23, v137
	v_mov_b32_e32 v24, v137
	v_mov_b32_e32 v25, v137
	v_mov_b32_e32 v26, v137
	v_mov_b32_e32 v27, v137
	v_mov_b32_e32 v88, v137
	v_mov_b32_e32 v89, v137
	v_mov_b32_e32 v90, v137
	v_mov_b32_e32 v91, v137
	v_mov_b32_e32 v92, v137
	v_mov_b32_e32 v93, v137
	v_mov_b32_e32 v94, v137
	v_mov_b32_e32 v95, v137
	v_mov_b32_e32 v28, v137
	v_mov_b32_e32 v29, v137
	v_mov_b32_e32 v30, v137
	v_mov_b32_e32 v31, v137
	v_mov_b32_e32 v32, v137
	v_mov_b32_e32 v33, v137
	v_mov_b32_e32 v34, v137
	v_mov_b32_e32 v35, v137
	v_mov_b32_e32 v96, v137
	v_mov_b32_e32 v97, v137
	v_mov_b32_e32 v98, v137
	v_mov_b32_e32 v99, v137
	v_mov_b32_e32 v100, v137
	v_mov_b32_e32 v101, v137
	v_mov_b32_e32 v102, v137
	v_mov_b32_e32 v103, v137
	v_mov_b32_e32 v36, v137
	v_mov_b32_e32 v37, v137
	v_mov_b32_e32 v38, v137
	v_mov_b32_e32 v39, v137
	v_mov_b32_e32 v40, v137
	v_mov_b32_e32 v41, v137
	v_mov_b32_e32 v42, v137
	v_mov_b32_e32 v43, v137
	v_mov_b32_e32 v104, v137
	v_mov_b32_e32 v105, v137
	v_mov_b32_e32 v106, v137
	v_mov_b32_e32 v107, v137
	v_mov_b32_e32 v108, v137
	v_mov_b32_e32 v109, v137
	v_mov_b32_e32 v110, v137
	v_mov_b32_e32 v111, v137
	v_mov_b32_e32 v44, v137
	v_mov_b32_e32 v45, v137
	v_mov_b32_e32 v46, v137
	v_mov_b32_e32 v47, v137
	v_mov_b32_e32 v48, v137
	v_mov_b32_e32 v49, v137
	v_mov_b32_e32 v50, v137
	v_mov_b32_e32 v51, v137
	v_mov_b32_e32 v112, v137
	v_mov_b32_e32 v113, v137
	v_mov_b32_e32 v114, v137
	v_mov_b32_e32 v115, v137
	v_mov_b32_e32 v116, v137
	v_mov_b32_e32 v117, v137
	v_mov_b32_e32 v118, v137
	v_mov_b32_e32 v119, v137
	v_mov_b32_e32 v52, v137
	v_mov_b32_e32 v53, v137
	v_mov_b32_e32 v54, v137
	v_mov_b32_e32 v55, v137
	v_mov_b32_e32 v60, v137
	v_mov_b32_e32 v61, v137
	v_mov_b32_e32 v62, v137
	v_mov_b32_e32 v63, v137
	v_mov_b32_e32 v120, v137
	v_mov_b32_e32 v121, v137
	v_mov_b32_e32 v122, v137
	v_mov_b32_e32 v123, v137
	v_mov_b32_e32 v124, v137
	v_mov_b32_e32 v125, v137
	v_mov_b32_e32 v126, v137
	v_mov_b32_e32 v127, v137
	s_waitcnt vmcnt(0) lgkmcnt(0)
	s_barrier
	s_mov_b32 s17, 0x10000
	s_and_b32 s17, s16, 0x10000
	s_xor_b32 s33, s17, 0x10000
	s_add_i32 s33, s5, s33
	s_add_i32 s34, s33, 0x8000
	s_mov_b32 m0, s33
	v_lshl_add_u64 v[254:255], v[162:163], 0, s[0:1]
	global_load_lds_dwordx4 v[254:255], off
	s_add_i32 m0, s33, 0x2000
	v_lshl_add_u64 v[254:255], v[164:165], 0, s[0:1]
	global_load_lds_dwordx4 v[254:255], off
	s_add_i32 m0, s33, 0x4000
	v_lshl_add_u64 v[254:255], v[166:167], 0, s[0:1]
	global_load_lds_dwordx4 v[254:255], off
	s_add_i32 m0, s33, 0x6000
	v_lshl_add_u64 v[254:255], v[168:169], 0, s[0:1]
	global_load_lds_dwordx4 v[254:255], off
	s_mov_b32 m0, s34
	v_lshl_add_u64 v[254:255], v[170:171], 0, s[0:1]
	global_load_lds_dwordx4 v[254:255], off
	s_add_i32 m0, s33, 0xa000
	v_lshl_add_u64 v[254:255], v[172:173], 0, s[0:1]
	global_load_lds_dwordx4 v[254:255], off
	s_add_i32 m0, s33, 0xc000
	v_lshl_add_u64 v[254:255], v[174:175], 0, s[0:1]
	global_load_lds_dwordx4 v[254:255], off
	s_add_i32 m0, s33, 0xe000
	v_lshl_add_u64 v[254:255], v[176:177], 0, s[0:1]
	global_load_lds_dwordx4 v[254:255], off
	v_add3_u32 v253, s17, v153, v129
	ds_read_b128 v[214:217], v253 offset:0x1000
	ds_read_b128 v[218:221], v253 offset:0x1800
	ds_read_b128 v[206:209], v253 offset:0
	v_add3_u32 v253, s17, v155, v129
	ds_read_b128 v[178:181], v253 offset:0
	v_add3_u32 v253, s17, v153, v129
	ds_read_b128 v[210:213], v253 offset:0x800
	v_add3_u32 v253, s17, v155, v129
	ds_read_b128 v[182:185], v253 offset:0x800
	ds_read_b128 v[198:201], v253 offset:0x1000
	ds_read_b128 v[202:205], v253 offset:0x1800
.Lginp0_body:
	v_add_u32_e32 v159, s17, v155
	v_add_u32_e32 v136, s17, v153
	v_add_u32_e32 v157, v136, v129
	v_add_u32_e32 v159, v159, v135
	s_waitcnt lgkmcnt(4)
	v_add_u32_e32 v136, v136, v135
	v_mfma_f32_16x16x32_bf16 v[124:127], v[178:181], v[206:209], v[124:127]
	s_waitcnt lgkmcnt(2)
	v_mfma_f32_16x16x32_bf16 v[120:123], v[182:185], v[206:209], v[120:123]
	s_waitcnt lgkmcnt(1)
	v_mfma_f32_16x16x32_bf16 v[60:63], v[198:201], v[206:209], v[60:63]
	s_waitcnt lgkmcnt(0)
	v_mfma_f32_16x16x32_bf16 v[52:55], v[202:205], v[206:209], v[52:55]
	ds_read_b128 v[206:209], v157 offset:0x2000
	v_mfma_f32_16x16x32_bf16 v[116:119], v[178:181], v[210:213], v[116:119]
	v_mfma_f32_16x16x32_bf16 v[112:115], v[182:185], v[210:213], v[112:115]
	v_mfma_f32_16x16x32_bf16 v[48:51], v[198:201], v[210:213], v[48:51]
	v_mfma_f32_16x16x32_bf16 v[44:47], v[202:205], v[210:213], v[44:47]
	ds_read_b128 v[210:213], v157 offset:0x2800
	s_waitcnt lgkmcnt(2)
	s_nop 0
	v_mfma_f32_16x16x32_bf16 v[108:111], v[178:181], v[214:217], v[108:111]
	v_mfma_f32_16x16x32_bf16 v[104:107], v[182:185], v[214:217], v[104:107]
	v_mfma_f32_16x16x32_bf16 v[40:43], v[198:201], v[214:217], v[40:43]
	v_mfma_f32_16x16x32_bf16 v[36:39], v[202:205], v[214:217], v[36:39]
	ds_read_b128 v[214:217], v157 offset:0x3000
	v_mfma_f32_16x16x32_bf16 v[100:103], v[178:181], v[218:221], v[100:103]
	v_mfma_f32_16x16x32_bf16 v[96:99], v[182:185], v[218:221], v[96:99]
	v_mfma_f32_16x16x32_bf16 v[32:35], v[198:201], v[218:221], v[32:35]
	v_mfma_f32_16x16x32_bf16 v[28:31], v[202:205], v[218:221], v[28:31]
	ds_read_b128 v[218:221], v157 offset:0x3800
	ds_read_b128 v[222:225], v159 offset:0
	ds_read_b128 v[226:229], v159 offset:0x800
	ds_read_b128 v[230:233], v159 offset:0x1000
	ds_read_b128 v[234:237], v159 offset:0x1800
	s_waitcnt lgkmcnt(6)
	s_nop 0
	v_mfma_f32_16x16x32_bf16 v[92:95], v[178:181], v[206:209], v[92:95]
	v_mfma_f32_16x16x32_bf16 v[88:91], v[182:185], v[206:209], v[88:91]
	v_mfma_f32_16x16x32_bf16 v[24:27], v[198:201], v[206:209], v[24:27]
	v_mfma_f32_16x16x32_bf16 v[20:23], v[202:205], v[206:209], v[20:23]
	ds_read_b128 v[206:209], v136 offset:0
	v_mfma_f32_16x16x32_bf16 v[84:87], v[178:181], v[210:213], v[84:87]
	v_mfma_f32_16x16x32_bf16 v[80:83], v[182:185], v[210:213], v[80:83]
	v_mfma_f32_16x16x32_bf16 v[16:19], v[198:201], v[210:213], v[16:19]
	v_mfma_f32_16x16x32_bf16 v[12:15], v[202:205], v[210:213], v[12:15]
	ds_read_b128 v[210:213], v136 offset:0x800
	s_waitcnt lgkmcnt(6)
	s_nop 0
	v_mfma_f32_16x16x32_bf16 v[76:79], v[178:181], v[214:217], v[76:79]
	v_mfma_f32_16x16x32_bf16 v[68:71], v[178:181], v[218:221], v[68:71]
	ds_read_b128 v[178:181], v136 offset:0x1000
	v_mfma_f32_16x16x32_bf16 v[72:75], v[182:185], v[214:217], v[72:75]
	v_mfma_f32_16x16x32_bf16 v[64:67], v[182:185], v[218:221], v[64:67]
	ds_read_b128 v[182:185], v136 offset:0x1800
	s_waitcnt lgkmcnt(2)
	v_mfma_f32_16x16x32_bf16 v[8:11], v[198:201], v[214:217], v[8:11]
	v_mfma_f32_16x16x32_bf16 v[0:3], v[198:201], v[218:221], v[0:3]
	ds_read_b128 v[198:201], v136 offset:0x2000
	v_mfma_f32_16x16x32_bf16 v[4:7], v[202:205], v[214:217], v[4:7]
	v_mfma_f32_16x16x32_bf16 v[56:59], v[202:205], v[218:221], v[56:59]
	ds_read_b128 v[202:205], v136 offset:0x2800
	s_waitcnt lgkmcnt(2)
	s_nop 0
	v_mfma_f32_16x16x32_bf16 v[108:111], v[222:225], v[178:181], v[108:111]
	v_mfma_f32_16x16x32_bf16 v[104:107], v[226:229], v[178:181], v[104:107]
	v_mfma_f32_16x16x32_bf16 v[40:43], v[230:233], v[178:181], v[40:43]
	v_mfma_f32_16x16x32_bf16 v[36:39], v[234:237], v[178:181], v[36:39]
	ds_read_b128 v[178:181], v136 offset:0x3000
	v_mfma_f32_16x16x32_bf16 v[100:103], v[222:225], v[182:185], v[100:103]
	v_mfma_f32_16x16x32_bf16 v[96:99], v[226:229], v[182:185], v[96:99]
	v_mfma_f32_16x16x32_bf16 v[32:35], v[230:233], v[182:185], v[32:35]
	v_mfma_f32_16x16x32_bf16 v[28:31], v[234:237], v[182:185], v[28:31]
	ds_read_b128 v[182:185], v136 offset:0x3800
	s_waitcnt lgkmcnt(2)
	v_mfma_f32_16x16x32_bf16 v[124:127], v[222:225], v[206:209], v[124:127]
	s_add_i32 s16, s16, 0x10000
	s_add_u32 s0, s0, 0x80
	s_addc_u32 s1, s1, 0
	s_waitcnt lgkmcnt(0)
	s_waitcnt vmcnt(0)
	s_waitcnt vmcnt(0) lgkmcnt(0)
	v_mfma_f32_16x16x32_bf16 v[120:123], v[226:229], v[206:209], v[120:123]
	s_barrier
	s_cmpk_eq_i32 s0, 0x780
	s_cbranch_scc1 .Lginp0_nodma
	s_mov_b32 s17, 0x10000
	s_and_b32 s17, s16, 0x10000
	s_xor_b32 s33, s17, 0x10000
	s_add_i32 s33, s5, s33
	s_add_i32 s34, s33, 0x8000
	v_add3_u32 v253, s17, v153, v129
	ds_read_b128 v[214:217], v253 offset:0x1000
	ds_read_b128 v[218:221], v253 offset:0x1800
	v_mfma_f32_16x16x32_bf16 v[60:63], v[230:233], v[206:209], v[60:63]
	s_mov_b32 m0, s33
	v_lshl_add_u64 v[254:255], v[162:163], 0, s[0:1]
	global_load_lds_dwordx4 v[254:255], off
	v_mfma_f32_16x16x32_bf16 v[52:55], v[234:237], v[206:209], v[52:55]
	ds_read_b128 v[206:209], v253 offset:0
	v_mfma_f32_16x16x32_bf16 v[76:79], v[222:225], v[178:181], v[76:79]
	s_add_i32 m0, s33, 0x2000
	v_lshl_add_u64 v[254:255], v[164:165], 0, s[0:1]
	global_load_lds_dwordx4 v[254:255], off
	v_mfma_f32_16x16x32_bf16 v[72:75], v[226:229], v[178:181], v[72:75]
	v_mfma_f32_16x16x32_bf16 v[8:11], v[230:233], v[178:181], v[8:11]
	s_add_i32 m0, s33, 0x4000
	v_lshl_add_u64 v[254:255], v[166:167], 0, s[0:1]
	global_load_lds_dwordx4 v[254:255], off
	v_mfma_f32_16x16x32_bf16 v[4:7], v[234:237], v[178:181], v[4:7]
	v_add3_u32 v253, s17, v155, v129
	ds_read_b128 v[178:181], v253 offset:0
	v_mfma_f32_16x16x32_bf16 v[116:119], v[222:225], v[210:213], v[116:119]
	s_add_i32 m0, s33, 0x6000
	v_lshl_add_u64 v[254:255], v[168:169], 0, s[0:1]
	global_load_lds_dwordx4 v[254:255], off
	v_mfma_f32_16x16x32_bf16 v[112:115], v[226:229], v[210:213], v[112:115]
	v_mfma_f32_16x16x32_bf16 v[48:51], v[230:233], v[210:213], v[48:51]
	s_mov_b32 m0, s34
	v_lshl_add_u64 v[254:255], v[170:171], 0, s[0:1]
	global_load_lds_dwordx4 v[254:255], off
	v_mfma_f32_16x16x32_bf16 v[44:47], v[234:237], v[210:213], v[44:47]
	v_add3_u32 v253, s17, v153, v129
	ds_read_b128 v[210:213], v253 offset:0x800
	v_mfma_f32_16x16x32_bf16 v[68:71], v[222:225], v[182:185], v[68:71]
	s_add_i32 m0, s33, 0xa000
	v_lshl_add_u64 v[254:255], v[172:173], 0, s[0:1]
	global_load_lds_dwordx4 v[254:255], off
	v_mfma_f32_16x16x32_bf16 v[64:67], v[226:229], v[182:185], v[64:67]
	v_mfma_f32_16x16x32_bf16 v[0:3], v[230:233], v[182:185], v[0:3]
	s_add_i32 m0, s33, 0xc000
	v_lshl_add_u64 v[254:255], v[174:175], 0, s[0:1]
	global_load_lds_dwordx4 v[254:255], off
	v_mfma_f32_16x16x32_bf16 v[56:59], v[234:237], v[182:185], v[56:59]
	v_add3_u32 v253, s17, v155, v129
	ds_read_b128 v[182:185], v253 offset:0x800
	v_mfma_f32_16x16x32_bf16 v[92:95], v[222:225], v[198:201], v[92:95]
	s_add_i32 m0, s33, 0xe000
	v_lshl_add_u64 v[254:255], v[176:177], 0, s[0:1]
	global_load_lds_dwordx4 v[254:255], off
	v_mfma_f32_16x16x32_bf16 v[88:91], v[226:229], v[198:201], v[88:91]
	v_mfma_f32_16x16x32_bf16 v[24:27], v[230:233], v[198:201], v[24:27]
	v_mfma_f32_16x16x32_bf16 v[20:23], v[234:237], v[198:201], v[20:23]
	ds_read_b128 v[198:201], v253 offset:0x1000
	v_mfma_f32_16x16x32_bf16 v[84:87], v[222:225], v[202:205], v[84:87]
	v_mfma_f32_16x16x32_bf16 v[80:83], v[226:229], v[202:205], v[80:83]
	v_mfma_f32_16x16x32_bf16 v[16:19], v[230:233], v[202:205], v[16:19]
	v_mfma_f32_16x16x32_bf16 v[12:15], v[234:237], v[202:205], v[12:15]
	ds_read_b128 v[202:205], v253 offset:0x1800
	s_branch .Lginp0_body
.Lginp0_nodma:
	s_mov_b32 s17, 0x10000
	v_add3_u32 v253, s17, v153, v129
	ds_read_b128 v[214:217], v253 offset:0x1000
	ds_read_b128 v[218:221], v253 offset:0x1800
	v_mfma_f32_16x16x32_bf16 v[60:63], v[230:233], v[206:209], v[60:63]
	v_mfma_f32_16x16x32_bf16 v[52:55], v[234:237], v[206:209], v[52:55]
	ds_read_b128 v[206:209], v253 offset:0
	v_mfma_f32_16x16x32_bf16 v[76:79], v[222:225], v[178:181], v[76:79]
	v_mfma_f32_16x16x32_bf16 v[72:75], v[226:229], v[178:181], v[72:75]
	v_mfma_f32_16x16x32_bf16 v[8:11], v[230:233], v[178:181], v[8:11]
	v_mfma_f32_16x16x32_bf16 v[4:7], v[234:237], v[178:181], v[4:7]
	v_add3_u32 v253, s17, v155, v129
	ds_read_b128 v[178:181], v253 offset:0
	v_mfma_f32_16x16x32_bf16 v[116:119], v[222:225], v[210:213], v[116:119]
	v_mfma_f32_16x16x32_bf16 v[112:115], v[226:229], v[210:213], v[112:115]
	v_mfma_f32_16x16x32_bf16 v[48:51], v[230:233], v[210:213], v[48:51]
	v_mfma_f32_16x16x32_bf16 v[44:47], v[234:237], v[210:213], v[44:47]
	v_add3_u32 v253, s17, v153, v129
	ds_read_b128 v[210:213], v253 offset:0x800
	v_mfma_f32_16x16x32_bf16 v[68:71], v[222:225], v[182:185], v[68:71]
	v_mfma_f32_16x16x32_bf16 v[64:67], v[226:229], v[182:185], v[64:67]
	v_mfma_f32_16x16x32_bf16 v[0:3], v[230:233], v[182:185], v[0:3]
	v_mfma_f32_16x16x32_bf16 v[56:59], v[234:237], v[182:185], v[56:59]
	v_add3_u32 v253, s17, v155, v129
	ds_read_b128 v[182:185], v253 offset:0x800
	v_mfma_f32_16x16x32_bf16 v[92:95], v[222:225], v[198:201], v[92:95]
	v_mfma_f32_16x16x32_bf16 v[88:91], v[226:229], v[198:201], v[88:91]
	v_mfma_f32_16x16x32_bf16 v[24:27], v[230:233], v[198:201], v[24:27]
	v_mfma_f32_16x16x32_bf16 v[20:23], v[234:237], v[198:201], v[20:23]
	ds_read_b128 v[198:201], v253 offset:0x1000
	v_mfma_f32_16x16x32_bf16 v[84:87], v[222:225], v[202:205], v[84:87]
	v_mfma_f32_16x16x32_bf16 v[80:83], v[226:229], v[202:205], v[80:83]
	v_mfma_f32_16x16x32_bf16 v[16:19], v[230:233], v[202:205], v[16:19]
	v_mfma_f32_16x16x32_bf16 v[12:15], v[234:237], v[202:205], v[12:15]
	ds_read_b128 v[202:205], v253 offset:0x1800
	v_add_u32_e32 v159, s17, v155
	v_add_u32_e32 v136, s17, v153
	v_add_u32_e32 v157, v136, v129
	v_add_u32_e32 v159, v159, v135
	s_waitcnt lgkmcnt(4)
	v_add_u32_e32 v136, v136, v135
	v_mfma_f32_16x16x32_bf16 v[124:127], v[178:181], v[206:209], v[124:127]
	s_waitcnt lgkmcnt(2)
	v_mfma_f32_16x16x32_bf16 v[120:123], v[182:185], v[206:209], v[120:123]
	s_waitcnt lgkmcnt(1)
	v_mfma_f32_16x16x32_bf16 v[60:63], v[198:201], v[206:209], v[60:63]
	s_waitcnt lgkmcnt(0)
	v_mfma_f32_16x16x32_bf16 v[52:55], v[202:205], v[206:209], v[52:55]
	ds_read_b128 v[206:209], v157 offset:0x2000
	v_mfma_f32_16x16x32_bf16 v[116:119], v[178:181], v[210:213], v[116:119]
	v_mfma_f32_16x16x32_bf16 v[112:115], v[182:185], v[210:213], v[112:115]
	v_mfma_f32_16x16x32_bf16 v[48:51], v[198:201], v[210:213], v[48:51]
	v_mfma_f32_16x16x32_bf16 v[44:47], v[202:205], v[210:213], v[44:47]
	ds_read_b128 v[210:213], v157 offset:0x2800
	s_waitcnt lgkmcnt(2)
	s_nop 0
	v_mfma_f32_16x16x32_bf16 v[108:111], v[178:181], v[214:217], v[108:111]
	v_mfma_f32_16x16x32_bf16 v[104:107], v[182:185], v[214:217], v[104:107]
	v_mfma_f32_16x16x32_bf16 v[40:43], v[198:201], v[214:217], v[40:43]
	v_mfma_f32_16x16x32_bf16 v[36:39], v[202:205], v[214:217], v[36:39]
	ds_read_b128 v[214:217], v157 offset:0x3000
	v_mfma_f32_16x16x32_bf16 v[100:103], v[178:181], v[218:221], v[100:103]
	v_mfma_f32_16x16x32_bf16 v[96:99], v[182:185], v[218:221], v[96:99]
	v_mfma_f32_16x16x32_bf16 v[32:35], v[198:201], v[218:221], v[32:35]
	v_mfma_f32_16x16x32_bf16 v[28:31], v[202:205], v[218:221], v[28:31]
	ds_read_b128 v[218:221], v157 offset:0x3800
	ds_read_b128 v[222:225], v159 offset:0
	ds_read_b128 v[226:229], v159 offset:0x800
	ds_read_b128 v[230:233], v159 offset:0x1000
	ds_read_b128 v[234:237], v159 offset:0x1800
	s_waitcnt lgkmcnt(6)
	s_nop 0
	v_mfma_f32_16x16x32_bf16 v[92:95], v[178:181], v[206:209], v[92:95]
	v_mfma_f32_16x16x32_bf16 v[88:91], v[182:185], v[206:209], v[88:91]
	v_mfma_f32_16x16x32_bf16 v[24:27], v[198:201], v[206:209], v[24:27]
	v_mfma_f32_16x16x32_bf16 v[20:23], v[202:205], v[206:209], v[20:23]
	ds_read_b128 v[206:209], v136 offset:0
	v_mfma_f32_16x16x32_bf16 v[84:87], v[178:181], v[210:213], v[84:87]
	v_mfma_f32_16x16x32_bf16 v[80:83], v[182:185], v[210:213], v[80:83]
	v_mfma_f32_16x16x32_bf16 v[16:19], v[198:201], v[210:213], v[16:19]
	v_mfma_f32_16x16x32_bf16 v[12:15], v[202:205], v[210:213], v[12:15]
	ds_read_b128 v[210:213], v136 offset:0x800
	s_waitcnt lgkmcnt(6)
	s_nop 0
	v_mfma_f32_16x16x32_bf16 v[76:79], v[178:181], v[214:217], v[76:79]
	v_mfma_f32_16x16x32_bf16 v[68:71], v[178:181], v[218:221], v[68:71]
	ds_read_b128 v[178:181], v136 offset:0x1000
	v_mfma_f32_16x16x32_bf16 v[72:75], v[182:185], v[214:217], v[72:75]
	v_mfma_f32_16x16x32_bf16 v[64:67], v[182:185], v[218:221], v[64:67]
	ds_read_b128 v[182:185], v136 offset:0x1800
	s_waitcnt lgkmcnt(2)
	v_mfma_f32_16x16x32_bf16 v[8:11], v[198:201], v[214:217], v[8:11]
	v_mfma_f32_16x16x32_bf16 v[0:3], v[198:201], v[218:221], v[0:3]
	ds_read_b128 v[198:201], v136 offset:0x2000
	v_mfma_f32_16x16x32_bf16 v[4:7], v[202:205], v[214:217], v[4:7]
	v_mfma_f32_16x16x32_bf16 v[56:59], v[202:205], v[218:221], v[56:59]
	ds_read_b128 v[202:205], v136 offset:0x2800
	s_waitcnt lgkmcnt(2)
	s_nop 0
	v_mfma_f32_16x16x32_bf16 v[108:111], v[222:225], v[178:181], v[108:111]
	v_mfma_f32_16x16x32_bf16 v[104:107], v[226:229], v[178:181], v[104:107]
	v_mfma_f32_16x16x32_bf16 v[40:43], v[230:233], v[178:181], v[40:43]
	v_mfma_f32_16x16x32_bf16 v[36:39], v[234:237], v[178:181], v[36:39]
	ds_read_b128 v[178:181], v136 offset:0x3000
	v_mfma_f32_16x16x32_bf16 v[100:103], v[222:225], v[182:185], v[100:103]
	v_mfma_f32_16x16x32_bf16 v[96:99], v[226:229], v[182:185], v[96:99]
	v_mfma_f32_16x16x32_bf16 v[32:35], v[230:233], v[182:185], v[32:35]
	v_mfma_f32_16x16x32_bf16 v[28:31], v[234:237], v[182:185], v[28:31]
	ds_read_b128 v[182:185], v136 offset:0x3800
	s_waitcnt lgkmcnt(2)
	v_mfma_f32_16x16x32_bf16 v[124:127], v[222:225], v[206:209], v[124:127]
	s_add_i32 s16, s16, 0x10000
	s_add_u32 s0, s0, 0x80
	s_addc_u32 s1, s1, 0
	s_waitcnt lgkmcnt(0)
	s_waitcnt vmcnt(0)
	s_waitcnt vmcnt(0) lgkmcnt(0)
	v_mfma_f32_16x16x32_bf16 v[120:123], v[226:229], v[206:209], v[120:123]
	s_barrier
	v_mfma_f32_16x16x32_bf16 v[60:63], v[230:233], v[206:209], v[60:63]
	v_mfma_f32_16x16x32_bf16 v[52:55], v[234:237], v[206:209], v[52:55]
	v_mfma_f32_16x16x32_bf16 v[116:119], v[222:225], v[210:213], v[116:119]
	v_mfma_f32_16x16x32_bf16 v[112:115], v[226:229], v[210:213], v[112:115]
	v_mfma_f32_16x16x32_bf16 v[48:51], v[230:233], v[210:213], v[48:51]
	v_mfma_f32_16x16x32_bf16 v[44:47], v[234:237], v[210:213], v[44:47]
	v_mfma_f32_16x16x32_bf16 v[92:95], v[222:225], v[198:201], v[92:95]
	v_mfma_f32_16x16x32_bf16 v[88:91], v[226:229], v[198:201], v[88:91]
	v_mfma_f32_16x16x32_bf16 v[24:27], v[230:233], v[198:201], v[24:27]
	v_mfma_f32_16x16x32_bf16 v[20:23], v[234:237], v[198:201], v[20:23]
	v_mfma_f32_16x16x32_bf16 v[84:87], v[222:225], v[202:205], v[84:87]
	v_mfma_f32_16x16x32_bf16 v[80:83], v[226:229], v[202:205], v[80:83]
	v_mfma_f32_16x16x32_bf16 v[16:19], v[230:233], v[202:205], v[16:19]
	v_mfma_f32_16x16x32_bf16 v[12:15], v[234:237], v[202:205], v[12:15]
	v_mfma_f32_16x16x32_bf16 v[76:79], v[222:225], v[178:181], v[76:79]
	v_mfma_f32_16x16x32_bf16 v[72:75], v[226:229], v[178:181], v[72:75]
	v_mfma_f32_16x16x32_bf16 v[8:11], v[230:233], v[178:181], v[8:11]
	v_mfma_f32_16x16x32_bf16 v[4:7], v[234:237], v[178:181], v[4:7]
	v_mfma_f32_16x16x32_bf16 v[68:71], v[222:225], v[182:185], v[68:71]
	v_mfma_f32_16x16x32_bf16 v[64:67], v[226:229], v[182:185], v[64:67]
	v_mfma_f32_16x16x32_bf16 v[0:3], v[230:233], v[182:185], v[0:3]
	v_mfma_f32_16x16x32_bf16 v[56:59], v[234:237], v[182:185], v[56:59]

.LBB0_414:
	s_or_b64 exec, exec, s[8:9]
	v_cvt_f32_u32_e32 v4, v2
	s_waitcnt vmcnt(0)
	v_readfirstlane_b32 s6, v3
	v_sub_u32_e32 v3, 0, v2
	v_rcp_iflag_f32_e32 v4, v4
	v_add_u32_e32 v5, s6, v1
	v_mul_f32_e32 v4, 0x4f7ffffe, v4
	v_cvt_u32_f32_e32 v4, v4
	v_mul_lo_u32 v1, v3, v4
	v_mul_hi_u32 v1, v4, v1
	v_add_u32_e32 v1, v4, v1
	v_mul_hi_u32 v1, v5, v1
	v_mul_lo_u32 v3, v1, v2
	v_sub_u32_e32 v3, v5, v3
	v_add_u32_e32 v4, 1, v1
	v_cmp_ge_u32_e32 vcc, v3, v2
	s_nop 1
	v_cndmask_b32_e32 v1, v1, v4, vcc
	v_sub_u32_e32 v4, v3, v2
	v_cndmask_b32_e32 v3, v3, v4, vcc
	v_add_u32_e32 v4, 1, v1
	v_cmp_ge_u32_e32 vcc, v3, v2
	v_add_u32_e32 v3, 1, v5
	s_nop 0
	v_cndmask_b32_e32 v1, v1, v4, vcc
	v_mul_lo_u32 v4, v2, v1
	v_add_u32_e32 v2, v4, v2
	v_cmp_ne_u32_e32 vcc, v3, v2
	s_and_saveexec_b64 s[6:7], vcc
	s_xor_b64 s[6:7], exec, s[6:7]
	s_cbranch_execz .LBB0_428
	s_waitcnt lgkmcnt(0)
	buffer_inv sc1
	v_mov_b32_e32 v0, 0
	v_mov_b32_e32 v1, 2
	s_add_u32 s12, s86, 0xe7b4500
	s_addc_u32 s13, s87, 0
	global_load_dword v0, v0, s[12:13] sc1
	s_waitcnt vmcnt(0)
	v_cmp_eq_u32_e32 vcc, v0, v1
	s_and_saveexec_b64 s[8:9], vcc
	s_cbranch_execz .LBB0_427
	s_add_u32 s10, s86, 0xe7b1200
	s_addc_u32 s11, s87, 0
	s_mov_b32 s26, 1
	s_mov_b64 s[14:15], 0
	v_mov_b32_e32 v0, 0
	s_branch .LBB0_418

.LBB0_502:
	s_or_b64 exec, exec, s[8:9]
	v_cvt_f32_u32_e32 v4, v2
	s_waitcnt vmcnt(0)
	v_readfirstlane_b32 s6, v3
	v_sub_u32_e32 v3, 0, v2
	v_rcp_iflag_f32_e32 v4, v4
	v_add_u32_e32 v5, s6, v1
	v_mul_f32_e32 v4, 0x4f7ffffe, v4
	v_cvt_u32_f32_e32 v4, v4
	v_mul_lo_u32 v1, v3, v4
	v_mul_hi_u32 v1, v4, v1
	v_add_u32_e32 v1, v4, v1
	v_mul_hi_u32 v1, v5, v1
	v_mul_lo_u32 v3, v1, v2
	v_sub_u32_e32 v3, v5, v3
	v_add_u32_e32 v4, 1, v1
	v_cmp_ge_u32_e32 vcc, v3, v2
	s_nop 1
	v_cndmask_b32_e32 v1, v1, v4, vcc
	v_sub_u32_e32 v4, v3, v2
	v_cndmask_b32_e32 v3, v3, v4, vcc
	v_add_u32_e32 v4, 1, v1
	v_cmp_ge_u32_e32 vcc, v3, v2
	v_add_u32_e32 v3, 1, v5
	s_nop 0
	v_cndmask_b32_e32 v1, v1, v4, vcc
	v_mul_lo_u32 v4, v2, v1
	v_add_u32_e32 v2, v4, v2
	v_cmp_ne_u32_e32 vcc, v3, v2
	s_and_saveexec_b64 s[6:7], vcc
	s_xor_b64 s[6:7], exec, s[6:7]
	s_cbranch_execz .LBB0_516
	s_waitcnt lgkmcnt(0)
	buffer_inv sc1
	v_mov_b32_e32 v0, 0
	v_mov_b32_e32 v1, 3
	s_add_u32 s14, s86, 0xe7b4500
	s_addc_u32 s15, s87, 0
	global_load_dword v0, v0, s[14:15] sc1
	s_waitcnt vmcnt(0)
	v_cmp_eq_u32_e32 vcc, v0, v1
	s_and_saveexec_b64 s[8:9], vcc
	s_cbranch_execz .LBB0_515
	s_add_u32 s10, s86, 0xe7b1200
	s_addc_u32 s11, s87, 0
	s_mov_b32 s28, 1
	s_mov_b64 s[16:17], 0
	v_mov_b32_e32 v0, 0
	s_branch .LBB0_506

.LBB0_706:
	s_or_b64 exec, exec, s[8:9]
	v_cvt_f32_u32_e32 v4, v2
	s_waitcnt vmcnt(0)
	v_readfirstlane_b32 s6, v3
	v_sub_u32_e32 v3, 0, v2
	v_rcp_iflag_f32_e32 v4, v4
	v_add_u32_e32 v5, s6, v1
	v_mul_f32_e32 v4, 0x4f7ffffe, v4
	v_cvt_u32_f32_e32 v4, v4
	v_mul_lo_u32 v1, v3, v4
	v_mul_hi_u32 v1, v4, v1
	v_add_u32_e32 v1, v4, v1
	v_mul_hi_u32 v1, v5, v1
	v_mul_lo_u32 v3, v1, v2
	v_sub_u32_e32 v3, v5, v3
	v_add_u32_e32 v4, 1, v1
	v_cmp_ge_u32_e32 vcc, v3, v2
	s_nop 1
	v_cndmask_b32_e32 v1, v1, v4, vcc
	v_sub_u32_e32 v4, v3, v2
	v_cndmask_b32_e32 v3, v3, v4, vcc
	v_add_u32_e32 v4, 1, v1
	v_cmp_ge_u32_e32 vcc, v3, v2
	v_add_u32_e32 v3, 1, v5
	s_nop 0
	v_cndmask_b32_e32 v1, v1, v4, vcc
	v_mul_lo_u32 v4, v2, v1
	v_add_u32_e32 v2, v4, v2
	v_cmp_ne_u32_e32 vcc, v3, v2
	s_and_saveexec_b64 s[6:7], vcc
	s_xor_b64 s[6:7], exec, s[6:7]
	s_cbranch_execz .LBB0_720
	s_waitcnt lgkmcnt(0)
	buffer_inv sc1
	v_mov_b32_e32 v0, 0
	v_mov_b32_e32 v1, 4
	s_add_u32 s12, s86, 0xe7b4500
	s_addc_u32 s13, s87, 0
	global_load_dword v0, v0, s[12:13] sc1
	s_waitcnt vmcnt(0)
	v_cmp_eq_u32_e32 vcc, v0, v1
	s_and_saveexec_b64 s[8:9], vcc
	s_cbranch_execz .LBB0_719
	s_add_u32 s10, s86, 0xe7b1200
	s_addc_u32 s11, s87, 0
	s_mov_b32 s26, 1
	s_mov_b64 s[14:15], 0
	v_mov_b32_e32 v0, 0
	s_branch .LBB0_710

.LBB0_742:
	s_ashr_i32 s4, s17, 31
	s_lshr_b32 s4, s4, 26
	s_add_i32 s4, s17, s4
	v_readfirstlane_b32 s9, v128
	s_ashr_i32 s10, s4, 6
	s_andn2_b32 s4, s4, 63
	s_lshr_b32 s11, s9, 1
	s_sub_i32 s8, s17, s4
	s_and_b32 s11, s11, 0x1ffff80
	s_lshl_b32 s4, s8, 19
	v_or_b32_e32 v8, s11, v189
	s_and_b32 s11, s9, 0xc0
	s_lshl_b32 s9, s9, 4
	v_add_u32_e32 v0, s4, v134
	v_lshlrev_b32_e32 v141, 7, v8
	v_or_b32_e32 v8, s11, v189
	s_and_b32 s9, s9, 0x7ffffc00
	v_add_u32_e32 v1, s4, v138
	v_lshl_or_b32 v143, v8, 7, v139
	v_and_b32_e32 v8, 0xfffff870, v0
	s_mov_b32 m0, s9
	v_add_u32_e32 v2, s4, v140
	global_load_lds_dwordx4 v8, s[86:87]
	v_and_b32_e32 v1, 0xfffff870, v1
	s_add_i32 m0, s9, 0x2000
	s_lshl_b32 s5, s10, 19
	v_add_u32_e32 v3, s4, v142
	global_load_lds_dwordx4 v1, s[86:87]
	v_and_b32_e32 v1, 0xfffff870, v2
	s_add_i32 m0, s9, 0x4000
	v_add_u32_e32 v4, s5, v144
	s_add_i32 s11, s9, 0x8000
	global_load_lds_dwordx4 v1, s[86:87]
	v_and_b32_e32 v1, 0xfffff870, v3
	s_add_i32 m0, s9, 0x6000
	v_add_u32_e32 v5, s5, v146
	global_load_lds_dwordx4 v1, s[86:87]
	v_and_b32_e32 v1, 0xfffff870, v4
	s_mov_b32 m0, s11
	v_add_u32_e32 v6, s5, v148
	global_load_lds_dwordx4 v1, s[86:87]
	v_and_b32_e32 v1, 0xfffff870, v5
	s_add_i32 m0, s9, 0xa000
	v_add_u32_e32 v7, s5, v150
	global_load_lds_dwordx4 v1, s[86:87]
	v_and_b32_e32 v1, 0xfffff870, v6
	s_add_i32 m0, s9, 0xc000
	v_and_b32_e32 v136, -16, v0
	global_load_lds_dwordx4 v1, s[86:87]
	v_and_b32_e32 v1, 0xfffff870, v7
	s_add_i32 m0, s9, 0xe000
	v_add_u32_e32 v0, s4, v152
	global_load_lds_dwordx4 v1, s[86:87]
	v_lshl_add_u64 v[162:163], s[6:7], 0, v[136:137]
	v_and_b32_e32 v136, -16, v0
	v_add_u32_e32 v0, s4, v154
	v_lshl_add_u64 v[164:165], s[6:7], 0, v[136:137]
	v_and_b32_e32 v136, -16, v0
	v_add_u32_e32 v0, s4, v156
	v_lshl_add_u64 v[166:167], s[6:7], 0, v[136:137]
	v_and_b32_e32 v136, -16, v0
	v_lshl_add_u64 v[168:169], s[6:7], 0, v[136:137]
	v_and_b32_e32 v136, -16, v4
	v_add_u32_e32 v0, s5, v158
	v_lshl_add_u64 v[170:171], s[6:7], 0, v[136:137]
	v_and_b32_e32 v136, -16, v0
	s_waitcnt vmcnt(0)
	v_lshl_add_u64 v[172:173], s[6:7], 0, v[136:137]
	v_and_b32_e32 v136, -16, v6
	v_add_u32_e32 v0, s5, v160
	v_lshl_add_u64 v[174:175], s[6:7], 0, v[136:137]
	v_and_b32_e32 v136, -16, v0
	v_lshl_add_u64 v[176:177], s[6:7], 0, v[136:137]
	s_mov_b64 s[4:5], 0
	s_mov_b32 s11, 0
	s_mov_b32 s18, 0
	v_mov_b32_e32 v56, 0
	v_mov_b32_e32 v57, v137
	v_mov_b32_e32 v58, v137
	v_mov_b32_e32 v59, v137
	v_mov_b32_e32 v52, 0
	v_mov_b32_e32 v53, v137
	v_mov_b32_e32 v54, v137
	v_mov_b32_e32 v55, v137
	v_mov_b32_e32 v64, 0
	v_mov_b32_e32 v65, v137
	v_mov_b32_e32 v66, v137
	v_mov_b32_e32 v67, v137
	v_mov_b32_e32 v68, 0
	v_mov_b32_e32 v69, v137
	v_mov_b32_e32 v70, v137
	v_mov_b32_e32 v71, v137
	v_mov_b32_e32 v0, 0
	v_mov_b32_e32 v1, v137
	v_mov_b32_e32 v2, v137
	v_mov_b32_e32 v3, v137
	v_mov_b32_e32 v4, 0
	v_mov_b32_e32 v5, v137
	v_mov_b32_e32 v6, v137
	v_mov_b32_e32 v7, v137
	v_mov_b32_e32 v72, 0
	v_mov_b32_e32 v73, v137
	v_mov_b32_e32 v74, v137
	v_mov_b32_e32 v75, v137
	v_mov_b32_e32 v76, 0
	v_mov_b32_e32 v77, v137
	v_mov_b32_e32 v78, v137
	v_mov_b32_e32 v79, v137
	v_mov_b32_e32 v8, 0
	v_mov_b32_e32 v9, v137
	v_mov_b32_e32 v10, v137
	v_mov_b32_e32 v11, v137
	v_mov_b32_e32 v12, 0
	v_mov_b32_e32 v13, v137
	v_mov_b32_e32 v14, v137
	v_mov_b32_e32 v15, v137
	v_mov_b32_e32 v80, 0
	v_mov_b32_e32 v81, v137
	v_mov_b32_e32 v82, v137
	v_mov_b32_e32 v83, v137
	v_mov_b32_e32 v84, 0
	v_mov_b32_e32 v85, v137
	v_mov_b32_e32 v86, v137
	v_mov_b32_e32 v87, v137
	v_mov_b32_e32 v16, 0
	v_mov_b32_e32 v17, v137
	v_mov_b32_e32 v18, v137
	v_mov_b32_e32 v19, v137
	v_mov_b32_e32 v20, 0
	v_mov_b32_e32 v21, v137
	v_mov_b32_e32 v22, v137
	v_mov_b32_e32 v23, v137
	v_mov_b32_e32 v88, 0
	v_mov_b32_e32 v89, v137
	v_mov_b32_e32 v90, v137
	v_mov_b32_e32 v91, v137
	v_mov_b32_e32 v92, 0
	v_mov_b32_e32 v93, v137
	v_mov_b32_e32 v94, v137
	v_mov_b32_e32 v95, v137
	v_mov_b32_e32 v24, 0
	v_mov_b32_e32 v25, v137
	v_mov_b32_e32 v26, v137
	v_mov_b32_e32 v27, v137
	v_mov_b32_e32 v28, 0
	v_mov_b32_e32 v29, v137
	v_mov_b32_e32 v30, v137
	v_mov_b32_e32 v31, v137
	s_waitcnt vmcnt(0)
	v_mov_b32_e32 v96, 0
	v_mov_b32_e32 v97, v137
	v_mov_b32_e32 v98, v137
	v_mov_b32_e32 v99, v137
	v_mov_b32_e32 v100, 0
	v_mov_b32_e32 v101, v137
	v_mov_b32_e32 v102, v137
	v_mov_b32_e32 v103, v137
	v_mov_b32_e32 v32, 0
	v_mov_b32_e32 v33, v137
	v_mov_b32_e32 v34, v137
	v_mov_b32_e32 v35, v137
	v_mov_b32_e32 v36, 0
	v_mov_b32_e32 v37, v137
	v_mov_b32_e32 v38, v137
	v_mov_b32_e32 v39, v137
	v_mov_b32_e32 v104, 0
	v_mov_b32_e32 v105, v137
	v_mov_b32_e32 v106, v137
	v_mov_b32_e32 v107, v137
	v_mov_b32_e32 v108, 0
	v_mov_b32_e32 v109, v137
	v_mov_b32_e32 v110, v137
	v_mov_b32_e32 v111, v137
	v_mov_b32_e32 v40, 0
	v_mov_b32_e32 v41, v137
	v_mov_b32_e32 v42, v137
	v_mov_b32_e32 v43, v137
	v_mov_b32_e32 v44, 0
	v_mov_b32_e32 v45, v137
	v_mov_b32_e32 v46, v137
	v_mov_b32_e32 v47, v137
	v_mov_b32_e32 v112, 0
	v_mov_b32_e32 v113, v137
	v_mov_b32_e32 v114, v137
	v_mov_b32_e32 v115, v137
	v_mov_b32_e32 v116, 0
	v_mov_b32_e32 v117, v137
	v_mov_b32_e32 v118, v137
	v_mov_b32_e32 v119, v137
	v_mov_b32_e32 v48, 0
	v_mov_b32_e32 v49, v137
	v_mov_b32_e32 v50, v137
	v_mov_b32_e32 v51, v137
	v_mov_b32_e32 v60, 0
	v_mov_b32_e32 v61, v137
	v_mov_b32_e32 v62, v137
	v_mov_b32_e32 v63, v137
	v_mov_b32_e32 v120, 0
	v_mov_b32_e32 v121, v137
	v_mov_b32_e32 v122, v137
	v_mov_b32_e32 v123, v137
	v_mov_b32_e32 v124, 0
	v_mov_b32_e32 v125, v137
	v_mov_b32_e32 v126, v137
	v_mov_b32_e32 v127, v137
	s_waitcnt lgkmcnt(0)
	s_barrier
	s_and_b32 s19, s11, 0x10000
	s_xor_b32 s24, s19, 0x10000
	s_add_i32 s24, s9, s24
	s_add_i32 s25, s24, 0x8000
	s_mov_b32 m0, s24
	v_lshl_add_u64 v[254:255], v[162:163], 0, s[4:5]
	global_load_lds_dwordx4 v[254:255], off
	s_add_i32 m0, s24, 0x2000
	v_lshl_add_u64 v[254:255], v[164:165], 0, s[4:5]
	global_load_lds_dwordx4 v[254:255], off
	s_add_i32 m0, s24, 0x4000
	v_lshl_add_u64 v[254:255], v[166:167], 0, s[4:5]
	global_load_lds_dwordx4 v[254:255], off
	s_add_i32 m0, s24, 0x6000
	v_lshl_add_u64 v[254:255], v[168:169], 0, s[4:5]
	global_load_lds_dwordx4 v[254:255], off
	s_mov_b32 m0, s25
	v_lshl_add_u64 v[254:255], v[170:171], 0, s[4:5]
	global_load_lds_dwordx4 v[254:255], off
	s_add_i32 m0, s24, 0xa000
	v_lshl_add_u64 v[254:255], v[172:173], 0, s[4:5]
	global_load_lds_dwordx4 v[254:255], off
	s_add_i32 m0, s24, 0xc000
	v_lshl_add_u64 v[254:255], v[174:175], 0, s[4:5]
	global_load_lds_dwordx4 v[254:255], off
	s_add_i32 m0, s24, 0xe000
	v_lshl_add_u64 v[254:255], v[176:177], 0, s[4:5]
	global_load_lds_dwordx4 v[254:255], off
	v_add3_u32 v253, s19, v141, v129
	ds_read_b128 v[214:217], v253 offset:0x1000
	ds_read_b128 v[218:221], v253 offset:0x1800
	ds_read_b128 v[206:209], v253 offset:0
	v_add3_u32 v253, s19, v143, v129
	ds_read_b128 v[178:181], v253 offset:0
	v_add3_u32 v253, s19, v141, v129
	ds_read_b128 v[210:213], v253 offset:0x800
	v_add3_u32 v253, s19, v143, v129
	ds_read_b128 v[182:185], v253 offset:0x800
	ds_read_b128 v[198:201], v253 offset:0x1000
	ds_read_b128 v[202:205], v253 offset:0x1800
.Lgout0_body:
	v_add_u32_e32 v147, s19, v143
	v_add_u32_e32 v136, s19, v141
	v_add_u32_e32 v145, v136, v129
	v_add_u32_e32 v147, v147, v135
	s_waitcnt lgkmcnt(4)
	v_add_u32_e32 v136, v136, v135
	v_mfma_f32_16x16x32_bf16 v[124:127], v[178:181], v[206:209], v[124:127]
	s_waitcnt lgkmcnt(2)
	v_mfma_f32_16x16x32_bf16 v[120:123], v[182:185], v[206:209], v[120:123]
	s_waitcnt lgkmcnt(1)
	v_mfma_f32_16x16x32_bf16 v[60:63], v[198:201], v[206:209], v[60:63]
	s_waitcnt lgkmcnt(0)
	v_mfma_f32_16x16x32_bf16 v[48:51], v[202:205], v[206:209], v[48:51]
	ds_read_b128 v[206:209], v145 offset:0x2000
	v_mfma_f32_16x16x32_bf16 v[116:119], v[178:181], v[210:213], v[116:119]
	v_mfma_f32_16x16x32_bf16 v[112:115], v[182:185], v[210:213], v[112:115]
	v_mfma_f32_16x16x32_bf16 v[44:47], v[198:201], v[210:213], v[44:47]
	v_mfma_f32_16x16x32_bf16 v[40:43], v[202:205], v[210:213], v[40:43]
	ds_read_b128 v[210:213], v145 offset:0x2800
	s_waitcnt lgkmcnt(2)
	s_nop 0
	v_mfma_f32_16x16x32_bf16 v[108:111], v[178:181], v[214:217], v[108:111]
	v_mfma_f32_16x16x32_bf16 v[104:107], v[182:185], v[214:217], v[104:107]
	v_mfma_f32_16x16x32_bf16 v[36:39], v[198:201], v[214:217], v[36:39]
	v_mfma_f32_16x16x32_bf16 v[32:35], v[202:205], v[214:217], v[32:35]
	ds_read_b128 v[214:217], v145 offset:0x3000
	v_mfma_f32_16x16x32_bf16 v[100:103], v[178:181], v[218:221], v[100:103]
	v_mfma_f32_16x16x32_bf16 v[96:99], v[182:185], v[218:221], v[96:99]
	v_mfma_f32_16x16x32_bf16 v[28:31], v[198:201], v[218:221], v[28:31]
	v_mfma_f32_16x16x32_bf16 v[24:27], v[202:205], v[218:221], v[24:27]
	ds_read_b128 v[218:221], v145 offset:0x3800
	ds_read_b128 v[222:225], v147 offset:0
	ds_read_b128 v[226:229], v147 offset:0x800
	ds_read_b128 v[230:233], v147 offset:0x1000
	ds_read_b128 v[234:237], v147 offset:0x1800
	s_waitcnt lgkmcnt(6)
	s_nop 0
	v_mfma_f32_16x16x32_bf16 v[92:95], v[178:181], v[206:209], v[92:95]
	v_mfma_f32_16x16x32_bf16 v[88:91], v[182:185], v[206:209], v[88:91]
	v_mfma_f32_16x16x32_bf16 v[20:23], v[198:201], v[206:209], v[20:23]
	v_mfma_f32_16x16x32_bf16 v[16:19], v[202:205], v[206:209], v[16:19]
	ds_read_b128 v[206:209], v136 offset:0
	v_mfma_f32_16x16x32_bf16 v[84:87], v[178:181], v[210:213], v[84:87]
	v_mfma_f32_16x16x32_bf16 v[80:83], v[182:185], v[210:213], v[80:83]
	v_mfma_f32_16x16x32_bf16 v[12:15], v[198:201], v[210:213], v[12:15]
	v_mfma_f32_16x16x32_bf16 v[8:11], v[202:205], v[210:213], v[8:11]
	ds_read_b128 v[210:213], v136 offset:0x800
	s_waitcnt lgkmcnt(6)
	s_nop 0
	v_mfma_f32_16x16x32_bf16 v[76:79], v[178:181], v[214:217], v[76:79]
	v_mfma_f32_16x16x32_bf16 v[68:71], v[178:181], v[218:221], v[68:71]
	ds_read_b128 v[178:181], v136 offset:0x1000
	v_mfma_f32_16x16x32_bf16 v[72:75], v[182:185], v[214:217], v[72:75]
	v_mfma_f32_16x16x32_bf16 v[64:67], v[182:185], v[218:221], v[64:67]
	ds_read_b128 v[182:185], v136 offset:0x1800
	s_waitcnt lgkmcnt(2)
	v_mfma_f32_16x16x32_bf16 v[4:7], v[198:201], v[214:217], v[4:7]
	v_mfma_f32_16x16x32_bf16 v[52:55], v[198:201], v[218:221], v[52:55]
	ds_read_b128 v[198:201], v136 offset:0x2000
	v_mfma_f32_16x16x32_bf16 v[0:3], v[202:205], v[214:217], v[0:3]
	v_mfma_f32_16x16x32_bf16 v[56:59], v[202:205], v[218:221], v[56:59]
	ds_read_b128 v[202:205], v136 offset:0x2800
	s_waitcnt lgkmcnt(2)
	s_nop 0
	v_mfma_f32_16x16x32_bf16 v[108:111], v[222:225], v[178:181], v[108:111]
	v_mfma_f32_16x16x32_bf16 v[104:107], v[226:229], v[178:181], v[104:107]
	v_mfma_f32_16x16x32_bf16 v[36:39], v[230:233], v[178:181], v[36:39]
	v_mfma_f32_16x16x32_bf16 v[32:35], v[234:237], v[178:181], v[32:35]
	ds_read_b128 v[178:181], v136 offset:0x3000
	v_mfma_f32_16x16x32_bf16 v[100:103], v[222:225], v[182:185], v[100:103]
	v_mfma_f32_16x16x32_bf16 v[96:99], v[226:229], v[182:185], v[96:99]
	v_mfma_f32_16x16x32_bf16 v[28:31], v[230:233], v[182:185], v[28:31]
	v_mfma_f32_16x16x32_bf16 v[24:27], v[234:237], v[182:185], v[24:27]
	ds_read_b128 v[182:185], v136 offset:0x3800
	s_waitcnt lgkmcnt(2)
	v_mfma_f32_16x16x32_bf16 v[124:127], v[222:225], v[206:209], v[124:127]
	s_add_i32 s11, s11, 0x10000
	s_add_u32 s4, s4, 0x80
	s_addc_u32 s5, s5, 0
	s_add_i32 s18, s18, 1
	s_waitcnt lgkmcnt(0)
	s_waitcnt vmcnt(0)
	s_waitcnt vmcnt(0) lgkmcnt(0)
	v_mfma_f32_16x16x32_bf16 v[120:123], v[226:229], v[206:209], v[120:123]
	s_barrier
	s_cmp_gt_u32 s18, 14
	s_cbranch_scc1 .Lgout0_nodma
	s_and_b32 s19, s11, 0x10000
	s_xor_b32 s24, s19, 0x10000
	s_add_i32 s24, s9, s24
	s_add_i32 s25, s24, 0x8000
	v_add3_u32 v253, s19, v141, v129
	ds_read_b128 v[214:217], v253 offset:0x1000
	ds_read_b128 v[218:221], v253 offset:0x1800
	v_mfma_f32_16x16x32_bf16 v[60:63], v[230:233], v[206:209], v[60:63]
	s_mov_b32 m0, s24
	v_lshl_add_u64 v[254:255], v[162:163], 0, s[4:5]
	global_load_lds_dwordx4 v[254:255], off
	v_mfma_f32_16x16x32_bf16 v[48:51], v[234:237], v[206:209], v[48:51]
	ds_read_b128 v[206:209], v253 offset:0
	v_mfma_f32_16x16x32_bf16 v[76:79], v[222:225], v[178:181], v[76:79]
	s_add_i32 m0, s24, 0x2000
	v_lshl_add_u64 v[254:255], v[164:165], 0, s[4:5]
	global_load_lds_dwordx4 v[254:255], off
	v_mfma_f32_16x16x32_bf16 v[72:75], v[226:229], v[178:181], v[72:75]
	v_mfma_f32_16x16x32_bf16 v[4:7], v[230:233], v[178:181], v[4:7]
	s_add_i32 m0, s24, 0x4000
	v_lshl_add_u64 v[254:255], v[166:167], 0, s[4:5]
	global_load_lds_dwordx4 v[254:255], off
	v_mfma_f32_16x16x32_bf16 v[0:3], v[234:237], v[178:181], v[0:3]
	v_add3_u32 v253, s19, v143, v129
	ds_read_b128 v[178:181], v253 offset:0
	v_mfma_f32_16x16x32_bf16 v[116:119], v[222:225], v[210:213], v[116:119]
	s_add_i32 m0, s24, 0x6000
	v_lshl_add_u64 v[254:255], v[168:169], 0, s[4:5]
	global_load_lds_dwordx4 v[254:255], off
	v_mfma_f32_16x16x32_bf16 v[112:115], v[226:229], v[210:213], v[112:115]
	v_mfma_f32_16x16x32_bf16 v[44:47], v[230:233], v[210:213], v[44:47]
	s_mov_b32 m0, s25
	v_lshl_add_u64 v[254:255], v[170:171], 0, s[4:5]
	global_load_lds_dwordx4 v[254:255], off
	v_mfma_f32_16x16x32_bf16 v[40:43], v[234:237], v[210:213], v[40:43]
	v_add3_u32 v253, s19, v141, v129
	ds_read_b128 v[210:213], v253 offset:0x800
	v_mfma_f32_16x16x32_bf16 v[68:71], v[222:225], v[182:185], v[68:71]
	s_add_i32 m0, s24, 0xa000
	v_lshl_add_u64 v[254:255], v[172:173], 0, s[4:5]
	global_load_lds_dwordx4 v[254:255], off
	v_mfma_f32_16x16x32_bf16 v[64:67], v[226:229], v[182:185], v[64:67]
	v_mfma_f32_16x16x32_bf16 v[52:55], v[230:233], v[182:185], v[52:55]
	s_add_i32 m0, s24, 0xc000
	v_lshl_add_u64 v[254:255], v[174:175], 0, s[4:5]
	global_load_lds_dwordx4 v[254:255], off
	v_mfma_f32_16x16x32_bf16 v[56:59], v[234:237], v[182:185], v[56:59]
	v_add3_u32 v253, s19, v143, v129
	ds_read_b128 v[182:185], v253 offset:0x800
	v_mfma_f32_16x16x32_bf16 v[92:95], v[222:225], v[198:201], v[92:95]
	s_add_i32 m0, s24, 0xe000
	v_lshl_add_u64 v[254:255], v[176:177], 0, s[4:5]
	global_load_lds_dwordx4 v[254:255], off
	v_mfma_f32_16x16x32_bf16 v[88:91], v[226:229], v[198:201], v[88:91]
	v_mfma_f32_16x16x32_bf16 v[20:23], v[230:233], v[198:201], v[20:23]
	v_mfma_f32_16x16x32_bf16 v[16:19], v[234:237], v[198:201], v[16:19]
	ds_read_b128 v[198:201], v253 offset:0x1000
	v_mfma_f32_16x16x32_bf16 v[84:87], v[222:225], v[202:205], v[84:87]
	v_mfma_f32_16x16x32_bf16 v[80:83], v[226:229], v[202:205], v[80:83]
	v_mfma_f32_16x16x32_bf16 v[12:15], v[230:233], v[202:205], v[12:15]
	v_mfma_f32_16x16x32_bf16 v[8:11], v[234:237], v[202:205], v[8:11]
	ds_read_b128 v[202:205], v253 offset:0x1800
	s_branch .Lgout0_body
.Lgout0_nodma:
	s_and_b32 s19, s11, 0x10000
	v_add3_u32 v253, s19, v141, v129
	ds_read_b128 v[214:217], v253 offset:0x1000
	ds_read_b128 v[218:221], v253 offset:0x1800
	v_mfma_f32_16x16x32_bf16 v[60:63], v[230:233], v[206:209], v[60:63]
	v_mfma_f32_16x16x32_bf16 v[48:51], v[234:237], v[206:209], v[48:51]
	ds_read_b128 v[206:209], v253 offset:0
	v_mfma_f32_16x16x32_bf16 v[76:79], v[222:225], v[178:181], v[76:79]
	v_mfma_f32_16x16x32_bf16 v[72:75], v[226:229], v[178:181], v[72:75]
	v_mfma_f32_16x16x32_bf16 v[4:7], v[230:233], v[178:181], v[4:7]
	v_mfma_f32_16x16x32_bf16 v[0:3], v[234:237], v[178:181], v[0:3]
	v_add3_u32 v253, s19, v143, v129
	ds_read_b128 v[178:181], v253 offset:0
	v_mfma_f32_16x16x32_bf16 v[116:119], v[222:225], v[210:213], v[116:119]
	v_mfma_f32_16x16x32_bf16 v[112:115], v[226:229], v[210:213], v[112:115]
	v_mfma_f32_16x16x32_bf16 v[44:47], v[230:233], v[210:213], v[44:47]
	v_mfma_f32_16x16x32_bf16 v[40:43], v[234:237], v[210:213], v[40:43]
	v_add3_u32 v253, s19, v141, v129
	ds_read_b128 v[210:213], v253 offset:0x800
	v_mfma_f32_16x16x32_bf16 v[68:71], v[222:225], v[182:185], v[68:71]
	v_mfma_f32_16x16x32_bf16 v[64:67], v[226:229], v[182:185], v[64:67]
	v_mfma_f32_16x16x32_bf16 v[52:55], v[230:233], v[182:185], v[52:55]
	v_mfma_f32_16x16x32_bf16 v[56:59], v[234:237], v[182:185], v[56:59]
	v_add3_u32 v253, s19, v143, v129
	ds_read_b128 v[182:185], v253 offset:0x800
	v_mfma_f32_16x16x32_bf16 v[92:95], v[222:225], v[198:201], v[92:95]
	v_mfma_f32_16x16x32_bf16 v[88:91], v[226:229], v[198:201], v[88:91]
	v_mfma_f32_16x16x32_bf16 v[20:23], v[230:233], v[198:201], v[20:23]
	v_mfma_f32_16x16x32_bf16 v[16:19], v[234:237], v[198:201], v[16:19]
	ds_read_b128 v[198:201], v253 offset:0x1000
	v_mfma_f32_16x16x32_bf16 v[84:87], v[222:225], v[202:205], v[84:87]
	v_mfma_f32_16x16x32_bf16 v[80:83], v[226:229], v[202:205], v[80:83]
	v_mfma_f32_16x16x32_bf16 v[12:15], v[230:233], v[202:205], v[12:15]
	v_mfma_f32_16x16x32_bf16 v[8:11], v[234:237], v[202:205], v[8:11]
	ds_read_b128 v[202:205], v253 offset:0x1800
	v_add_u32_e32 v147, s19, v143
	v_add_u32_e32 v136, s19, v141
	v_add_u32_e32 v145, v136, v129
	v_add_u32_e32 v147, v147, v135
	s_waitcnt lgkmcnt(4)
	v_add_u32_e32 v136, v136, v135
	v_mfma_f32_16x16x32_bf16 v[124:127], v[178:181], v[206:209], v[124:127]
	s_waitcnt lgkmcnt(2)
	v_mfma_f32_16x16x32_bf16 v[120:123], v[182:185], v[206:209], v[120:123]
	s_waitcnt lgkmcnt(1)
	v_mfma_f32_16x16x32_bf16 v[60:63], v[198:201], v[206:209], v[60:63]
	s_waitcnt lgkmcnt(0)
	v_mfma_f32_16x16x32_bf16 v[48:51], v[202:205], v[206:209], v[48:51]
	ds_read_b128 v[206:209], v145 offset:0x2000
	v_mfma_f32_16x16x32_bf16 v[116:119], v[178:181], v[210:213], v[116:119]
	v_mfma_f32_16x16x32_bf16 v[112:115], v[182:185], v[210:213], v[112:115]
	v_mfma_f32_16x16x32_bf16 v[44:47], v[198:201], v[210:213], v[44:47]
	v_mfma_f32_16x16x32_bf16 v[40:43], v[202:205], v[210:213], v[40:43]
	ds_read_b128 v[210:213], v145 offset:0x2800
	s_waitcnt lgkmcnt(2)
	s_nop 0
	v_mfma_f32_16x16x32_bf16 v[108:111], v[178:181], v[214:217], v[108:111]
	v_mfma_f32_16x16x32_bf16 v[104:107], v[182:185], v[214:217], v[104:107]
	v_mfma_f32_16x16x32_bf16 v[36:39], v[198:201], v[214:217], v[36:39]
	v_mfma_f32_16x16x32_bf16 v[32:35], v[202:205], v[214:217], v[32:35]
	ds_read_b128 v[214:217], v145 offset:0x3000
	v_mfma_f32_16x16x32_bf16 v[100:103], v[178:181], v[218:221], v[100:103]
	v_mfma_f32_16x16x32_bf16 v[96:99], v[182:185], v[218:221], v[96:99]
	v_mfma_f32_16x16x32_bf16 v[28:31], v[198:201], v[218:221], v[28:31]
	v_mfma_f32_16x16x32_bf16 v[24:27], v[202:205], v[218:221], v[24:27]
	ds_read_b128 v[218:221], v145 offset:0x3800
	ds_read_b128 v[222:225], v147 offset:0
	ds_read_b128 v[226:229], v147 offset:0x800
	ds_read_b128 v[230:233], v147 offset:0x1000
	ds_read_b128 v[234:237], v147 offset:0x1800
	s_waitcnt lgkmcnt(6)
	s_nop 0
	v_mfma_f32_16x16x32_bf16 v[92:95], v[178:181], v[206:209], v[92:95]
	v_mfma_f32_16x16x32_bf16 v[88:91], v[182:185], v[206:209], v[88:91]
	v_mfma_f32_16x16x32_bf16 v[20:23], v[198:201], v[206:209], v[20:23]
	v_mfma_f32_16x16x32_bf16 v[16:19], v[202:205], v[206:209], v[16:19]
	ds_read_b128 v[206:209], v136 offset:0
	v_mfma_f32_16x16x32_bf16 v[84:87], v[178:181], v[210:213], v[84:87]
	v_mfma_f32_16x16x32_bf16 v[80:83], v[182:185], v[210:213], v[80:83]
	v_mfma_f32_16x16x32_bf16 v[12:15], v[198:201], v[210:213], v[12:15]
	v_mfma_f32_16x16x32_bf16 v[8:11], v[202:205], v[210:213], v[8:11]
	ds_read_b128 v[210:213], v136 offset:0x800
	s_waitcnt lgkmcnt(6)
	s_nop 0
	v_mfma_f32_16x16x32_bf16 v[76:79], v[178:181], v[214:217], v[76:79]
	v_mfma_f32_16x16x32_bf16 v[68:71], v[178:181], v[218:221], v[68:71]
	ds_read_b128 v[178:181], v136 offset:0x1000
	v_mfma_f32_16x16x32_bf16 v[72:75], v[182:185], v[214:217], v[72:75]
	v_mfma_f32_16x16x32_bf16 v[64:67], v[182:185], v[218:221], v[64:67]
	ds_read_b128 v[182:185], v136 offset:0x1800
	s_waitcnt lgkmcnt(2)
	v_mfma_f32_16x16x32_bf16 v[4:7], v[198:201], v[214:217], v[4:7]
	v_mfma_f32_16x16x32_bf16 v[52:55], v[198:201], v[218:221], v[52:55]
	ds_read_b128 v[198:201], v136 offset:0x2000
	v_mfma_f32_16x16x32_bf16 v[0:3], v[202:205], v[214:217], v[0:3]
	v_mfma_f32_16x16x32_bf16 v[56:59], v[202:205], v[218:221], v[56:59]
	ds_read_b128 v[202:205], v136 offset:0x2800
	s_waitcnt lgkmcnt(2)
	s_nop 0
	v_mfma_f32_16x16x32_bf16 v[108:111], v[222:225], v[178:181], v[108:111]
	v_mfma_f32_16x16x32_bf16 v[104:107], v[226:229], v[178:181], v[104:107]
	v_mfma_f32_16x16x32_bf16 v[36:39], v[230:233], v[178:181], v[36:39]
	v_mfma_f32_16x16x32_bf16 v[32:35], v[234:237], v[178:181], v[32:35]
	ds_read_b128 v[178:181], v136 offset:0x3000
	v_mfma_f32_16x16x32_bf16 v[100:103], v[222:225], v[182:185], v[100:103]
	v_mfma_f32_16x16x32_bf16 v[96:99], v[226:229], v[182:185], v[96:99]
	v_mfma_f32_16x16x32_bf16 v[28:31], v[230:233], v[182:185], v[28:31]
	v_mfma_f32_16x16x32_bf16 v[24:27], v[234:237], v[182:185], v[24:27]
	ds_read_b128 v[182:185], v136 offset:0x3800
	s_waitcnt lgkmcnt(2)
	v_mfma_f32_16x16x32_bf16 v[124:127], v[222:225], v[206:209], v[124:127]
	s_add_i32 s11, s11, 0x10000
	s_add_u32 s4, s4, 0x80
	s_addc_u32 s5, s5, 0
	s_add_i32 s18, s18, 1
	s_waitcnt lgkmcnt(0)
	s_waitcnt vmcnt(0)
	s_waitcnt vmcnt(0) lgkmcnt(0)
	v_mfma_f32_16x16x32_bf16 v[120:123], v[226:229], v[206:209], v[120:123]
	s_barrier
	v_mfma_f32_16x16x32_bf16 v[60:63], v[230:233], v[206:209], v[60:63]
	v_mfma_f32_16x16x32_bf16 v[48:51], v[234:237], v[206:209], v[48:51]
	v_mfma_f32_16x16x32_bf16 v[116:119], v[222:225], v[210:213], v[116:119]
	v_mfma_f32_16x16x32_bf16 v[112:115], v[226:229], v[210:213], v[112:115]
	v_mfma_f32_16x16x32_bf16 v[44:47], v[230:233], v[210:213], v[44:47]
	v_mfma_f32_16x16x32_bf16 v[40:43], v[234:237], v[210:213], v[40:43]
	v_mfma_f32_16x16x32_bf16 v[92:95], v[222:225], v[198:201], v[92:95]
	v_mfma_f32_16x16x32_bf16 v[88:91], v[226:229], v[198:201], v[88:91]
	v_mfma_f32_16x16x32_bf16 v[20:23], v[230:233], v[198:201], v[20:23]
	v_mfma_f32_16x16x32_bf16 v[16:19], v[234:237], v[198:201], v[16:19]
	v_mfma_f32_16x16x32_bf16 v[84:87], v[222:225], v[202:205], v[84:87]
	v_mfma_f32_16x16x32_bf16 v[80:83], v[226:229], v[202:205], v[80:83]
	v_mfma_f32_16x16x32_bf16 v[12:15], v[230:233], v[202:205], v[12:15]
	v_mfma_f32_16x16x32_bf16 v[8:11], v[234:237], v[202:205], v[8:11]
	v_mfma_f32_16x16x32_bf16 v[76:79], v[222:225], v[178:181], v[76:79]
	v_mfma_f32_16x16x32_bf16 v[72:75], v[226:229], v[178:181], v[72:75]
	v_mfma_f32_16x16x32_bf16 v[4:7], v[230:233], v[178:181], v[4:7]
	v_mfma_f32_16x16x32_bf16 v[0:3], v[234:237], v[178:181], v[0:3]
	v_mfma_f32_16x16x32_bf16 v[68:71], v[222:225], v[182:185], v[68:71]
	v_mfma_f32_16x16x32_bf16 v[64:67], v[226:229], v[182:185], v[64:67]
	v_mfma_f32_16x16x32_bf16 v[52:55], v[230:233], v[182:185], v[52:55]
	v_mfma_f32_16x16x32_bf16 v[56:59], v[234:237], v[182:185], v[56:59]

.LBB0_892:
	s_or_b64 exec, exec, s[8:9]
	v_cvt_f32_u32_e32 v4, v2
	s_waitcnt vmcnt(0)
	v_readfirstlane_b32 s6, v3
	v_sub_u32_e32 v3, 0, v2
	v_rcp_iflag_f32_e32 v4, v4
	v_add_u32_e32 v5, s6, v1
	v_mul_f32_e32 v4, 0x4f7ffffe, v4
	v_cvt_u32_f32_e32 v4, v4
	v_mul_lo_u32 v1, v3, v4
	v_mul_hi_u32 v1, v4, v1
	v_add_u32_e32 v1, v4, v1
	v_mul_hi_u32 v1, v5, v1
	v_mul_lo_u32 v3, v1, v2
	v_sub_u32_e32 v3, v5, v3
	v_add_u32_e32 v4, 1, v1
	v_cmp_ge_u32_e32 vcc, v3, v2
	s_nop 1
	v_cndmask_b32_e32 v1, v1, v4, vcc
	v_sub_u32_e32 v4, v3, v2
	v_cndmask_b32_e32 v3, v3, v4, vcc
	v_add_u32_e32 v4, 1, v1
	v_cmp_ge_u32_e32 vcc, v3, v2
	v_add_u32_e32 v3, 1, v5
	s_nop 0
	v_cndmask_b32_e32 v1, v1, v4, vcc
	v_mul_lo_u32 v4, v2, v1
	v_add_u32_e32 v2, v4, v2
	v_cmp_ne_u32_e32 vcc, v3, v2
	s_and_saveexec_b64 s[6:7], vcc
	s_xor_b64 s[6:7], exec, s[6:7]
	s_cbranch_execz .LBB0_906
	s_waitcnt lgkmcnt(0)
	buffer_inv sc1
	v_mov_b32_e32 v0, 0
	v_mov_b32_e32 v1, 5
	s_add_u32 s12, s86, 0xe7b4500
	s_addc_u32 s13, s87, 0
	global_load_dword v0, v0, s[12:13] sc1
	s_waitcnt vmcnt(0)
	v_cmp_eq_u32_e32 vcc, v0, v1
	s_and_saveexec_b64 s[8:9], vcc
	s_cbranch_execz .LBB0_905
	s_add_u32 s10, s86, 0xe7b1200
	s_addc_u32 s11, s87, 0
	s_mov_b32 s30, 1
	s_mov_b64 s[14:15], 0
	v_mov_b32_e32 v0, 0
	s_branch .LBB0_896

.LBB0_955:
	s_or_b64 exec, exec, s[8:9]
	v_cvt_f32_u32_e32 v4, v2
	s_waitcnt vmcnt(0)
	v_readfirstlane_b32 s6, v3
	v_sub_u32_e32 v3, 0, v2
	v_rcp_iflag_f32_e32 v4, v4
	v_add_u32_e32 v5, s6, v1
	v_mul_f32_e32 v4, 0x4f7ffffe, v4
	v_cvt_u32_f32_e32 v4, v4
	v_mul_lo_u32 v1, v3, v4
	v_mul_hi_u32 v1, v4, v1
	v_add_u32_e32 v1, v4, v1
	v_mul_hi_u32 v1, v5, v1
	v_mul_lo_u32 v3, v1, v2
	v_sub_u32_e32 v3, v5, v3
	v_add_u32_e32 v4, 1, v1
	v_cmp_ge_u32_e32 vcc, v3, v2
	s_nop 1
	v_cndmask_b32_e32 v1, v1, v4, vcc
	v_sub_u32_e32 v4, v3, v2
	v_cndmask_b32_e32 v3, v3, v4, vcc
	v_add_u32_e32 v4, 1, v1
	v_cmp_ge_u32_e32 vcc, v3, v2
	v_add_u32_e32 v3, 1, v5
	s_nop 0
	v_cndmask_b32_e32 v1, v1, v4, vcc
	v_mul_lo_u32 v4, v2, v1
	v_add_u32_e32 v2, v4, v2
	v_cmp_ne_u32_e32 vcc, v3, v2
	s_and_saveexec_b64 s[6:7], vcc
	s_xor_b64 s[6:7], exec, s[6:7]
	s_cbranch_execz .LBB0_969
	s_waitcnt lgkmcnt(0)
	buffer_inv sc1
	v_mov_b32_e32 v0, 0
	v_mov_b32_e32 v1, 6
	s_add_u32 s12, s86, 0xe7b4500
	s_addc_u32 s13, s87, 0
	global_load_dword v0, v0, s[12:13] sc1
	s_waitcnt vmcnt(0)
	v_cmp_eq_u32_e32 vcc, v0, v1
	s_and_saveexec_b64 s[8:9], vcc
	s_cbranch_execz .LBB0_968
	s_add_u32 s10, s86, 0xe7b1200
	s_addc_u32 s11, s87, 0
	s_mov_b32 s30, 1
	s_mov_b64 s[14:15], 0
	v_mov_b32_e32 v0, 0
	s_branch .LBB0_959

.LBB0_1004:
	s_waitcnt vmcnt(2)
	v_add_u32_e32 v6, s5, v139
	v_cmp_lt_i32_e32 vcc, s13, v6
	s_and_saveexec_b64 s[0:1], vcc
	s_xor_b64 s[0:1], exec, s[0:1]
	v_add_u32_e32 v4, 0xffffff78, v6
	v_mul_hi_u32 v3, v4, s12
	v_lshrrev_b32_e32 v5, 1, v3
	v_lshl_add_u32 v3, v5, 8, v149
	v_lshl_add_u32 v5, v5, 1, v5
	v_sub_u32_e32 v4, v4, v5
	s_or_saveexec_b64 s[0:1], s[0:1]
	v_mov_b32_e32 v5, 0x100
	s_xor_b64 exec, exec, s[0:1]
	v_mul_hi_i32 v3, v6, s14
	v_lshrrev_b32_e32 v4, 31, v3
	v_ashrrev_i32_e32 v3, 3, v3
	v_add_u32_e32 v4, v3, v4
	v_lshlrev_b32_e32 v3, 11, v4
	v_lshl_add_u32 v4, v4, 4, v4
	v_sub_u32_e32 v4, v6, v4
	v_mov_b32_e32 v5, 0x800
	s_or_b64 exec, exec, s[0:1]
	s_mul_i32 s0, s27, 0x7e
	v_add_u32_e32 v8, s0, v129
	v_add_u32_e32 v6, s25, v8
	v_lshl_add_u32 v9, v6, 11, v136
	v_mad_u64_u32 v[6:7], s[0:1], v1, s15, v[138:139]
	s_mul_i32 s0, s7, 0x7e
	v_add_u32_e32 v0, v6, v0
	v_add_u32_e32 v10, s0, v129
	v_lshl_add_u32 v7, v0, 11, v140
	v_add_u32_e32 v0, s6, v10
	v_lshl_add_u32 v11, v0, 11, v136
	v_mad_u64_u32 v[0:1], s[0:1], v4, s15, v[142:143]
	v_cmp_gt_u32_e32 vcc, s24, v10
	v_add_u32_e32 v1, v0, v3
	v_readfirstlane_b32 s0, v128
	v_cndmask_b32_e32 v3, v145, v11, vcc
	v_cmp_lt_u32_e32 vcc, v6, v2
	s_lshr_b32 s1, s0, 1
	v_lshl_add_u32 v1, v1, 11, v144
	v_cndmask_b32_e32 v2, v145, v7, vcc
	v_cmp_gt_u32_e32 vcc, s26, v8
	v_subrev_u32_e32 v134, s86, v3
	s_and_b32 s1, s1, 0x1ffff80
	v_cndmask_b32_e32 v3, v145, v9, vcc
	v_cmp_lt_u32_e32 vcc, v0, v5
	v_subrev_u32_e32 v2, s86, v2
	s_lshl_b32 s7, s4, 19
	v_cndmask_b32_e32 v0, v145, v1, vcc
	v_or_b32_e32 v1, s1, v189
	s_and_b32 s1, s0, 0xc0
	s_lshl_b32 s0, s0, 4
	s_and_b32 s6, s0, 0x7ffffc00
	s_mov_b32 m0, s6
	v_subrev_u32_e32 v4, s86, v3
	global_load_lds_dwordx4 v134, s[86:87]
	s_add_i32 m0, s6, 0x2000
	v_subrev_u32_e32 v0, s86, v0
	global_load_lds_dwordx4 v2, s[86:87]
	s_add_i32 m0, s6, 0x4000
	v_add_u32_e32 v6, s7, v146
	s_add_i32 s0, s6, 0x8000
	global_load_lds_dwordx4 v4, s[86:87]
	s_add_i32 m0, s6, 0x6000
	v_add_u32_e32 v8, s7, v148
	global_load_lds_dwordx4 v0, s[86:87]
	v_and_b32_e32 v6, 0xfffff870, v6
	s_mov_b32 m0, s0
	v_add_u32_e32 v9, s7, v150
	global_load_lds_dwordx4 v6, s[86:87]
	v_and_b32_e32 v8, 0xfffff870, v8
	s_add_i32 m0, s6, 0xa000
	v_add_u32_e32 v10, s7, v152
	global_load_lds_dwordx4 v8, s[86:87]
	v_and_b32_e32 v8, 0xfffff870, v9
	s_add_i32 m0, s6, 0xc000
	v_and_b32_e32 v10, 0xfffff870, v10
	global_load_lds_dwordx4 v8, s[86:87]
	s_add_i32 m0, s6, 0xe000
	v_lshlrev_b32_e32 v155, 7, v1
	global_load_lds_dwordx4 v10, s[86:87]
	v_or_b32_e32 v1, s1, v189
	v_lshl_or_b32 v172, v1, 7, v147
	v_mov_b32_e32 v1, v135
	s_waitcnt vmcnt(0)
	v_lshl_add_u64 v[162:163], s[56:57], 0, v[0:1]
	v_add_u32_e32 v0, s7, v154
	v_mov_b32_e32 v3, v135
	v_mov_b32_e32 v5, v135
	v_mov_b32_e32 v7, v135
	v_mov_b32_e32 v9, v135
	v_mov_b32_e32 v11, v135
	v_lshl_add_u64 v[156:157], s[56:57], 0, v[134:135]
	v_and_b32_e32 v134, -16, v0
	v_mov_b32_e32 v52, 0
	v_lshl_add_u64 v[158:159], s[56:57], 0, v[2:3]
	v_lshl_add_u64 v[160:161], s[56:57], 0, v[4:5]
	v_lshl_add_u64 v[164:165], s[56:57], 0, v[6:7]
	v_lshl_add_u64 v[166:167], s[56:57], 0, v[134:135]
	v_lshl_add_u64 v[168:169], s[56:57], 0, v[8:9]
	v_lshl_add_u64 v[170:171], s[56:57], 0, v[10:11]
	s_mov_b32 s7, 0
	s_mov_b64 s[0:1], 0
	v_mov_b32_e32 v53, v52
	v_mov_b32_e32 v54, v52
	v_mov_b32_e32 v55, v52
	v_mov_b32_e32 v0, v52
	v_mov_b32_e32 v1, v52
	v_mov_b32_e32 v2, v52
	v_mov_b32_e32 v3, v52
	v_mov_b32_e32 v64, v52
	v_mov_b32_e32 v65, v52
	v_mov_b32_e32 v66, v52
	v_mov_b32_e32 v67, v52
	v_mov_b32_e32 v68, v52
	v_mov_b32_e32 v69, v52
	v_mov_b32_e32 v70, v52
	v_mov_b32_e32 v71, v52
	v_mov_b32_e32 v4, v52
	v_mov_b32_e32 v5, v52
	v_mov_b32_e32 v6, v52
	v_mov_b32_e32 v7, v52
	v_mov_b32_e32 v8, v52
	v_mov_b32_e32 v9, v52
	v_mov_b32_e32 v10, v52
	v_mov_b32_e32 v11, v52
	v_mov_b32_e32 v72, v52
	v_mov_b32_e32 v73, v52
	v_mov_b32_e32 v74, v52
	v_mov_b32_e32 v75, v52
	v_mov_b32_e32 v76, v52
	v_mov_b32_e32 v77, v52
	v_mov_b32_e32 v78, v52
	v_mov_b32_e32 v79, v52
	s_waitcnt vmcnt(0)
	v_mov_b32_e32 v12, v52
	v_mov_b32_e32 v13, v52
	v_mov_b32_e32 v14, v52
	v_mov_b32_e32 v15, v52
	v_mov_b32_e32 v16, v52
	v_mov_b32_e32 v17, v52
	v_mov_b32_e32 v18, v52
	v_mov_b32_e32 v19, v52
	v_mov_b32_e32 v80, v52
	v_mov_b32_e32 v81, v52
	v_mov_b32_e32 v82, v52
	v_mov_b32_e32 v83, v52
	v_mov_b32_e32 v84, v52
	v_mov_b32_e32 v85, v52
	v_mov_b32_e32 v86, v52
	v_mov_b32_e32 v87, v52
	v_mov_b32_e32 v20, v52
	v_mov_b32_e32 v21, v52
	v_mov_b32_e32 v22, v52
	v_mov_b32_e32 v23, v52
	v_mov_b32_e32 v24, v52
	v_mov_b32_e32 v25, v52
	v_mov_b32_e32 v26, v52
	v_mov_b32_e32 v27, v52
	v_mov_b32_e32 v88, v52
	v_mov_b32_e32 v89, v52
	v_mov_b32_e32 v90, v52
	v_mov_b32_e32 v91, v52
	v_mov_b32_e32 v92, v52
	v_mov_b32_e32 v93, v52
	v_mov_b32_e32 v94, v52
	v_mov_b32_e32 v95, v52
	v_mov_b32_e32 v28, v52
	v_mov_b32_e32 v29, v52
	v_mov_b32_e32 v30, v52
	v_mov_b32_e32 v31, v52
	v_mov_b32_e32 v32, v52
	v_mov_b32_e32 v33, v52
	v_mov_b32_e32 v34, v52
	v_mov_b32_e32 v35, v52
	s_waitcnt vmcnt(0)
	v_mov_b32_e32 v96, v52
	v_mov_b32_e32 v97, v52
	v_mov_b32_e32 v98, v52
	v_mov_b32_e32 v99, v52
	v_mov_b32_e32 v100, v52
	v_mov_b32_e32 v101, v52
	v_mov_b32_e32 v102, v52
	v_mov_b32_e32 v103, v52
	v_mov_b32_e32 v36, v52
	v_mov_b32_e32 v37, v52
	v_mov_b32_e32 v38, v52
	v_mov_b32_e32 v39, v52
	v_mov_b32_e32 v40, v52
	v_mov_b32_e32 v41, v52
	v_mov_b32_e32 v42, v52
	v_mov_b32_e32 v43, v52
	v_mov_b32_e32 v104, v52
	v_mov_b32_e32 v105, v52
	v_mov_b32_e32 v106, v52
	v_mov_b32_e32 v107, v52
	v_mov_b32_e32 v108, v52
	v_mov_b32_e32 v109, v52
	v_mov_b32_e32 v110, v52
	v_mov_b32_e32 v111, v52
	v_mov_b32_e32 v44, v52
	v_mov_b32_e32 v45, v52
	v_mov_b32_e32 v46, v52
	v_mov_b32_e32 v47, v52
	v_mov_b32_e32 v48, v52
	v_mov_b32_e32 v49, v52
	v_mov_b32_e32 v50, v52
	v_mov_b32_e32 v51, v52
	v_mov_b32_e32 v112, v52
	v_mov_b32_e32 v113, v52
	v_mov_b32_e32 v114, v52
	v_mov_b32_e32 v115, v52
	v_mov_b32_e32 v116, v52
	v_mov_b32_e32 v117, v52
	v_mov_b32_e32 v118, v52
	v_mov_b32_e32 v119, v52
	v_mov_b32_e32 v56, v52
	v_mov_b32_e32 v57, v52
	v_mov_b32_e32 v58, v52
	v_mov_b32_e32 v59, v52
	v_mov_b32_e32 v60, v52
	v_mov_b32_e32 v61, v52
	v_mov_b32_e32 v62, v52
	v_mov_b32_e32 v63, v52
	v_mov_b32_e32 v120, v52
	v_mov_b32_e32 v121, v52
	v_mov_b32_e32 v122, v52
	v_mov_b32_e32 v123, v52
	v_mov_b32_e32 v124, v52
	v_mov_b32_e32 v125, v52
	v_mov_b32_e32 v126, v52
	v_mov_b32_e32 v127, v52
	s_waitcnt lgkmcnt(0)
	s_barrier
	s_mov_b32 s24, 0x10000
	s_and_b32 s24, s7, 0x10000
	s_xor_b32 s25, s24, 0x10000
	s_add_i32 s25, s6, s25
	s_add_i32 s26, s25, 0x8000
	s_mov_b32 m0, s25
	v_lshl_add_u64 v[254:255], v[156:157], 0, s[0:1]
	global_load_lds_dwordx4 v[254:255], off
	s_add_i32 m0, s25, 0x2000
	v_lshl_add_u64 v[254:255], v[158:159], 0, s[0:1]
	global_load_lds_dwordx4 v[254:255], off
	s_add_i32 m0, s25, 0x4000
	v_lshl_add_u64 v[254:255], v[160:161], 0, s[0:1]
	global_load_lds_dwordx4 v[254:255], off
	s_add_i32 m0, s25, 0x6000
	v_lshl_add_u64 v[254:255], v[162:163], 0, s[0:1]
	global_load_lds_dwordx4 v[254:255], off
	s_mov_b32 m0, s26
	v_lshl_add_u64 v[254:255], v[164:165], 0, s[0:1]
	global_load_lds_dwordx4 v[254:255], off
	s_add_i32 m0, s25, 0xa000
	v_lshl_add_u64 v[254:255], v[166:167], 0, s[0:1]
	global_load_lds_dwordx4 v[254:255], off
	s_add_i32 m0, s25, 0xc000
	v_lshl_add_u64 v[254:255], v[168:169], 0, s[0:1]
	global_load_lds_dwordx4 v[254:255], off
	s_add_i32 m0, s25, 0xe000
	v_lshl_add_u64 v[254:255], v[170:171], 0, s[0:1]
	global_load_lds_dwordx4 v[254:255], off
	v_add3_u32 v253, s24, v155, v141
	ds_read_b128 v[210:213], v253 offset:0x1000
	ds_read_b128 v[214:217], v253 offset:0x1800
	ds_read_b128 v[202:205], v253 offset:0
	v_add3_u32 v253, s24, v172, v141
	ds_read_b128 v[174:177], v253 offset:0
	v_add3_u32 v253, s24, v155, v141
	ds_read_b128 v[206:209], v253 offset:0x800
	v_add3_u32 v253, s24, v172, v141
	ds_read_b128 v[178:181], v253 offset:0x800
	ds_read_b128 v[182:185], v253 offset:0x1000
	ds_read_b128 v[198:201], v253 offset:0x1800
.Lgffu0_body:
	v_add_u32_e32 v186, s24, v172
	v_add_u32_e32 v134, s24, v155
	v_add_u32_e32 v173, v134, v141
	v_add_u32_e32 v186, v186, v143
	s_waitcnt lgkmcnt(4)
	v_add_u32_e32 v134, v134, v143
	v_mfma_f32_16x16x32_bf16 v[124:127], v[174:177], v[202:205], v[124:127]
	s_waitcnt lgkmcnt(2)
	v_mfma_f32_16x16x32_bf16 v[120:123], v[178:181], v[202:205], v[120:123]
	s_waitcnt lgkmcnt(1)
	v_mfma_f32_16x16x32_bf16 v[60:63], v[182:185], v[202:205], v[60:63]
	s_waitcnt lgkmcnt(0)
	v_mfma_f32_16x16x32_bf16 v[56:59], v[198:201], v[202:205], v[56:59]
	ds_read_b128 v[202:205], v173 offset:0x2000
	v_mfma_f32_16x16x32_bf16 v[116:119], v[174:177], v[206:209], v[116:119]
	v_mfma_f32_16x16x32_bf16 v[112:115], v[178:181], v[206:209], v[112:115]
	v_mfma_f32_16x16x32_bf16 v[48:51], v[182:185], v[206:209], v[48:51]
	v_mfma_f32_16x16x32_bf16 v[44:47], v[198:201], v[206:209], v[44:47]
	ds_read_b128 v[206:209], v173 offset:0x2800
	s_waitcnt lgkmcnt(2)
	s_nop 0
	v_mfma_f32_16x16x32_bf16 v[108:111], v[174:177], v[210:213], v[108:111]
	v_mfma_f32_16x16x32_bf16 v[104:107], v[178:181], v[210:213], v[104:107]
	v_mfma_f32_16x16x32_bf16 v[40:43], v[182:185], v[210:213], v[40:43]
	v_mfma_f32_16x16x32_bf16 v[36:39], v[198:201], v[210:213], v[36:39]
	ds_read_b128 v[210:213], v173 offset:0x3000
	v_mfma_f32_16x16x32_bf16 v[100:103], v[174:177], v[214:217], v[100:103]
	v_mfma_f32_16x16x32_bf16 v[96:99], v[178:181], v[214:217], v[96:99]
	v_mfma_f32_16x16x32_bf16 v[32:35], v[182:185], v[214:217], v[32:35]
	v_mfma_f32_16x16x32_bf16 v[28:31], v[198:201], v[214:217], v[28:31]
	ds_read_b128 v[214:217], v173 offset:0x3800
	ds_read_b128 v[218:221], v186 offset:0
	ds_read_b128 v[222:225], v186 offset:0x800
	ds_read_b128 v[226:229], v186 offset:0x1000
	ds_read_b128 v[230:233], v186 offset:0x1800
	s_waitcnt lgkmcnt(6)
	s_nop 0
	v_mfma_f32_16x16x32_bf16 v[92:95], v[174:177], v[202:205], v[92:95]
	v_mfma_f32_16x16x32_bf16 v[88:91], v[178:181], v[202:205], v[88:91]
	v_mfma_f32_16x16x32_bf16 v[24:27], v[182:185], v[202:205], v[24:27]
	v_mfma_f32_16x16x32_bf16 v[20:23], v[198:201], v[202:205], v[20:23]
	ds_read_b128 v[202:205], v134 offset:0
	v_mfma_f32_16x16x32_bf16 v[84:87], v[174:177], v[206:209], v[84:87]
	v_mfma_f32_16x16x32_bf16 v[80:83], v[178:181], v[206:209], v[80:83]
	v_mfma_f32_16x16x32_bf16 v[16:19], v[182:185], v[206:209], v[16:19]
	v_mfma_f32_16x16x32_bf16 v[12:15], v[198:201], v[206:209], v[12:15]
	ds_read_b128 v[206:209], v134 offset:0x800
	s_waitcnt lgkmcnt(6)
	s_nop 0
	v_mfma_f32_16x16x32_bf16 v[76:79], v[174:177], v[210:213], v[76:79]
	v_mfma_f32_16x16x32_bf16 v[68:71], v[174:177], v[214:217], v[68:71]
	ds_read_b128 v[174:177], v134 offset:0x1000
	v_mfma_f32_16x16x32_bf16 v[72:75], v[178:181], v[210:213], v[72:75]
	v_mfma_f32_16x16x32_bf16 v[64:67], v[178:181], v[214:217], v[64:67]
	ds_read_b128 v[178:181], v134 offset:0x1800
	s_waitcnt lgkmcnt(2)
	v_mfma_f32_16x16x32_bf16 v[8:11], v[182:185], v[210:213], v[8:11]
	v_mfma_f32_16x16x32_bf16 v[0:3], v[182:185], v[214:217], v[0:3]
	ds_read_b128 v[182:185], v134 offset:0x2000
	v_mfma_f32_16x16x32_bf16 v[4:7], v[198:201], v[210:213], v[4:7]
	v_mfma_f32_16x16x32_bf16 v[52:55], v[198:201], v[214:217], v[52:55]
	ds_read_b128 v[198:201], v134 offset:0x2800
	s_waitcnt lgkmcnt(2)
	s_nop 0
	v_mfma_f32_16x16x32_bf16 v[108:111], v[218:221], v[174:177], v[108:111]
	v_mfma_f32_16x16x32_bf16 v[104:107], v[222:225], v[174:177], v[104:107]
	v_mfma_f32_16x16x32_bf16 v[40:43], v[226:229], v[174:177], v[40:43]
	v_mfma_f32_16x16x32_bf16 v[36:39], v[230:233], v[174:177], v[36:39]
	ds_read_b128 v[174:177], v134 offset:0x3000
	v_mfma_f32_16x16x32_bf16 v[100:103], v[218:221], v[178:181], v[100:103]
	v_mfma_f32_16x16x32_bf16 v[96:99], v[222:225], v[178:181], v[96:99]
	v_mfma_f32_16x16x32_bf16 v[32:35], v[226:229], v[178:181], v[32:35]
	v_mfma_f32_16x16x32_bf16 v[28:31], v[230:233], v[178:181], v[28:31]
	ds_read_b128 v[178:181], v134 offset:0x3800
	s_waitcnt lgkmcnt(2)
	v_mfma_f32_16x16x32_bf16 v[124:127], v[218:221], v[202:205], v[124:127]
	s_add_i32 s7, s7, 0x10000
	s_add_u32 s0, s0, 0x80
	s_addc_u32 s1, s1, 0
	s_waitcnt lgkmcnt(0)
	s_waitcnt vmcnt(0)
	s_waitcnt vmcnt(0) lgkmcnt(0)
	v_mfma_f32_16x16x32_bf16 v[120:123], v[222:225], v[202:205], v[120:123]
	s_barrier
	s_cmpk_eq_i32 s0, 0x780
	s_cbranch_scc1 .Lgffu0_nodma
	s_mov_b32 s24, 0x10000
	s_and_b32 s24, s7, 0x10000
	s_xor_b32 s25, s24, 0x10000
	s_add_i32 s25, s6, s25
	s_add_i32 s26, s25, 0x8000
	v_add3_u32 v253, s24, v155, v141
	ds_read_b128 v[210:213], v253 offset:0x1000
	ds_read_b128 v[214:217], v253 offset:0x1800
	v_mfma_f32_16x16x32_bf16 v[60:63], v[226:229], v[202:205], v[60:63]
	s_mov_b32 m0, s25
	v_lshl_add_u64 v[254:255], v[156:157], 0, s[0:1]
	global_load_lds_dwordx4 v[254:255], off
	v_mfma_f32_16x16x32_bf16 v[56:59], v[230:233], v[202:205], v[56:59]
	ds_read_b128 v[202:205], v253 offset:0
	v_mfma_f32_16x16x32_bf16 v[76:79], v[218:221], v[174:177], v[76:79]
	s_add_i32 m0, s25, 0x2000
	v_lshl_add_u64 v[254:255], v[158:159], 0, s[0:1]
	global_load_lds_dwordx4 v[254:255], off
	v_mfma_f32_16x16x32_bf16 v[72:75], v[222:225], v[174:177], v[72:75]
	v_mfma_f32_16x16x32_bf16 v[8:11], v[226:229], v[174:177], v[8:11]
	s_add_i32 m0, s25, 0x4000
	v_lshl_add_u64 v[254:255], v[160:161], 0, s[0:1]
	global_load_lds_dwordx4 v[254:255], off
	v_mfma_f32_16x16x32_bf16 v[4:7], v[230:233], v[174:177], v[4:7]
	v_add3_u32 v253, s24, v172, v141
	ds_read_b128 v[174:177], v253 offset:0
	v_mfma_f32_16x16x32_bf16 v[116:119], v[218:221], v[206:209], v[116:119]
	s_add_i32 m0, s25, 0x6000
	v_lshl_add_u64 v[254:255], v[162:163], 0, s[0:1]
	global_load_lds_dwordx4 v[254:255], off
	v_mfma_f32_16x16x32_bf16 v[112:115], v[222:225], v[206:209], v[112:115]
	v_mfma_f32_16x16x32_bf16 v[48:51], v[226:229], v[206:209], v[48:51]
	s_mov_b32 m0, s26
	v_lshl_add_u64 v[254:255], v[164:165], 0, s[0:1]
	global_load_lds_dwordx4 v[254:255], off
	v_mfma_f32_16x16x32_bf16 v[44:47], v[230:233], v[206:209], v[44:47]
	v_add3_u32 v253, s24, v155, v141
	ds_read_b128 v[206:209], v253 offset:0x800
	v_mfma_f32_16x16x32_bf16 v[68:71], v[218:221], v[178:181], v[68:71]
	s_add_i32 m0, s25, 0xa000
	v_lshl_add_u64 v[254:255], v[166:167], 0, s[0:1]
	global_load_lds_dwordx4 v[254:255], off
	v_mfma_f32_16x16x32_bf16 v[64:67], v[222:225], v[178:181], v[64:67]
	v_mfma_f32_16x16x32_bf16 v[0:3], v[226:229], v[178:181], v[0:3]
	s_add_i32 m0, s25, 0xc000
	v_lshl_add_u64 v[254:255], v[168:169], 0, s[0:1]
	global_load_lds_dwordx4 v[254:255], off
	v_mfma_f32_16x16x32_bf16 v[52:55], v[230:233], v[178:181], v[52:55]
	v_add3_u32 v253, s24, v172, v141
	ds_read_b128 v[178:181], v253 offset:0x800
	v_mfma_f32_16x16x32_bf16 v[92:95], v[218:221], v[182:185], v[92:95]
	s_add_i32 m0, s25, 0xe000
	v_lshl_add_u64 v[254:255], v[170:171], 0, s[0:1]
	global_load_lds_dwordx4 v[254:255], off
	v_mfma_f32_16x16x32_bf16 v[88:91], v[222:225], v[182:185], v[88:91]
	v_mfma_f32_16x16x32_bf16 v[24:27], v[226:229], v[182:185], v[24:27]
	v_mfma_f32_16x16x32_bf16 v[20:23], v[230:233], v[182:185], v[20:23]
	ds_read_b128 v[182:185], v253 offset:0x1000
	v_mfma_f32_16x16x32_bf16 v[84:87], v[218:221], v[198:201], v[84:87]
	v_mfma_f32_16x16x32_bf16 v[80:83], v[222:225], v[198:201], v[80:83]
	v_mfma_f32_16x16x32_bf16 v[16:19], v[226:229], v[198:201], v[16:19]
	v_mfma_f32_16x16x32_bf16 v[12:15], v[230:233], v[198:201], v[12:15]
	ds_read_b128 v[198:201], v253 offset:0x1800
	s_branch .Lgffu0_body
.Lgffu0_nodma:
	s_mov_b32 s24, 0x10000
	v_add3_u32 v253, s24, v155, v141
	ds_read_b128 v[210:213], v253 offset:0x1000
	ds_read_b128 v[214:217], v253 offset:0x1800
	v_mfma_f32_16x16x32_bf16 v[60:63], v[226:229], v[202:205], v[60:63]
	v_mfma_f32_16x16x32_bf16 v[56:59], v[230:233], v[202:205], v[56:59]
	ds_read_b128 v[202:205], v253 offset:0
	v_mfma_f32_16x16x32_bf16 v[76:79], v[218:221], v[174:177], v[76:79]
	v_mfma_f32_16x16x32_bf16 v[72:75], v[222:225], v[174:177], v[72:75]
	v_mfma_f32_16x16x32_bf16 v[8:11], v[226:229], v[174:177], v[8:11]
	v_mfma_f32_16x16x32_bf16 v[4:7], v[230:233], v[174:177], v[4:7]
	v_add3_u32 v253, s24, v172, v141
	ds_read_b128 v[174:177], v253 offset:0
	v_mfma_f32_16x16x32_bf16 v[116:119], v[218:221], v[206:209], v[116:119]
	v_mfma_f32_16x16x32_bf16 v[112:115], v[222:225], v[206:209], v[112:115]
	v_mfma_f32_16x16x32_bf16 v[48:51], v[226:229], v[206:209], v[48:51]
	v_mfma_f32_16x16x32_bf16 v[44:47], v[230:233], v[206:209], v[44:47]
	v_add3_u32 v253, s24, v155, v141
	ds_read_b128 v[206:209], v253 offset:0x800
	v_mfma_f32_16x16x32_bf16 v[68:71], v[218:221], v[178:181], v[68:71]
	v_mfma_f32_16x16x32_bf16 v[64:67], v[222:225], v[178:181], v[64:67]
	v_mfma_f32_16x16x32_bf16 v[0:3], v[226:229], v[178:181], v[0:3]
	v_mfma_f32_16x16x32_bf16 v[52:55], v[230:233], v[178:181], v[52:55]
	v_add3_u32 v253, s24, v172, v141
	ds_read_b128 v[178:181], v253 offset:0x800
	v_mfma_f32_16x16x32_bf16 v[92:95], v[218:221], v[182:185], v[92:95]
	v_mfma_f32_16x16x32_bf16 v[88:91], v[222:225], v[182:185], v[88:91]
	v_mfma_f32_16x16x32_bf16 v[24:27], v[226:229], v[182:185], v[24:27]
	v_mfma_f32_16x16x32_bf16 v[20:23], v[230:233], v[182:185], v[20:23]
	ds_read_b128 v[182:185], v253 offset:0x1000
	v_mfma_f32_16x16x32_bf16 v[84:87], v[218:221], v[198:201], v[84:87]
	v_mfma_f32_16x16x32_bf16 v[80:83], v[222:225], v[198:201], v[80:83]
	v_mfma_f32_16x16x32_bf16 v[16:19], v[226:229], v[198:201], v[16:19]
	v_mfma_f32_16x16x32_bf16 v[12:15], v[230:233], v[198:201], v[12:15]
	ds_read_b128 v[198:201], v253 offset:0x1800
	v_add_u32_e32 v186, s24, v172
	v_add_u32_e32 v134, s24, v155
	v_add_u32_e32 v173, v134, v141
	v_add_u32_e32 v186, v186, v143
	s_waitcnt lgkmcnt(4)
	v_add_u32_e32 v134, v134, v143
	v_mfma_f32_16x16x32_bf16 v[124:127], v[174:177], v[202:205], v[124:127]
	s_waitcnt lgkmcnt(2)
	v_mfma_f32_16x16x32_bf16 v[120:123], v[178:181], v[202:205], v[120:123]
	s_waitcnt lgkmcnt(1)
	v_mfma_f32_16x16x32_bf16 v[60:63], v[182:185], v[202:205], v[60:63]
	s_waitcnt lgkmcnt(0)
	v_mfma_f32_16x16x32_bf16 v[56:59], v[198:201], v[202:205], v[56:59]
	ds_read_b128 v[202:205], v173 offset:0x2000
	v_mfma_f32_16x16x32_bf16 v[116:119], v[174:177], v[206:209], v[116:119]
	v_mfma_f32_16x16x32_bf16 v[112:115], v[178:181], v[206:209], v[112:115]
	v_mfma_f32_16x16x32_bf16 v[48:51], v[182:185], v[206:209], v[48:51]
	v_mfma_f32_16x16x32_bf16 v[44:47], v[198:201], v[206:209], v[44:47]
	ds_read_b128 v[206:209], v173 offset:0x2800
	s_waitcnt lgkmcnt(2)
	s_nop 0
	v_mfma_f32_16x16x32_bf16 v[108:111], v[174:177], v[210:213], v[108:111]
	v_mfma_f32_16x16x32_bf16 v[104:107], v[178:181], v[210:213], v[104:107]
	v_mfma_f32_16x16x32_bf16 v[40:43], v[182:185], v[210:213], v[40:43]
	v_mfma_f32_16x16x32_bf16 v[36:39], v[198:201], v[210:213], v[36:39]
	ds_read_b128 v[210:213], v173 offset:0x3000
	v_mfma_f32_16x16x32_bf16 v[100:103], v[174:177], v[214:217], v[100:103]
	v_mfma_f32_16x16x32_bf16 v[96:99], v[178:181], v[214:217], v[96:99]
	v_mfma_f32_16x16x32_bf16 v[32:35], v[182:185], v[214:217], v[32:35]
	v_mfma_f32_16x16x32_bf16 v[28:31], v[198:201], v[214:217], v[28:31]
	ds_read_b128 v[214:217], v173 offset:0x3800
	ds_read_b128 v[218:221], v186 offset:0
	ds_read_b128 v[222:225], v186 offset:0x800
	ds_read_b128 v[226:229], v186 offset:0x1000
	ds_read_b128 v[230:233], v186 offset:0x1800
	s_waitcnt lgkmcnt(6)
	s_nop 0
	v_mfma_f32_16x16x32_bf16 v[92:95], v[174:177], v[202:205], v[92:95]
	v_mfma_f32_16x16x32_bf16 v[88:91], v[178:181], v[202:205], v[88:91]
	v_mfma_f32_16x16x32_bf16 v[24:27], v[182:185], v[202:205], v[24:27]
	v_mfma_f32_16x16x32_bf16 v[20:23], v[198:201], v[202:205], v[20:23]
	ds_read_b128 v[202:205], v134 offset:0
	v_mfma_f32_16x16x32_bf16 v[84:87], v[174:177], v[206:209], v[84:87]
	v_mfma_f32_16x16x32_bf16 v[80:83], v[178:181], v[206:209], v[80:83]
	v_mfma_f32_16x16x32_bf16 v[16:19], v[182:185], v[206:209], v[16:19]
	v_mfma_f32_16x16x32_bf16 v[12:15], v[198:201], v[206:209], v[12:15]
	ds_read_b128 v[206:209], v134 offset:0x800
	s_waitcnt lgkmcnt(6)
	s_nop 0
	v_mfma_f32_16x16x32_bf16 v[76:79], v[174:177], v[210:213], v[76:79]
	v_mfma_f32_16x16x32_bf16 v[68:71], v[174:177], v[214:217], v[68:71]
	ds_read_b128 v[174:177], v134 offset:0x1000
	v_mfma_f32_16x16x32_bf16 v[72:75], v[178:181], v[210:213], v[72:75]
	v_mfma_f32_16x16x32_bf16 v[64:67], v[178:181], v[214:217], v[64:67]
	ds_read_b128 v[178:181], v134 offset:0x1800
	s_waitcnt lgkmcnt(2)
	v_mfma_f32_16x16x32_bf16 v[8:11], v[182:185], v[210:213], v[8:11]
	v_mfma_f32_16x16x32_bf16 v[0:3], v[182:185], v[214:217], v[0:3]
	ds_read_b128 v[182:185], v134 offset:0x2000
	v_mfma_f32_16x16x32_bf16 v[4:7], v[198:201], v[210:213], v[4:7]
	v_mfma_f32_16x16x32_bf16 v[52:55], v[198:201], v[214:217], v[52:55]
	ds_read_b128 v[198:201], v134 offset:0x2800
	s_waitcnt lgkmcnt(2)
	s_nop 0
	v_mfma_f32_16x16x32_bf16 v[108:111], v[218:221], v[174:177], v[108:111]
	v_mfma_f32_16x16x32_bf16 v[104:107], v[222:225], v[174:177], v[104:107]
	v_mfma_f32_16x16x32_bf16 v[40:43], v[226:229], v[174:177], v[40:43]
	v_mfma_f32_16x16x32_bf16 v[36:39], v[230:233], v[174:177], v[36:39]
	ds_read_b128 v[174:177], v134 offset:0x3000
	v_mfma_f32_16x16x32_bf16 v[100:103], v[218:221], v[178:181], v[100:103]
	v_mfma_f32_16x16x32_bf16 v[96:99], v[222:225], v[178:181], v[96:99]
	v_mfma_f32_16x16x32_bf16 v[32:35], v[226:229], v[178:181], v[32:35]
	v_mfma_f32_16x16x32_bf16 v[28:31], v[230:233], v[178:181], v[28:31]
	ds_read_b128 v[178:181], v134 offset:0x3800
	s_waitcnt lgkmcnt(2)
	v_mfma_f32_16x16x32_bf16 v[124:127], v[218:221], v[202:205], v[124:127]
	s_add_i32 s7, s7, 0x10000
	s_add_u32 s0, s0, 0x80
	s_addc_u32 s1, s1, 0
	s_waitcnt lgkmcnt(0)
	s_waitcnt vmcnt(0)
	s_waitcnt vmcnt(0) lgkmcnt(0)
	v_mfma_f32_16x16x32_bf16 v[120:123], v[222:225], v[202:205], v[120:123]
	s_barrier
	v_mfma_f32_16x16x32_bf16 v[60:63], v[226:229], v[202:205], v[60:63]
	v_mfma_f32_16x16x32_bf16 v[56:59], v[230:233], v[202:205], v[56:59]
	v_mfma_f32_16x16x32_bf16 v[116:119], v[218:221], v[206:209], v[116:119]
	v_mfma_f32_16x16x32_bf16 v[112:115], v[222:225], v[206:209], v[112:115]
	v_mfma_f32_16x16x32_bf16 v[48:51], v[226:229], v[206:209], v[48:51]
	v_mfma_f32_16x16x32_bf16 v[44:47], v[230:233], v[206:209], v[44:47]
	v_mfma_f32_16x16x32_bf16 v[92:95], v[218:221], v[182:185], v[92:95]
	v_mfma_f32_16x16x32_bf16 v[88:91], v[222:225], v[182:185], v[88:91]
	v_mfma_f32_16x16x32_bf16 v[24:27], v[226:229], v[182:185], v[24:27]
	v_mfma_f32_16x16x32_bf16 v[20:23], v[230:233], v[182:185], v[20:23]
	v_mfma_f32_16x16x32_bf16 v[84:87], v[218:221], v[198:201], v[84:87]
	v_mfma_f32_16x16x32_bf16 v[80:83], v[222:225], v[198:201], v[80:83]
	v_mfma_f32_16x16x32_bf16 v[16:19], v[226:229], v[198:201], v[16:19]
	v_mfma_f32_16x16x32_bf16 v[12:15], v[230:233], v[198:201], v[12:15]
	v_mfma_f32_16x16x32_bf16 v[76:79], v[218:221], v[174:177], v[76:79]
	v_mfma_f32_16x16x32_bf16 v[72:75], v[222:225], v[174:177], v[72:75]
	v_mfma_f32_16x16x32_bf16 v[8:11], v[226:229], v[174:177], v[8:11]
	v_mfma_f32_16x16x32_bf16 v[4:7], v[230:233], v[174:177], v[4:7]
	v_mfma_f32_16x16x32_bf16 v[68:71], v[218:221], v[178:181], v[68:71]
	v_mfma_f32_16x16x32_bf16 v[64:67], v[222:225], v[178:181], v[64:67]
	v_mfma_f32_16x16x32_bf16 v[0:3], v[226:229], v[178:181], v[0:3]
	v_mfma_f32_16x16x32_bf16 v[52:55], v[230:233], v[178:181], v[52:55]

.LBB0_1155:
	s_or_b64 exec, exec, s[8:9]
	v_cvt_f32_u32_e32 v4, v2
	s_waitcnt vmcnt(0)
	v_readfirstlane_b32 s6, v3
	v_sub_u32_e32 v3, 0, v2
	v_rcp_iflag_f32_e32 v4, v4
	v_add_u32_e32 v5, s6, v1
	v_mul_f32_e32 v4, 0x4f7ffffe, v4
	v_cvt_u32_f32_e32 v4, v4
	v_mul_lo_u32 v1, v3, v4
	v_mul_hi_u32 v1, v4, v1
	v_add_u32_e32 v1, v4, v1
	v_mul_hi_u32 v1, v5, v1
	v_mul_lo_u32 v3, v1, v2
	v_sub_u32_e32 v3, v5, v3
	v_add_u32_e32 v4, 1, v1
	v_cmp_ge_u32_e32 vcc, v3, v2
	s_nop 1
	v_cndmask_b32_e32 v1, v1, v4, vcc
	v_sub_u32_e32 v4, v3, v2
	v_cndmask_b32_e32 v3, v3, v4, vcc
	v_add_u32_e32 v4, 1, v1
	v_cmp_ge_u32_e32 vcc, v3, v2
	v_add_u32_e32 v3, 1, v5
	s_nop 0
	v_cndmask_b32_e32 v1, v1, v4, vcc
	v_mul_lo_u32 v4, v2, v1
	v_add_u32_e32 v2, v4, v2
	v_cmp_ne_u32_e32 vcc, v3, v2
	s_and_saveexec_b64 s[6:7], vcc
	s_xor_b64 s[6:7], exec, s[6:7]
	s_cbranch_execz .LBB0_1169
	s_waitcnt lgkmcnt(0)
	buffer_inv sc1
	v_mov_b32_e32 v0, 0
	v_mov_b32_e32 v1, 7
	s_add_u32 s12, s86, 0xe7b4500
	s_addc_u32 s13, s87, 0
	global_load_dword v0, v0, s[12:13] sc1
	s_waitcnt vmcnt(0)
	v_cmp_eq_u32_e32 vcc, v0, v1
	s_and_saveexec_b64 s[8:9], vcc
	s_cbranch_execz .LBB0_1168
	s_add_u32 s10, s86, 0xe7b1200
	s_addc_u32 s11, s87, 0
	s_mov_b32 s30, 1
	s_mov_b64 s[14:15], 0
	v_mov_b32_e32 v0, 0
	s_branch .LBB0_1159

.LBB0_1191:
	s_ashr_i32 s6, s17, 31
	s_lshr_b32 s6, s6, 26
	s_add_i32 s6, s17, s6
	s_ashr_i32 s12, s6, 6
	s_andn2_b32 s6, s6, 63
	s_sub_i32 s10, s17, s6
	s_mul_i32 s6, s10, 0xb0000
	v_readfirstlane_b32 s11, v128
	s_lshl_b32 s13, s6, 1
	v_or_b32_e32 v3, s6, v134
	s_lshr_b32 s6, s11, 1
	s_and_b32 s6, s6, 0x1ffff80
	v_lshl_add_u32 v4, v3, 1, v144
	v_or_b32_e32 v3, s6, v189
	s_and_b32 s6, s11, 0xc0
	v_lshlrev_b32_e32 v141, 7, v3
	v_or_b32_e32 v3, s6, v189
	s_lshl_b32 s6, s11, 4
	v_add_u32_e32 v0, s13, v138
	s_and_b32 s11, s6, 0x7ffffc00
	v_add_u32_e32 v1, s13, v140
	v_and_b32_e32 v136, 0xfffffe70, v0
	s_mov_b32 m0, s11
	v_add_u32_e32 v2, s13, v142
	global_load_lds_dwordx4 v136, s[86:87]
	v_and_b32_e32 v0, 0xfffffe70, v1
	s_add_i32 m0, s11, 0x2000
	s_mul_i32 s7, s12, 0x160000
	global_load_lds_dwordx4 v0, s[86:87]
	v_and_b32_e32 v2, 0xfffffe70, v2
	s_add_i32 m0, s11, 0x4000
	v_add_u32_e32 v6, s7, v146
	s_add_i32 s6, s11, 0x8000
	global_load_lds_dwordx4 v2, s[86:87]
	v_and_b32_e32 v4, 0xfffffe70, v4
	s_add_i32 m0, s11, 0x6000
	v_add_u32_e32 v8, s7, v148
	global_load_lds_dwordx4 v4, s[86:87]
	v_and_b32_e32 v6, 0xfffffe70, v6
	s_mov_b32 m0, s6
	v_add_u32_e32 v10, s7, v150
	global_load_lds_dwordx4 v6, s[86:87]
	v_and_b32_e32 v8, 0xfffffe70, v8
	s_add_i32 m0, s11, 0xa000
	s_waitcnt vmcnt(0)
	v_add_u32_e32 v12, s7, v152
	global_load_lds_dwordx4 v8, s[86:87]
	v_and_b32_e32 v10, 0xfffffe70, v10
	s_add_i32 m0, s11, 0xc000
	v_and_b32_e32 v12, 0xfffffe70, v12
	global_load_lds_dwordx4 v10, s[86:87]
	s_add_i32 m0, s11, 0xe000
	v_lshl_or_b32 v143, v3, 7, v139
	global_load_lds_dwordx4 v12, s[86:87]
	s_waitcnt vmcnt(0)
	v_mov_b32_e32 v1, v137
	v_mov_b32_e32 v3, v137
	v_mov_b32_e32 v5, v137
	v_mov_b32_e32 v7, v137
	v_mov_b32_e32 v9, v137
	v_mov_b32_e32 v11, v137
	v_mov_b32_e32 v13, v137
	v_lshl_add_u64 v[154:155], s[8:9], 0, v[136:137]
	v_lshl_add_u64 v[156:157], s[8:9], 0, v[0:1]
	v_lshl_add_u64 v[158:159], s[8:9], 0, v[2:3]
	v_lshl_add_u64 v[160:161], s[8:9], 0, v[4:5]
	v_lshl_add_u64 v[162:163], s[8:9], 0, v[6:7]
	v_lshl_add_u64 v[164:165], s[8:9], 0, v[8:9]
	v_lshl_add_u64 v[166:167], s[8:9], 0, v[10:11]
	v_lshl_add_u64 v[168:169], s[8:9], 0, v[12:13]
	s_mov_b64 s[6:7], 0
	s_mov_b32 s13, 0
	s_mov_b32 s20, 0
	v_mov_b32_e32 v56, 0
	v_mov_b32_e32 v57, v137
	v_mov_b32_e32 v58, v137
	v_mov_b32_e32 v59, v137
	v_mov_b32_e32 v52, 0
	v_mov_b32_e32 v53, v137
	v_mov_b32_e32 v54, v137
	v_mov_b32_e32 v55, v137
	v_mov_b32_e32 v64, 0
	v_mov_b32_e32 v65, v137
	v_mov_b32_e32 v66, v137
	v_mov_b32_e32 v67, v137
	v_mov_b32_e32 v68, 0
	v_mov_b32_e32 v69, v137
	v_mov_b32_e32 v70, v137
	v_mov_b32_e32 v71, v137
	v_mov_b32_e32 v0, 0
	v_mov_b32_e32 v2, v137
	v_mov_b32_e32 v4, 0
	v_mov_b32_e32 v6, v137
	v_mov_b32_e32 v72, 0
	v_mov_b32_e32 v73, v137
	v_mov_b32_e32 v74, v137
	v_mov_b32_e32 v75, v137
	v_mov_b32_e32 v76, 0
	v_mov_b32_e32 v77, v137
	v_mov_b32_e32 v78, v137
	v_mov_b32_e32 v79, v137
	v_mov_b32_e32 v8, 0
	v_mov_b32_e32 v10, v137
	v_mov_b32_e32 v12, 0
	v_mov_b32_e32 v14, v137
	v_mov_b32_e32 v15, v137
	v_mov_b32_e32 v80, 0
	v_mov_b32_e32 v81, v137
	v_mov_b32_e32 v82, v137
	v_mov_b32_e32 v83, v137
	v_mov_b32_e32 v84, 0
	v_mov_b32_e32 v85, v137
	v_mov_b32_e32 v86, v137
	v_mov_b32_e32 v87, v137
	v_mov_b32_e32 v16, 0
	v_mov_b32_e32 v17, v137
	v_mov_b32_e32 v18, v137
	v_mov_b32_e32 v19, v137
	v_mov_b32_e32 v20, 0
	v_mov_b32_e32 v21, v137
	v_mov_b32_e32 v22, v137
	v_mov_b32_e32 v23, v137
	v_mov_b32_e32 v88, 0
	v_mov_b32_e32 v89, v137
	v_mov_b32_e32 v90, v137
	v_mov_b32_e32 v91, v137
	v_mov_b32_e32 v92, 0
	v_mov_b32_e32 v93, v137
	v_mov_b32_e32 v94, v137
	v_mov_b32_e32 v95, v137
	v_mov_b32_e32 v24, 0
	v_mov_b32_e32 v25, v137
	v_mov_b32_e32 v26, v137
	v_mov_b32_e32 v27, v137
	v_mov_b32_e32 v28, 0
	v_mov_b32_e32 v29, v137
	v_mov_b32_e32 v30, v137
	v_mov_b32_e32 v31, v137
	v_mov_b32_e32 v96, 0
	v_mov_b32_e32 v97, v137
	v_mov_b32_e32 v98, v137
	v_mov_b32_e32 v99, v137
	v_mov_b32_e32 v100, 0
	v_mov_b32_e32 v101, v137
	v_mov_b32_e32 v102, v137
	v_mov_b32_e32 v103, v137
	v_mov_b32_e32 v32, 0
	v_mov_b32_e32 v33, v137
	v_mov_b32_e32 v34, v137
	v_mov_b32_e32 v35, v137
	v_mov_b32_e32 v36, 0
	v_mov_b32_e32 v37, v137
	v_mov_b32_e32 v38, v137
	v_mov_b32_e32 v39, v137
	v_mov_b32_e32 v104, 0
	v_mov_b32_e32 v105, v137
	v_mov_b32_e32 v106, v137
	v_mov_b32_e32 v107, v137
	v_mov_b32_e32 v108, 0
	v_mov_b32_e32 v109, v137
	v_mov_b32_e32 v110, v137
	v_mov_b32_e32 v111, v137
	v_mov_b32_e32 v40, 0
	v_mov_b32_e32 v41, v137
	v_mov_b32_e32 v42, v137
	v_mov_b32_e32 v43, v137
	v_mov_b32_e32 v44, 0
	v_mov_b32_e32 v45, v137
	v_mov_b32_e32 v46, v137
	v_mov_b32_e32 v47, v137
	v_mov_b32_e32 v112, 0
	v_mov_b32_e32 v113, v137
	v_mov_b32_e32 v114, v137
	v_mov_b32_e32 v115, v137
	v_mov_b32_e32 v116, 0
	v_mov_b32_e32 v117, v137
	v_mov_b32_e32 v118, v137
	v_mov_b32_e32 v119, v137
	v_mov_b32_e32 v48, 0
	v_mov_b32_e32 v49, v137
	v_mov_b32_e32 v50, v137
	v_mov_b32_e32 v51, v137
	v_mov_b32_e32 v60, 0
	v_mov_b32_e32 v61, v137
	v_mov_b32_e32 v62, v137
	v_mov_b32_e32 v63, v137
	v_mov_b32_e32 v120, 0
	v_mov_b32_e32 v121, v137
	v_mov_b32_e32 v122, v137
	v_mov_b32_e32 v123, v137
	v_mov_b32_e32 v124, 0
	v_mov_b32_e32 v125, v137
	v_mov_b32_e32 v126, v137
	v_mov_b32_e32 v127, v137
	s_waitcnt vmcnt(0) lgkmcnt(0)
	s_barrier
	s_and_b32 s21, s13, 0x10000
	s_xor_b32 s24, s21, 0x10000
	s_add_i32 s24, s11, s24
	s_add_i32 s25, s24, 0x8000
	s_mov_b32 m0, s24
	v_lshl_add_u64 v[254:255], v[154:155], 0, s[6:7]
	global_load_lds_dwordx4 v[254:255], off
	s_add_i32 m0, s24, 0x2000
	v_lshl_add_u64 v[254:255], v[156:157], 0, s[6:7]
	global_load_lds_dwordx4 v[254:255], off
	s_add_i32 m0, s24, 0x4000
	v_lshl_add_u64 v[254:255], v[158:159], 0, s[6:7]
	global_load_lds_dwordx4 v[254:255], off
	s_add_i32 m0, s24, 0x6000
	v_lshl_add_u64 v[254:255], v[160:161], 0, s[6:7]
	global_load_lds_dwordx4 v[254:255], off
	s_mov_b32 m0, s25
	v_lshl_add_u64 v[254:255], v[162:163], 0, s[6:7]
	global_load_lds_dwordx4 v[254:255], off
	s_add_i32 m0, s24, 0xa000
	v_lshl_add_u64 v[254:255], v[164:165], 0, s[6:7]
	global_load_lds_dwordx4 v[254:255], off
	s_add_i32 m0, s24, 0xc000
	v_lshl_add_u64 v[254:255], v[166:167], 0, s[6:7]
	global_load_lds_dwordx4 v[254:255], off
	s_add_i32 m0, s24, 0xe000
	v_lshl_add_u64 v[254:255], v[168:169], 0, s[6:7]
	global_load_lds_dwordx4 v[254:255], off
	v_add3_u32 v253, s21, v141, v129
	ds_read_b128 v[206:209], v253 offset:0x1000
	ds_read_b128 v[210:213], v253 offset:0x1800
	ds_read_b128 v[198:201], v253 offset:0
	v_add3_u32 v253, s21, v143, v129
	ds_read_b128 v[170:173], v253 offset:0
	v_add3_u32 v253, s21, v141, v129
	ds_read_b128 v[202:205], v253 offset:0x800
	v_add3_u32 v253, s21, v143, v129
	ds_read_b128 v[174:177], v253 offset:0x800
	ds_read_b128 v[178:181], v253 offset:0x1000
	ds_read_b128 v[182:185], v253 offset:0x1800
.Lgdwn0_body:
	v_add_u32_e32 v147, s21, v143
	v_add_u32_e32 v136, s21, v141
	v_add_u32_e32 v145, v136, v129
	v_add_u32_e32 v147, v147, v135
	s_waitcnt lgkmcnt(4)
	v_add_u32_e32 v136, v136, v135
	v_mfma_f32_16x16x32_bf16 v[124:127], v[170:173], v[198:201], v[124:127]
	s_waitcnt lgkmcnt(2)
	v_mfma_f32_16x16x32_bf16 v[120:123], v[174:177], v[198:201], v[120:123]
	s_waitcnt lgkmcnt(1)
	v_mfma_f32_16x16x32_bf16 v[60:63], v[178:181], v[198:201], v[60:63]
	s_waitcnt lgkmcnt(0)
	v_mfma_f32_16x16x32_bf16 v[48:51], v[182:185], v[198:201], v[48:51]
	ds_read_b128 v[198:201], v145 offset:0x2000
	v_mfma_f32_16x16x32_bf16 v[116:119], v[170:173], v[202:205], v[116:119]
	v_mfma_f32_16x16x32_bf16 v[112:115], v[174:177], v[202:205], v[112:115]
	v_mfma_f32_16x16x32_bf16 v[44:47], v[178:181], v[202:205], v[44:47]
	v_mfma_f32_16x16x32_bf16 v[40:43], v[182:185], v[202:205], v[40:43]
	ds_read_b128 v[202:205], v145 offset:0x2800
	s_waitcnt lgkmcnt(2)
	s_nop 0
	v_mfma_f32_16x16x32_bf16 v[108:111], v[170:173], v[206:209], v[108:111]
	v_mfma_f32_16x16x32_bf16 v[104:107], v[174:177], v[206:209], v[104:107]
	v_mfma_f32_16x16x32_bf16 v[36:39], v[178:181], v[206:209], v[36:39]
	v_mfma_f32_16x16x32_bf16 v[32:35], v[182:185], v[206:209], v[32:35]
	ds_read_b128 v[206:209], v145 offset:0x3000
	v_mfma_f32_16x16x32_bf16 v[100:103], v[170:173], v[210:213], v[100:103]
	v_mfma_f32_16x16x32_bf16 v[96:99], v[174:177], v[210:213], v[96:99]
	v_mfma_f32_16x16x32_bf16 v[28:31], v[178:181], v[210:213], v[28:31]
	v_mfma_f32_16x16x32_bf16 v[24:27], v[182:185], v[210:213], v[24:27]
	ds_read_b128 v[210:213], v145 offset:0x3800
	ds_read_b128 v[214:217], v147 offset:0
	ds_read_b128 v[218:221], v147 offset:0x800
	ds_read_b128 v[222:225], v147 offset:0x1000
	ds_read_b128 v[226:229], v147 offset:0x1800
	s_waitcnt lgkmcnt(6)
	s_nop 0
	v_mfma_f32_16x16x32_bf16 v[92:95], v[170:173], v[198:201], v[92:95]
	v_mfma_f32_16x16x32_bf16 v[88:91], v[174:177], v[198:201], v[88:91]
	v_mfma_f32_16x16x32_bf16 v[20:23], v[178:181], v[198:201], v[20:23]
	v_mfma_f32_16x16x32_bf16 v[16:19], v[182:185], v[198:201], v[16:19]
	ds_read_b128 v[198:201], v136 offset:0
	v_mfma_f32_16x16x32_bf16 v[84:87], v[170:173], v[202:205], v[84:87]
	v_mfma_f32_16x16x32_bf16 v[80:83], v[174:177], v[202:205], v[80:83]
	v_mfma_f32_16x16x32_bf16 v[12:15], v[178:181], v[202:205], v[12:15]
	v_mfma_f32_16x16x32_bf16 v[8:11], v[182:185], v[202:205], v[8:11]
	ds_read_b128 v[202:205], v136 offset:0x800
	s_waitcnt lgkmcnt(6)
	s_nop 0
	v_mfma_f32_16x16x32_bf16 v[76:79], v[170:173], v[206:209], v[76:79]
	v_mfma_f32_16x16x32_bf16 v[68:71], v[170:173], v[210:213], v[68:71]
	ds_read_b128 v[170:173], v136 offset:0x1000
	v_mfma_f32_16x16x32_bf16 v[72:75], v[174:177], v[206:209], v[72:75]
	v_mfma_f32_16x16x32_bf16 v[64:67], v[174:177], v[210:213], v[64:67]
	ds_read_b128 v[174:177], v136 offset:0x1800
	s_waitcnt lgkmcnt(2)
	v_mfma_f32_16x16x32_bf16 v[4:7], v[178:181], v[206:209], v[4:7]
	v_mfma_f32_16x16x32_bf16 v[52:55], v[178:181], v[210:213], v[52:55]
	ds_read_b128 v[178:181], v136 offset:0x2000
	v_mfma_f32_16x16x32_bf16 v[0:3], v[182:185], v[206:209], v[0:3]
	v_mfma_f32_16x16x32_bf16 v[56:59], v[182:185], v[210:213], v[56:59]
	ds_read_b128 v[182:185], v136 offset:0x2800
	s_waitcnt lgkmcnt(2)
	s_nop 0
	v_mfma_f32_16x16x32_bf16 v[108:111], v[214:217], v[170:173], v[108:111]
	v_mfma_f32_16x16x32_bf16 v[104:107], v[218:221], v[170:173], v[104:107]
	v_mfma_f32_16x16x32_bf16 v[36:39], v[222:225], v[170:173], v[36:39]
	v_mfma_f32_16x16x32_bf16 v[32:35], v[226:229], v[170:173], v[32:35]
	ds_read_b128 v[170:173], v136 offset:0x3000
	v_mfma_f32_16x16x32_bf16 v[100:103], v[214:217], v[174:177], v[100:103]
	v_mfma_f32_16x16x32_bf16 v[96:99], v[218:221], v[174:177], v[96:99]
	v_mfma_f32_16x16x32_bf16 v[28:31], v[222:225], v[174:177], v[28:31]
	v_mfma_f32_16x16x32_bf16 v[24:27], v[226:229], v[174:177], v[24:27]
	ds_read_b128 v[174:177], v136 offset:0x3800
	s_waitcnt lgkmcnt(2)
	v_mfma_f32_16x16x32_bf16 v[124:127], v[214:217], v[198:201], v[124:127]
	s_add_i32 s13, s13, 0x10000
	s_add_u32 s6, s6, 0x80
	s_addc_u32 s7, s7, 0
	s_add_i32 s20, s20, 1
	s_waitcnt lgkmcnt(0)
	s_waitcnt vmcnt(0)
	s_waitcnt vmcnt(0) lgkmcnt(0)
	v_mfma_f32_16x16x32_bf16 v[120:123], v[218:221], v[198:201], v[120:123]
	s_barrier
	s_cmp_gt_u32 s20, 42
	s_cbranch_scc1 .Lgdwn0_nodma
	s_and_b32 s21, s13, 0x10000
	s_xor_b32 s24, s21, 0x10000
	s_add_i32 s24, s11, s24
	s_add_i32 s25, s24, 0x8000
	v_add3_u32 v253, s21, v141, v129
	ds_read_b128 v[206:209], v253 offset:0x1000
	ds_read_b128 v[210:213], v253 offset:0x1800
	v_mfma_f32_16x16x32_bf16 v[60:63], v[222:225], v[198:201], v[60:63]
	s_mov_b32 m0, s24
	v_lshl_add_u64 v[254:255], v[154:155], 0, s[6:7]
	global_load_lds_dwordx4 v[254:255], off
	v_mfma_f32_16x16x32_bf16 v[48:51], v[226:229], v[198:201], v[48:51]
	ds_read_b128 v[198:201], v253 offset:0
	v_mfma_f32_16x16x32_bf16 v[76:79], v[214:217], v[170:173], v[76:79]
	s_add_i32 m0, s24, 0x2000
	v_lshl_add_u64 v[254:255], v[156:157], 0, s[6:7]
	global_load_lds_dwordx4 v[254:255], off
	v_mfma_f32_16x16x32_bf16 v[72:75], v[218:221], v[170:173], v[72:75]
	v_mfma_f32_16x16x32_bf16 v[4:7], v[222:225], v[170:173], v[4:7]
	s_add_i32 m0, s24, 0x4000
	v_lshl_add_u64 v[254:255], v[158:159], 0, s[6:7]
	global_load_lds_dwordx4 v[254:255], off
	v_mfma_f32_16x16x32_bf16 v[0:3], v[226:229], v[170:173], v[0:3]
	v_add3_u32 v253, s21, v143, v129
	ds_read_b128 v[170:173], v253 offset:0
	v_mfma_f32_16x16x32_bf16 v[116:119], v[214:217], v[202:205], v[116:119]
	s_add_i32 m0, s24, 0x6000
	v_lshl_add_u64 v[254:255], v[160:161], 0, s[6:7]
	global_load_lds_dwordx4 v[254:255], off
	v_mfma_f32_16x16x32_bf16 v[112:115], v[218:221], v[202:205], v[112:115]
	v_mfma_f32_16x16x32_bf16 v[44:47], v[222:225], v[202:205], v[44:47]
	s_mov_b32 m0, s25
	v_lshl_add_u64 v[254:255], v[162:163], 0, s[6:7]
	global_load_lds_dwordx4 v[254:255], off
	v_mfma_f32_16x16x32_bf16 v[40:43], v[226:229], v[202:205], v[40:43]
	v_add3_u32 v253, s21, v141, v129
	ds_read_b128 v[202:205], v253 offset:0x800
	v_mfma_f32_16x16x32_bf16 v[68:71], v[214:217], v[174:177], v[68:71]
	s_add_i32 m0, s24, 0xa000
	v_lshl_add_u64 v[254:255], v[164:165], 0, s[6:7]
	global_load_lds_dwordx4 v[254:255], off
	v_mfma_f32_16x16x32_bf16 v[64:67], v[218:221], v[174:177], v[64:67]
	v_mfma_f32_16x16x32_bf16 v[52:55], v[222:225], v[174:177], v[52:55]
	s_add_i32 m0, s24, 0xc000
	v_lshl_add_u64 v[254:255], v[166:167], 0, s[6:7]
	global_load_lds_dwordx4 v[254:255], off
	v_mfma_f32_16x16x32_bf16 v[56:59], v[226:229], v[174:177], v[56:59]
	v_add3_u32 v253, s21, v143, v129
	ds_read_b128 v[174:177], v253 offset:0x800
	v_mfma_f32_16x16x32_bf16 v[92:95], v[214:217], v[178:181], v[92:95]
	s_add_i32 m0, s24, 0xe000
	v_lshl_add_u64 v[254:255], v[168:169], 0, s[6:7]
	global_load_lds_dwordx4 v[254:255], off
	v_mfma_f32_16x16x32_bf16 v[88:91], v[218:221], v[178:181], v[88:91]
	v_mfma_f32_16x16x32_bf16 v[20:23], v[222:225], v[178:181], v[20:23]
	v_mfma_f32_16x16x32_bf16 v[16:19], v[226:229], v[178:181], v[16:19]
	ds_read_b128 v[178:181], v253 offset:0x1000
	v_mfma_f32_16x16x32_bf16 v[84:87], v[214:217], v[182:185], v[84:87]
	v_mfma_f32_16x16x32_bf16 v[80:83], v[218:221], v[182:185], v[80:83]
	v_mfma_f32_16x16x32_bf16 v[12:15], v[222:225], v[182:185], v[12:15]
	v_mfma_f32_16x16x32_bf16 v[8:11], v[226:229], v[182:185], v[8:11]
	ds_read_b128 v[182:185], v253 offset:0x1800
	s_branch .Lgdwn0_body
.Lgdwn0_nodma:
	s_and_b32 s21, s13, 0x10000
	v_add3_u32 v253, s21, v141, v129
	ds_read_b128 v[206:209], v253 offset:0x1000
	ds_read_b128 v[210:213], v253 offset:0x1800
	v_mfma_f32_16x16x32_bf16 v[60:63], v[222:225], v[198:201], v[60:63]
	v_mfma_f32_16x16x32_bf16 v[48:51], v[226:229], v[198:201], v[48:51]
	ds_read_b128 v[198:201], v253 offset:0
	v_mfma_f32_16x16x32_bf16 v[76:79], v[214:217], v[170:173], v[76:79]
	v_mfma_f32_16x16x32_bf16 v[72:75], v[218:221], v[170:173], v[72:75]
	v_mfma_f32_16x16x32_bf16 v[4:7], v[222:225], v[170:173], v[4:7]
	v_mfma_f32_16x16x32_bf16 v[0:3], v[226:229], v[170:173], v[0:3]
	v_add3_u32 v253, s21, v143, v129
	ds_read_b128 v[170:173], v253 offset:0
	v_mfma_f32_16x16x32_bf16 v[116:119], v[214:217], v[202:205], v[116:119]
	v_mfma_f32_16x16x32_bf16 v[112:115], v[218:221], v[202:205], v[112:115]
	v_mfma_f32_16x16x32_bf16 v[44:47], v[222:225], v[202:205], v[44:47]
	v_mfma_f32_16x16x32_bf16 v[40:43], v[226:229], v[202:205], v[40:43]
	v_add3_u32 v253, s21, v141, v129
	ds_read_b128 v[202:205], v253 offset:0x800
	v_mfma_f32_16x16x32_bf16 v[68:71], v[214:217], v[174:177], v[68:71]
	v_mfma_f32_16x16x32_bf16 v[64:67], v[218:221], v[174:177], v[64:67]
	v_mfma_f32_16x16x32_bf16 v[52:55], v[222:225], v[174:177], v[52:55]
	v_mfma_f32_16x16x32_bf16 v[56:59], v[226:229], v[174:177], v[56:59]
	v_add3_u32 v253, s21, v143, v129
	ds_read_b128 v[174:177], v253 offset:0x800
	v_mfma_f32_16x16x32_bf16 v[92:95], v[214:217], v[178:181], v[92:95]
	v_mfma_f32_16x16x32_bf16 v[88:91], v[218:221], v[178:181], v[88:91]
	v_mfma_f32_16x16x32_bf16 v[20:23], v[222:225], v[178:181], v[20:23]
	v_mfma_f32_16x16x32_bf16 v[16:19], v[226:229], v[178:181], v[16:19]
	ds_read_b128 v[178:181], v253 offset:0x1000
	v_mfma_f32_16x16x32_bf16 v[84:87], v[214:217], v[182:185], v[84:87]
	v_mfma_f32_16x16x32_bf16 v[80:83], v[218:221], v[182:185], v[80:83]
	v_mfma_f32_16x16x32_bf16 v[12:15], v[222:225], v[182:185], v[12:15]
	v_mfma_f32_16x16x32_bf16 v[8:11], v[226:229], v[182:185], v[8:11]
	ds_read_b128 v[182:185], v253 offset:0x1800
	v_add_u32_e32 v147, s21, v143
	v_add_u32_e32 v136, s21, v141
	v_add_u32_e32 v145, v136, v129
	v_add_u32_e32 v147, v147, v135
	s_waitcnt lgkmcnt(4)
	v_add_u32_e32 v136, v136, v135
	v_mfma_f32_16x16x32_bf16 v[124:127], v[170:173], v[198:201], v[124:127]
	s_waitcnt lgkmcnt(2)
	v_mfma_f32_16x16x32_bf16 v[120:123], v[174:177], v[198:201], v[120:123]
	s_waitcnt lgkmcnt(1)
	v_mfma_f32_16x16x32_bf16 v[60:63], v[178:181], v[198:201], v[60:63]
	s_waitcnt lgkmcnt(0)
	v_mfma_f32_16x16x32_bf16 v[48:51], v[182:185], v[198:201], v[48:51]
	ds_read_b128 v[198:201], v145 offset:0x2000
	v_mfma_f32_16x16x32_bf16 v[116:119], v[170:173], v[202:205], v[116:119]
	v_mfma_f32_16x16x32_bf16 v[112:115], v[174:177], v[202:205], v[112:115]
	v_mfma_f32_16x16x32_bf16 v[44:47], v[178:181], v[202:205], v[44:47]
	v_mfma_f32_16x16x32_bf16 v[40:43], v[182:185], v[202:205], v[40:43]
	ds_read_b128 v[202:205], v145 offset:0x2800
	s_waitcnt lgkmcnt(2)
	s_nop 0
	v_mfma_f32_16x16x32_bf16 v[108:111], v[170:173], v[206:209], v[108:111]
	v_mfma_f32_16x16x32_bf16 v[104:107], v[174:177], v[206:209], v[104:107]
	v_mfma_f32_16x16x32_bf16 v[36:39], v[178:181], v[206:209], v[36:39]
	v_mfma_f32_16x16x32_bf16 v[32:35], v[182:185], v[206:209], v[32:35]
	ds_read_b128 v[206:209], v145 offset:0x3000
	v_mfma_f32_16x16x32_bf16 v[100:103], v[170:173], v[210:213], v[100:103]
	v_mfma_f32_16x16x32_bf16 v[96:99], v[174:177], v[210:213], v[96:99]
	v_mfma_f32_16x16x32_bf16 v[28:31], v[178:181], v[210:213], v[28:31]
	v_mfma_f32_16x16x32_bf16 v[24:27], v[182:185], v[210:213], v[24:27]
	ds_read_b128 v[210:213], v145 offset:0x3800
	ds_read_b128 v[214:217], v147 offset:0
	ds_read_b128 v[218:221], v147 offset:0x800
	ds_read_b128 v[222:225], v147 offset:0x1000
	ds_read_b128 v[226:229], v147 offset:0x1800
	s_waitcnt lgkmcnt(6)
	s_nop 0
	v_mfma_f32_16x16x32_bf16 v[92:95], v[170:173], v[198:201], v[92:95]
	v_mfma_f32_16x16x32_bf16 v[88:91], v[174:177], v[198:201], v[88:91]
	v_mfma_f32_16x16x32_bf16 v[20:23], v[178:181], v[198:201], v[20:23]
	v_mfma_f32_16x16x32_bf16 v[16:19], v[182:185], v[198:201], v[16:19]
	ds_read_b128 v[198:201], v136 offset:0
	v_mfma_f32_16x16x32_bf16 v[84:87], v[170:173], v[202:205], v[84:87]
	v_mfma_f32_16x16x32_bf16 v[80:83], v[174:177], v[202:205], v[80:83]
	v_mfma_f32_16x16x32_bf16 v[12:15], v[178:181], v[202:205], v[12:15]
	v_mfma_f32_16x16x32_bf16 v[8:11], v[182:185], v[202:205], v[8:11]
	ds_read_b128 v[202:205], v136 offset:0x800
	s_waitcnt lgkmcnt(6)
	s_nop 0
	v_mfma_f32_16x16x32_bf16 v[76:79], v[170:173], v[206:209], v[76:79]
	v_mfma_f32_16x16x32_bf16 v[68:71], v[170:173], v[210:213], v[68:71]
	ds_read_b128 v[170:173], v136 offset:0x1000
	v_mfma_f32_16x16x32_bf16 v[72:75], v[174:177], v[206:209], v[72:75]
	v_mfma_f32_16x16x32_bf16 v[64:67], v[174:177], v[210:213], v[64:67]
	ds_read_b128 v[174:177], v136 offset:0x1800
	s_waitcnt lgkmcnt(2)
	v_mfma_f32_16x16x32_bf16 v[4:7], v[178:181], v[206:209], v[4:7]
	v_mfma_f32_16x16x32_bf16 v[52:55], v[178:181], v[210:213], v[52:55]
	ds_read_b128 v[178:181], v136 offset:0x2000
	v_mfma_f32_16x16x32_bf16 v[0:3], v[182:185], v[206:209], v[0:3]
	v_mfma_f32_16x16x32_bf16 v[56:59], v[182:185], v[210:213], v[56:59]
	ds_read_b128 v[182:185], v136 offset:0x2800
	s_waitcnt lgkmcnt(2)
	s_nop 0
	v_mfma_f32_16x16x32_bf16 v[108:111], v[214:217], v[170:173], v[108:111]
	v_mfma_f32_16x16x32_bf16 v[104:107], v[218:221], v[170:173], v[104:107]
	v_mfma_f32_16x16x32_bf16 v[36:39], v[222:225], v[170:173], v[36:39]
	v_mfma_f32_16x16x32_bf16 v[32:35], v[226:229], v[170:173], v[32:35]
	ds_read_b128 v[170:173], v136 offset:0x3000
	v_mfma_f32_16x16x32_bf16 v[100:103], v[214:217], v[174:177], v[100:103]
	v_mfma_f32_16x16x32_bf16 v[96:99], v[218:221], v[174:177], v[96:99]
	v_mfma_f32_16x16x32_bf16 v[28:31], v[222:225], v[174:177], v[28:31]
	v_mfma_f32_16x16x32_bf16 v[24:27], v[226:229], v[174:177], v[24:27]
	ds_read_b128 v[174:177], v136 offset:0x3800
	s_waitcnt lgkmcnt(2)
	v_mfma_f32_16x16x32_bf16 v[124:127], v[214:217], v[198:201], v[124:127]
	s_add_i32 s13, s13, 0x10000
	s_add_u32 s6, s6, 0x80
	s_addc_u32 s7, s7, 0
	s_add_i32 s20, s20, 1
	s_waitcnt lgkmcnt(0)
	s_waitcnt vmcnt(0)
	s_waitcnt vmcnt(0) lgkmcnt(0)
	v_mfma_f32_16x16x32_bf16 v[120:123], v[218:221], v[198:201], v[120:123]
	s_barrier
	v_mfma_f32_16x16x32_bf16 v[60:63], v[222:225], v[198:201], v[60:63]
	v_mfma_f32_16x16x32_bf16 v[48:51], v[226:229], v[198:201], v[48:51]
	v_mfma_f32_16x16x32_bf16 v[116:119], v[214:217], v[202:205], v[116:119]
	v_mfma_f32_16x16x32_bf16 v[112:115], v[218:221], v[202:205], v[112:115]
	v_mfma_f32_16x16x32_bf16 v[44:47], v[222:225], v[202:205], v[44:47]
	v_mfma_f32_16x16x32_bf16 v[40:43], v[226:229], v[202:205], v[40:43]
	v_mfma_f32_16x16x32_bf16 v[92:95], v[214:217], v[178:181], v[92:95]
	v_mfma_f32_16x16x32_bf16 v[88:91], v[218:221], v[178:181], v[88:91]
	v_mfma_f32_16x16x32_bf16 v[20:23], v[222:225], v[178:181], v[20:23]
	v_mfma_f32_16x16x32_bf16 v[16:19], v[226:229], v[178:181], v[16:19]
	v_mfma_f32_16x16x32_bf16 v[84:87], v[214:217], v[182:185], v[84:87]
	v_mfma_f32_16x16x32_bf16 v[80:83], v[218:221], v[182:185], v[80:83]
	v_mfma_f32_16x16x32_bf16 v[12:15], v[222:225], v[182:185], v[12:15]
	v_mfma_f32_16x16x32_bf16 v[8:11], v[226:229], v[182:185], v[8:11]
	v_mfma_f32_16x16x32_bf16 v[76:79], v[214:217], v[170:173], v[76:79]
	v_mfma_f32_16x16x32_bf16 v[72:75], v[218:221], v[170:173], v[72:75]
	v_mfma_f32_16x16x32_bf16 v[4:7], v[222:225], v[170:173], v[4:7]
	v_mfma_f32_16x16x32_bf16 v[0:3], v[226:229], v[170:173], v[0:3]
	v_mfma_f32_16x16x32_bf16 v[68:71], v[214:217], v[174:177], v[68:71]
	v_mfma_f32_16x16x32_bf16 v[64:67], v[218:221], v[174:177], v[64:67]
	v_mfma_f32_16x16x32_bf16 v[52:55], v[222:225], v[174:177], v[52:55]
	v_mfma_f32_16x16x32_bf16 v[56:59], v[226:229], v[174:177], v[56:59]

.LBB0_1357:
	s_or_b64 exec, exec, s[10:11]
	v_cvt_f32_u32_e32 v4, v2
	s_waitcnt vmcnt(0)
	v_readfirstlane_b32 s8, v3
	v_sub_u32_e32 v3, 0, v2
	v_rcp_iflag_f32_e32 v4, v4
	v_add_u32_e32 v5, s8, v1
	v_mul_f32_e32 v4, 0x4f7ffffe, v4
	v_cvt_u32_f32_e32 v4, v4
	v_mul_lo_u32 v1, v3, v4
	v_mul_hi_u32 v1, v4, v1
	v_add_u32_e32 v1, v4, v1
	v_mul_hi_u32 v1, v5, v1
	v_mul_lo_u32 v3, v1, v2
	v_sub_u32_e32 v3, v5, v3
	v_add_u32_e32 v4, 1, v1
	v_cmp_ge_u32_e32 vcc, v3, v2
	s_nop 1
	v_cndmask_b32_e32 v1, v1, v4, vcc
	v_sub_u32_e32 v4, v3, v2
	v_cndmask_b32_e32 v3, v3, v4, vcc
	v_add_u32_e32 v4, 1, v1
	v_cmp_ge_u32_e32 vcc, v3, v2
	v_add_u32_e32 v3, 1, v5
	s_nop 0
	v_cndmask_b32_e32 v1, v1, v4, vcc
	v_mul_lo_u32 v4, v2, v1
	v_add_u32_e32 v2, v4, v2
	v_cmp_ne_u32_e32 vcc, v3, v2
	s_and_saveexec_b64 s[8:9], vcc
	s_xor_b64 s[8:9], exec, s[8:9]
	s_cbranch_execz .LBB0_1371
	s_waitcnt lgkmcnt(0)
	buffer_inv sc1
	v_mov_b32_e32 v0, 0
	v_mov_b32_e32 v1, 8
	s_add_u32 s14, s86, 0xe7b4500
	s_addc_u32 s15, s87, 0
	global_load_dword v0, v0, s[14:15] sc1
	s_waitcnt vmcnt(0)
	v_cmp_eq_u32_e32 vcc, v0, v1
	s_and_saveexec_b64 s[10:11], vcc
	s_cbranch_execz .LBB0_1370
	s_add_u32 s12, s86, 0xe7b1200
	s_addc_u32 s13, s87, 0
	s_mov_b32 s28, 1
	s_mov_b64 s[16:17], 0
	v_mov_b32_e32 v0, 0
	s_branch .LBB0_1361

.LBB0_1420:
	s_or_b64 exec, exec, s[10:11]
	v_cvt_f32_u32_e32 v4, v2
	s_waitcnt vmcnt(0)
	v_readfirstlane_b32 s8, v3
	v_sub_u32_e32 v3, 0, v2
	v_rcp_iflag_f32_e32 v4, v4
	v_add_u32_e32 v5, s8, v1
	v_mul_f32_e32 v4, 0x4f7ffffe, v4
	v_cvt_u32_f32_e32 v4, v4
	v_mul_lo_u32 v1, v3, v4
	v_mul_hi_u32 v1, v4, v1
	v_add_u32_e32 v1, v4, v1
	v_mul_hi_u32 v1, v5, v1
	v_mul_lo_u32 v3, v1, v2
	v_sub_u32_e32 v3, v5, v3
	v_add_u32_e32 v4, 1, v1
	v_cmp_ge_u32_e32 vcc, v3, v2
	s_nop 1
	v_cndmask_b32_e32 v1, v1, v4, vcc
	v_sub_u32_e32 v4, v3, v2
	v_cndmask_b32_e32 v3, v3, v4, vcc
	v_add_u32_e32 v4, 1, v1
	v_cmp_ge_u32_e32 vcc, v3, v2
	v_add_u32_e32 v3, 1, v5
	s_nop 0
	v_cndmask_b32_e32 v1, v1, v4, vcc
	v_mul_lo_u32 v4, v2, v1
	v_add_u32_e32 v2, v4, v2
	v_cmp_ne_u32_e32 vcc, v3, v2
	s_and_saveexec_b64 s[8:9], vcc
	s_xor_b64 s[8:9], exec, s[8:9]
	s_cbranch_execz .LBB0_1434
	s_waitcnt lgkmcnt(0)
	buffer_inv sc1
	v_mov_b32_e32 v0, 0
	v_mov_b32_e32 v1, 9
	s_add_u32 s14, s86, 0xe7b4500
	s_addc_u32 s15, s87, 0
	global_load_dword v0, v0, s[14:15] sc1
	s_waitcnt vmcnt(0)
	v_cmp_eq_u32_e32 vcc, v0, v1
	s_and_saveexec_b64 s[10:11], vcc
	s_cbranch_execz .LBB0_1433
	s_add_u32 s12, s86, 0xe7b1200
	s_addc_u32 s13, s87, 0
	s_mov_b32 s28, 1
	s_mov_b64 s[16:17], 0
	v_mov_b32_e32 v0, 0
	s_branch .LBB0_1424

.LBB0_1461:
	v_readfirstlane_b32 s11, v128
	s_lshr_b32 s12, s11, 1
	s_and_b32 s12, s12, 0x1ffff80
	s_lshl_b32 s0, s10, 19
	v_or_b32_e32 v5, s12, v189
	s_and_b32 s12, s11, 0xc0
	s_lshl_b32 s11, s11, 4
	v_add_u32_e32 v2, s0, v134
	v_lshlrev_b32_e32 v167, 7, v5
	v_or_b32_e32 v5, s12, v189
	s_and_b32 s11, s11, 0x7ffffc00
	v_add_u32_e32 v0, s0, v138
	v_lshl_or_b32 v203, v5, 7, v165
	v_and_b32_e32 v5, 0xfffff870, v2
	s_mov_b32 m0, s11
	v_add_u32_e32 v1, s0, v140
	global_load_lds_dwordx4 v5, s[86:87]
	v_and_b32_e32 v0, 0xfffff870, v0
	s_add_i32 m0, s11, 0x2000
	s_lshl_b32 s1, s30, 19
	v_add_u32_e32 v3, s0, v142
	global_load_lds_dwordx4 v0, s[86:87]
	v_and_b32_e32 v0, 0xfffff870, v1
	s_add_i32 m0, s11, 0x4000
	s_add_i32 s8, s1, 0x1080000
	global_load_lds_dwordx4 v0, s[86:87]
	v_and_b32_e32 v0, 0xfffff870, v3
	s_add_i32 m0, s11, 0x6000
	s_add_i32 s12, s11, 0x8000
	global_load_lds_dwordx4 v0, s[86:87]
	v_or_b32_e32 v0, s8, v144
	v_mov_b32_e32 v1, v145
	v_lshl_add_u64 v[0:1], s[86:87], 0, v[0:1]
	s_mov_b32 m0, s12
	v_add_u32_e32 v4, s1, v150
	global_load_lds_dwordx4 v[0:1], off
	v_or_b32_e32 v0, s8, v146
	v_mov_b32_e32 v1, v129
	v_lshl_add_u64 v[0:1], s[86:87], 0, v[0:1]
	s_add_i32 m0, s11, 0xa000
	v_and_b32_e32 v136, -16, v2
	global_load_lds_dwordx4 v[0:1], off
	v_or_b32_e32 v0, s8, v148
	v_mov_b32_e32 v1, v149
	v_lshl_add_u64 v[0:1], s[86:87], 0, v[0:1]
	s_add_i32 m0, s11, 0xc000
	v_lshl_add_u64 v[168:169], s[6:7], 0, v[136:137]
	global_load_lds_dwordx4 v[0:1], off
	v_and_b32_e32 v0, 0xfffff870, v4
	s_add_i32 m0, s11, 0xe000
	v_mov_b32_e32 v52, 0
	global_load_lds_dwordx4 v0, s[86:87]
	v_add_u32_e32 v0, s0, v152
	v_and_b32_e32 v136, -16, v0
	v_add_u32_e32 v0, s0, v154
	v_lshl_add_u64 v[170:171], s[6:7], 0, v[136:137]
	v_and_b32_e32 v136, -16, v0
	v_add_u32_e32 v0, s0, v156
	s_waitcnt vmcnt(0)
	v_lshl_add_u64 v[172:173], s[6:7], 0, v[136:137]
	v_and_b32_e32 v136, -16, v0
	v_add_u32_e32 v0, s1, v164
	v_lshl_add_u64 v[174:175], s[6:7], 0, v[136:137]
	v_and_b32_e32 v136, -16, v0
	v_lshl_add_u64 v[176:177], v[158:159], 0, s[8:9]
	v_lshl_add_u64 v[178:179], v[160:161], 0, s[8:9]
	v_lshl_add_u64 v[180:181], v[162:163], 0, s[8:9]
	v_lshl_add_u64 v[182:183], s[6:7], 0, v[136:137]
	s_mov_b32 s8, 0
	s_mov_b64 s[0:1], 0
	v_mov_b32_e32 v53, v52
	v_mov_b32_e32 v54, v52
	v_mov_b32_e32 v55, v52
	v_mov_b32_e32 v0, v52
	v_mov_b32_e32 v1, v52
	v_mov_b32_e32 v2, v52
	v_mov_b32_e32 v3, v52
	v_mov_b32_e32 v64, v52
	v_mov_b32_e32 v65, v52
	v_mov_b32_e32 v66, v52
	v_mov_b32_e32 v67, v52
	v_mov_b32_e32 v68, v52
	v_mov_b32_e32 v69, v52
	v_mov_b32_e32 v70, v52
	v_mov_b32_e32 v71, v52
	v_mov_b32_e32 v4, v52
	v_mov_b32_e32 v5, v52
	v_mov_b32_e32 v6, v52
	v_mov_b32_e32 v7, v52
	v_mov_b32_e32 v8, v52
	v_mov_b32_e32 v9, v52
	v_mov_b32_e32 v10, v52
	v_mov_b32_e32 v11, v52
	v_mov_b32_e32 v72, v52
	v_mov_b32_e32 v73, v52
	v_mov_b32_e32 v74, v52
	v_mov_b32_e32 v75, v52
	v_mov_b32_e32 v76, v52
	v_mov_b32_e32 v77, v52
	v_mov_b32_e32 v78, v52
	v_mov_b32_e32 v79, v52
	s_waitcnt vmcnt(0)
	v_mov_b32_e32 v12, v52
	v_mov_b32_e32 v13, v52
	v_mov_b32_e32 v14, v52
	v_mov_b32_e32 v15, v52
	v_mov_b32_e32 v16, v52
	v_mov_b32_e32 v17, v52
	v_mov_b32_e32 v18, v52
	v_mov_b32_e32 v19, v52
	v_mov_b32_e32 v80, v52
	v_mov_b32_e32 v81, v52
	v_mov_b32_e32 v82, v52
	v_mov_b32_e32 v83, v52
	v_mov_b32_e32 v84, v52
	v_mov_b32_e32 v85, v52
	v_mov_b32_e32 v86, v52
	v_mov_b32_e32 v87, v52
	v_mov_b32_e32 v20, v52
	v_mov_b32_e32 v21, v52
	v_mov_b32_e32 v22, v52
	v_mov_b32_e32 v23, v52
	v_mov_b32_e32 v24, v52
	v_mov_b32_e32 v25, v52
	v_mov_b32_e32 v26, v52
	v_mov_b32_e32 v27, v52
	v_mov_b32_e32 v88, v52
	v_mov_b32_e32 v89, v52
	v_mov_b32_e32 v90, v52
	v_mov_b32_e32 v91, v52
	v_mov_b32_e32 v92, v52
	v_mov_b32_e32 v93, v52
	v_mov_b32_e32 v94, v52
	v_mov_b32_e32 v95, v52
	v_mov_b32_e32 v28, v52
	v_mov_b32_e32 v29, v52
	v_mov_b32_e32 v30, v52
	v_mov_b32_e32 v31, v52
	v_mov_b32_e32 v32, v52
	v_mov_b32_e32 v33, v52
	v_mov_b32_e32 v34, v52
	v_mov_b32_e32 v35, v52
	v_mov_b32_e32 v96, v52
	v_mov_b32_e32 v97, v52
	v_mov_b32_e32 v98, v52
	v_mov_b32_e32 v99, v52
	v_mov_b32_e32 v100, v52
	v_mov_b32_e32 v101, v52
	v_mov_b32_e32 v102, v52
	v_mov_b32_e32 v103, v52
	v_mov_b32_e32 v36, v52
	v_mov_b32_e32 v37, v52
	v_mov_b32_e32 v38, v52
	v_mov_b32_e32 v39, v52
	v_mov_b32_e32 v40, v52
	v_mov_b32_e32 v41, v52
	v_mov_b32_e32 v42, v52
	v_mov_b32_e32 v43, v52
	v_mov_b32_e32 v104, v52
	v_mov_b32_e32 v105, v52
	v_mov_b32_e32 v106, v52
	v_mov_b32_e32 v107, v52
	v_mov_b32_e32 v108, v52
	v_mov_b32_e32 v109, v52
	v_mov_b32_e32 v110, v52
	v_mov_b32_e32 v111, v52
	v_mov_b32_e32 v44, v52
	v_mov_b32_e32 v45, v52
	v_mov_b32_e32 v46, v52
	v_mov_b32_e32 v47, v52
	v_mov_b32_e32 v48, v52
	v_mov_b32_e32 v49, v52
	v_mov_b32_e32 v50, v52
	v_mov_b32_e32 v51, v52
	v_mov_b32_e32 v112, v52
	v_mov_b32_e32 v113, v52
	v_mov_b32_e32 v114, v52
	v_mov_b32_e32 v115, v52
	v_mov_b32_e32 v116, v52
	v_mov_b32_e32 v117, v52
	v_mov_b32_e32 v118, v52
	v_mov_b32_e32 v119, v52
	v_mov_b32_e32 v56, v52
	v_mov_b32_e32 v57, v52
	v_mov_b32_e32 v58, v52
	v_mov_b32_e32 v59, v52
	v_mov_b32_e32 v60, v52
	v_mov_b32_e32 v61, v52
	v_mov_b32_e32 v62, v52
	v_mov_b32_e32 v63, v52
	v_mov_b32_e32 v120, v52
	v_mov_b32_e32 v121, v52
	v_mov_b32_e32 v122, v52
	v_mov_b32_e32 v123, v52
	v_mov_b32_e32 v124, v52
	v_mov_b32_e32 v125, v52
	v_mov_b32_e32 v126, v52
	v_mov_b32_e32 v127, v52
	s_waitcnt lgkmcnt(0)
	s_barrier
	s_mov_b32 s12, 0x10000
	s_and_b32 s12, s8, 0x10000
	s_xor_b32 s13, s12, 0x10000
	s_add_i32 s13, s11, s13
	s_add_i32 s31, s13, 0x8000
	s_mov_b32 m0, s13
	v_lshl_add_u64 v[254:255], v[168:169], 0, s[0:1]
	global_load_lds_dwordx4 v[254:255], off
	s_add_i32 m0, s13, 0x2000
	v_lshl_add_u64 v[254:255], v[170:171], 0, s[0:1]
	global_load_lds_dwordx4 v[254:255], off
	s_add_i32 m0, s13, 0x4000
	v_lshl_add_u64 v[254:255], v[172:173], 0, s[0:1]
	global_load_lds_dwordx4 v[254:255], off
	s_add_i32 m0, s13, 0x6000
	v_lshl_add_u64 v[254:255], v[174:175], 0, s[0:1]
	global_load_lds_dwordx4 v[254:255], off
	s_mov_b32 m0, s31
	v_lshl_add_u64 v[254:255], v[176:177], 0, s[0:1]
	global_load_lds_dwordx4 v[254:255], off
	s_add_i32 m0, s13, 0xa000
	v_lshl_add_u64 v[254:255], v[178:179], 0, s[0:1]
	global_load_lds_dwordx4 v[254:255], off
	s_add_i32 m0, s13, 0xc000
	v_lshl_add_u64 v[254:255], v[180:181], 0, s[0:1]
	global_load_lds_dwordx4 v[254:255], off
	s_add_i32 m0, s13, 0xe000
	v_lshl_add_u64 v[254:255], v[182:183], 0, s[0:1]
	global_load_lds_dwordx4 v[254:255], off
	v_add3_u32 v253, s12, v167, v139
	ds_read_b128 v[228:231], v253 offset:0x1000
	ds_read_b128 v[232:235], v253 offset:0x1800
	ds_read_b128 v[220:223], v253 offset:0
	v_add3_u32 v253, s12, v203, v139
	ds_read_b128 v[204:207], v253 offset:0
	v_add3_u32 v253, s12, v167, v139
	ds_read_b128 v[224:227], v253 offset:0x800
	v_add3_u32 v253, s12, v203, v139
	ds_read_b128 v[208:211], v253 offset:0x800
	ds_read_b128 v[212:215], v253 offset:0x1000
	ds_read_b128 v[216:219], v253 offset:0x1800
.Lginp1_body:
	v_add_u32_e32 v237, s12, v203
	v_add_u32_e32 v136, s12, v167
	v_add_u32_e32 v236, v136, v139
	v_add_u32_e32 v248, v237, v147
	s_waitcnt lgkmcnt(4)
	v_add_u32_e32 v136, v136, v147
	v_mfma_f32_16x16x32_bf16 v[124:127], v[204:207], v[220:223], v[124:127]
	s_waitcnt lgkmcnt(2)
	v_mfma_f32_16x16x32_bf16 v[120:123], v[208:211], v[220:223], v[120:123]
	s_waitcnt lgkmcnt(1)
	v_mfma_f32_16x16x32_bf16 v[60:63], v[212:215], v[220:223], v[60:63]
	s_waitcnt lgkmcnt(0)
	v_mfma_f32_16x16x32_bf16 v[56:59], v[216:219], v[220:223], v[56:59]
	ds_read_b128 v[220:223], v236 offset:0x2000
	v_mfma_f32_16x16x32_bf16 v[116:119], v[204:207], v[224:227], v[116:119]
	v_mfma_f32_16x16x32_bf16 v[112:115], v[208:211], v[224:227], v[112:115]
	v_mfma_f32_16x16x32_bf16 v[48:51], v[212:215], v[224:227], v[48:51]
	v_mfma_f32_16x16x32_bf16 v[44:47], v[216:219], v[224:227], v[44:47]
	ds_read_b128 v[224:227], v236 offset:0x2800
	s_waitcnt lgkmcnt(2)
	s_nop 0
	v_mfma_f32_16x16x32_bf16 v[108:111], v[204:207], v[228:231], v[108:111]
	v_mfma_f32_16x16x32_bf16 v[104:107], v[208:211], v[228:231], v[104:107]
	v_mfma_f32_16x16x32_bf16 v[40:43], v[212:215], v[228:231], v[40:43]
	v_mfma_f32_16x16x32_bf16 v[36:39], v[216:219], v[228:231], v[36:39]
	ds_read_b128 v[228:231], v236 offset:0x3000
	v_mfma_f32_16x16x32_bf16 v[100:103], v[204:207], v[232:235], v[100:103]
	v_mfma_f32_16x16x32_bf16 v[96:99], v[208:211], v[232:235], v[96:99]
	v_mfma_f32_16x16x32_bf16 v[32:35], v[212:215], v[232:235], v[32:35]
	v_mfma_f32_16x16x32_bf16 v[28:31], v[216:219], v[232:235], v[28:31]
	ds_read_b128 v[232:235], v236 offset:0x3800
	ds_read_b128 v[236:239], v248 offset:0
	ds_read_b128 v[240:243], v248 offset:0x800
	ds_read_b128 v[244:247], v248 offset:0x1000
	ds_read_b128 v[248:251], v248 offset:0x1800
	s_waitcnt lgkmcnt(6)
	s_nop 0
	v_mfma_f32_16x16x32_bf16 v[92:95], v[204:207], v[220:223], v[92:95]
	v_mfma_f32_16x16x32_bf16 v[88:91], v[208:211], v[220:223], v[88:91]
	v_mfma_f32_16x16x32_bf16 v[24:27], v[212:215], v[220:223], v[24:27]
	v_mfma_f32_16x16x32_bf16 v[20:23], v[216:219], v[220:223], v[20:23]
	ds_read_b128 v[220:223], v136 offset:0
	v_mfma_f32_16x16x32_bf16 v[84:87], v[204:207], v[224:227], v[84:87]
	v_mfma_f32_16x16x32_bf16 v[80:83], v[208:211], v[224:227], v[80:83]
	v_mfma_f32_16x16x32_bf16 v[16:19], v[212:215], v[224:227], v[16:19]
	v_mfma_f32_16x16x32_bf16 v[12:15], v[216:219], v[224:227], v[12:15]
	ds_read_b128 v[224:227], v136 offset:0x800
	s_waitcnt lgkmcnt(6)
	s_nop 0
	v_mfma_f32_16x16x32_bf16 v[76:79], v[204:207], v[228:231], v[76:79]
	v_mfma_f32_16x16x32_bf16 v[68:71], v[204:207], v[232:235], v[68:71]
	ds_read_b128 v[204:207], v136 offset:0x1000
	v_mfma_f32_16x16x32_bf16 v[72:75], v[208:211], v[228:231], v[72:75]
	v_mfma_f32_16x16x32_bf16 v[64:67], v[208:211], v[232:235], v[64:67]
	ds_read_b128 v[208:211], v136 offset:0x1800
	s_waitcnt lgkmcnt(2)
	v_mfma_f32_16x16x32_bf16 v[8:11], v[212:215], v[228:231], v[8:11]
	v_mfma_f32_16x16x32_bf16 v[0:3], v[212:215], v[232:235], v[0:3]
	ds_read_b128 v[212:215], v136 offset:0x2000
	v_mfma_f32_16x16x32_bf16 v[4:7], v[216:219], v[228:231], v[4:7]
	v_mfma_f32_16x16x32_bf16 v[52:55], v[216:219], v[232:235], v[52:55]
	ds_read_b128 v[216:219], v136 offset:0x2800
	s_waitcnt lgkmcnt(2)
	s_nop 0
	v_mfma_f32_16x16x32_bf16 v[108:111], v[236:239], v[204:207], v[108:111]
	v_mfma_f32_16x16x32_bf16 v[104:107], v[240:243], v[204:207], v[104:107]
	v_mfma_f32_16x16x32_bf16 v[40:43], v[244:247], v[204:207], v[40:43]
	v_mfma_f32_16x16x32_bf16 v[36:39], v[248:251], v[204:207], v[36:39]
	ds_read_b128 v[204:207], v136 offset:0x3000
	v_mfma_f32_16x16x32_bf16 v[100:103], v[236:239], v[208:211], v[100:103]
	v_mfma_f32_16x16x32_bf16 v[96:99], v[240:243], v[208:211], v[96:99]
	v_mfma_f32_16x16x32_bf16 v[32:35], v[244:247], v[208:211], v[32:35]
	v_mfma_f32_16x16x32_bf16 v[28:31], v[248:251], v[208:211], v[28:31]
	ds_read_b128 v[208:211], v136 offset:0x3800
	s_waitcnt lgkmcnt(2)
	v_mfma_f32_16x16x32_bf16 v[124:127], v[236:239], v[220:223], v[124:127]
	s_add_i32 s8, s8, 0x10000
	s_add_u32 s0, s0, 0x80
	s_addc_u32 s1, s1, 0
	s_waitcnt lgkmcnt(0)
	s_waitcnt vmcnt(0)
	s_waitcnt vmcnt(0) lgkmcnt(0)
	v_mfma_f32_16x16x32_bf16 v[120:123], v[240:243], v[220:223], v[120:123]
	s_barrier
	s_cmpk_eq_i32 s0, 0x780
	s_cbranch_scc1 .Lginp1_nodma
	s_mov_b32 s12, 0x10000
	s_and_b32 s12, s8, 0x10000
	s_xor_b32 s13, s12, 0x10000
	s_add_i32 s13, s11, s13
	s_add_i32 s31, s13, 0x8000
	v_add3_u32 v253, s12, v167, v139
	ds_read_b128 v[228:231], v253 offset:0x1000
	ds_read_b128 v[232:235], v253 offset:0x1800
	v_mfma_f32_16x16x32_bf16 v[60:63], v[244:247], v[220:223], v[60:63]
	s_mov_b32 m0, s13
	v_lshl_add_u64 v[254:255], v[168:169], 0, s[0:1]
	global_load_lds_dwordx4 v[254:255], off
	v_mfma_f32_16x16x32_bf16 v[56:59], v[248:251], v[220:223], v[56:59]
	ds_read_b128 v[220:223], v253 offset:0
	v_mfma_f32_16x16x32_bf16 v[76:79], v[236:239], v[204:207], v[76:79]
	s_add_i32 m0, s13, 0x2000
	v_lshl_add_u64 v[254:255], v[170:171], 0, s[0:1]
	global_load_lds_dwordx4 v[254:255], off
	v_mfma_f32_16x16x32_bf16 v[72:75], v[240:243], v[204:207], v[72:75]
	v_mfma_f32_16x16x32_bf16 v[8:11], v[244:247], v[204:207], v[8:11]
	s_add_i32 m0, s13, 0x4000
	v_lshl_add_u64 v[254:255], v[172:173], 0, s[0:1]
	global_load_lds_dwordx4 v[254:255], off
	v_mfma_f32_16x16x32_bf16 v[4:7], v[248:251], v[204:207], v[4:7]
	v_add3_u32 v253, s12, v203, v139
	ds_read_b128 v[204:207], v253 offset:0
	v_mfma_f32_16x16x32_bf16 v[116:119], v[236:239], v[224:227], v[116:119]
	s_add_i32 m0, s13, 0x6000
	v_lshl_add_u64 v[254:255], v[174:175], 0, s[0:1]
	global_load_lds_dwordx4 v[254:255], off
	v_mfma_f32_16x16x32_bf16 v[112:115], v[240:243], v[224:227], v[112:115]
	v_mfma_f32_16x16x32_bf16 v[48:51], v[244:247], v[224:227], v[48:51]
	s_mov_b32 m0, s31
	v_lshl_add_u64 v[254:255], v[176:177], 0, s[0:1]
	global_load_lds_dwordx4 v[254:255], off
	v_mfma_f32_16x16x32_bf16 v[44:47], v[248:251], v[224:227], v[44:47]
	v_add3_u32 v253, s12, v167, v139
	ds_read_b128 v[224:227], v253 offset:0x800
	v_mfma_f32_16x16x32_bf16 v[68:71], v[236:239], v[208:211], v[68:71]
	s_add_i32 m0, s13, 0xa000
	v_lshl_add_u64 v[254:255], v[178:179], 0, s[0:1]
	global_load_lds_dwordx4 v[254:255], off
	v_mfma_f32_16x16x32_bf16 v[64:67], v[240:243], v[208:211], v[64:67]
	v_mfma_f32_16x16x32_bf16 v[0:3], v[244:247], v[208:211], v[0:3]
	s_add_i32 m0, s13, 0xc000
	v_lshl_add_u64 v[254:255], v[180:181], 0, s[0:1]
	global_load_lds_dwordx4 v[254:255], off
	v_mfma_f32_16x16x32_bf16 v[52:55], v[248:251], v[208:211], v[52:55]
	v_add3_u32 v253, s12, v203, v139
	ds_read_b128 v[208:211], v253 offset:0x800
	v_mfma_f32_16x16x32_bf16 v[92:95], v[236:239], v[212:215], v[92:95]
	s_add_i32 m0, s13, 0xe000
	v_lshl_add_u64 v[254:255], v[182:183], 0, s[0:1]
	global_load_lds_dwordx4 v[254:255], off
	v_mfma_f32_16x16x32_bf16 v[88:91], v[240:243], v[212:215], v[88:91]
	v_mfma_f32_16x16x32_bf16 v[24:27], v[244:247], v[212:215], v[24:27]
	v_mfma_f32_16x16x32_bf16 v[20:23], v[248:251], v[212:215], v[20:23]
	ds_read_b128 v[212:215], v253 offset:0x1000
	v_mfma_f32_16x16x32_bf16 v[84:87], v[236:239], v[216:219], v[84:87]
	v_mfma_f32_16x16x32_bf16 v[80:83], v[240:243], v[216:219], v[80:83]
	v_mfma_f32_16x16x32_bf16 v[16:19], v[244:247], v[216:219], v[16:19]
	v_mfma_f32_16x16x32_bf16 v[12:15], v[248:251], v[216:219], v[12:15]
	ds_read_b128 v[216:219], v253 offset:0x1800
	s_branch .Lginp1_body
.Lginp1_nodma:
	s_mov_b32 s12, 0x10000
	v_add3_u32 v253, s12, v167, v139
	ds_read_b128 v[228:231], v253 offset:0x1000
	ds_read_b128 v[232:235], v253 offset:0x1800
	v_mfma_f32_16x16x32_bf16 v[60:63], v[244:247], v[220:223], v[60:63]
	v_mfma_f32_16x16x32_bf16 v[56:59], v[248:251], v[220:223], v[56:59]
	ds_read_b128 v[220:223], v253 offset:0
	v_mfma_f32_16x16x32_bf16 v[76:79], v[236:239], v[204:207], v[76:79]
	v_mfma_f32_16x16x32_bf16 v[72:75], v[240:243], v[204:207], v[72:75]
	v_mfma_f32_16x16x32_bf16 v[8:11], v[244:247], v[204:207], v[8:11]
	v_mfma_f32_16x16x32_bf16 v[4:7], v[248:251], v[204:207], v[4:7]
	v_add3_u32 v253, s12, v203, v139
	ds_read_b128 v[204:207], v253 offset:0
	v_mfma_f32_16x16x32_bf16 v[116:119], v[236:239], v[224:227], v[116:119]
	v_mfma_f32_16x16x32_bf16 v[112:115], v[240:243], v[224:227], v[112:115]
	v_mfma_f32_16x16x32_bf16 v[48:51], v[244:247], v[224:227], v[48:51]
	v_mfma_f32_16x16x32_bf16 v[44:47], v[248:251], v[224:227], v[44:47]
	v_add3_u32 v253, s12, v167, v139
	ds_read_b128 v[224:227], v253 offset:0x800
	v_mfma_f32_16x16x32_bf16 v[68:71], v[236:239], v[208:211], v[68:71]
	v_mfma_f32_16x16x32_bf16 v[64:67], v[240:243], v[208:211], v[64:67]
	v_mfma_f32_16x16x32_bf16 v[0:3], v[244:247], v[208:211], v[0:3]
	v_mfma_f32_16x16x32_bf16 v[52:55], v[248:251], v[208:211], v[52:55]
	v_add3_u32 v253, s12, v203, v139
	ds_read_b128 v[208:211], v253 offset:0x800
	v_mfma_f32_16x16x32_bf16 v[92:95], v[236:239], v[212:215], v[92:95]
	v_mfma_f32_16x16x32_bf16 v[88:91], v[240:243], v[212:215], v[88:91]
	v_mfma_f32_16x16x32_bf16 v[24:27], v[244:247], v[212:215], v[24:27]
	v_mfma_f32_16x16x32_bf16 v[20:23], v[248:251], v[212:215], v[20:23]
	ds_read_b128 v[212:215], v253 offset:0x1000
	v_mfma_f32_16x16x32_bf16 v[84:87], v[236:239], v[216:219], v[84:87]
	v_mfma_f32_16x16x32_bf16 v[80:83], v[240:243], v[216:219], v[80:83]
	v_mfma_f32_16x16x32_bf16 v[16:19], v[244:247], v[216:219], v[16:19]
	v_mfma_f32_16x16x32_bf16 v[12:15], v[248:251], v[216:219], v[12:15]
	ds_read_b128 v[216:219], v253 offset:0x1800
	v_add_u32_e32 v237, s12, v203
	v_add_u32_e32 v136, s12, v167
	v_add_u32_e32 v236, v136, v139
	v_add_u32_e32 v248, v237, v147
	s_waitcnt lgkmcnt(4)
	v_add_u32_e32 v136, v136, v147
	v_mfma_f32_16x16x32_bf16 v[124:127], v[204:207], v[220:223], v[124:127]
	s_waitcnt lgkmcnt(2)
	v_mfma_f32_16x16x32_bf16 v[120:123], v[208:211], v[220:223], v[120:123]
	s_waitcnt lgkmcnt(1)
	v_mfma_f32_16x16x32_bf16 v[60:63], v[212:215], v[220:223], v[60:63]
	s_waitcnt lgkmcnt(0)
	v_mfma_f32_16x16x32_bf16 v[56:59], v[216:219], v[220:223], v[56:59]
	ds_read_b128 v[220:223], v236 offset:0x2000
	v_mfma_f32_16x16x32_bf16 v[116:119], v[204:207], v[224:227], v[116:119]
	v_mfma_f32_16x16x32_bf16 v[112:115], v[208:211], v[224:227], v[112:115]
	v_mfma_f32_16x16x32_bf16 v[48:51], v[212:215], v[224:227], v[48:51]
	v_mfma_f32_16x16x32_bf16 v[44:47], v[216:219], v[224:227], v[44:47]
	ds_read_b128 v[224:227], v236 offset:0x2800
	s_waitcnt lgkmcnt(2)
	s_nop 0
	v_mfma_f32_16x16x32_bf16 v[108:111], v[204:207], v[228:231], v[108:111]
	v_mfma_f32_16x16x32_bf16 v[104:107], v[208:211], v[228:231], v[104:107]
	v_mfma_f32_16x16x32_bf16 v[40:43], v[212:215], v[228:231], v[40:43]
	v_mfma_f32_16x16x32_bf16 v[36:39], v[216:219], v[228:231], v[36:39]
	ds_read_b128 v[228:231], v236 offset:0x3000
	v_mfma_f32_16x16x32_bf16 v[100:103], v[204:207], v[232:235], v[100:103]
	v_mfma_f32_16x16x32_bf16 v[96:99], v[208:211], v[232:235], v[96:99]
	v_mfma_f32_16x16x32_bf16 v[32:35], v[212:215], v[232:235], v[32:35]
	v_mfma_f32_16x16x32_bf16 v[28:31], v[216:219], v[232:235], v[28:31]
	ds_read_b128 v[232:235], v236 offset:0x3800
	ds_read_b128 v[236:239], v248 offset:0
	ds_read_b128 v[240:243], v248 offset:0x800
	ds_read_b128 v[244:247], v248 offset:0x1000
	ds_read_b128 v[248:251], v248 offset:0x1800
	s_waitcnt lgkmcnt(6)
	s_nop 0
	v_mfma_f32_16x16x32_bf16 v[92:95], v[204:207], v[220:223], v[92:95]
	v_mfma_f32_16x16x32_bf16 v[88:91], v[208:211], v[220:223], v[88:91]
	v_mfma_f32_16x16x32_bf16 v[24:27], v[212:215], v[220:223], v[24:27]
	v_mfma_f32_16x16x32_bf16 v[20:23], v[216:219], v[220:223], v[20:23]
	ds_read_b128 v[220:223], v136 offset:0
	v_mfma_f32_16x16x32_bf16 v[84:87], v[204:207], v[224:227], v[84:87]
	v_mfma_f32_16x16x32_bf16 v[80:83], v[208:211], v[224:227], v[80:83]
	v_mfma_f32_16x16x32_bf16 v[16:19], v[212:215], v[224:227], v[16:19]
	v_mfma_f32_16x16x32_bf16 v[12:15], v[216:219], v[224:227], v[12:15]
	ds_read_b128 v[224:227], v136 offset:0x800
	s_waitcnt lgkmcnt(6)
	s_nop 0
	v_mfma_f32_16x16x32_bf16 v[76:79], v[204:207], v[228:231], v[76:79]
	v_mfma_f32_16x16x32_bf16 v[68:71], v[204:207], v[232:235], v[68:71]
	ds_read_b128 v[204:207], v136 offset:0x1000
	v_mfma_f32_16x16x32_bf16 v[72:75], v[208:211], v[228:231], v[72:75]
	v_mfma_f32_16x16x32_bf16 v[64:67], v[208:211], v[232:235], v[64:67]
	ds_read_b128 v[208:211], v136 offset:0x1800
	s_waitcnt lgkmcnt(2)
	v_mfma_f32_16x16x32_bf16 v[8:11], v[212:215], v[228:231], v[8:11]
	v_mfma_f32_16x16x32_bf16 v[0:3], v[212:215], v[232:235], v[0:3]
	ds_read_b128 v[212:215], v136 offset:0x2000
	v_mfma_f32_16x16x32_bf16 v[4:7], v[216:219], v[228:231], v[4:7]
	v_mfma_f32_16x16x32_bf16 v[52:55], v[216:219], v[232:235], v[52:55]
	ds_read_b128 v[216:219], v136 offset:0x2800
	s_waitcnt lgkmcnt(2)
	s_nop 0
	v_mfma_f32_16x16x32_bf16 v[108:111], v[236:239], v[204:207], v[108:111]
	v_mfma_f32_16x16x32_bf16 v[104:107], v[240:243], v[204:207], v[104:107]
	v_mfma_f32_16x16x32_bf16 v[40:43], v[244:247], v[204:207], v[40:43]
	v_mfma_f32_16x16x32_bf16 v[36:39], v[248:251], v[204:207], v[36:39]
	ds_read_b128 v[204:207], v136 offset:0x3000
	v_mfma_f32_16x16x32_bf16 v[100:103], v[236:239], v[208:211], v[100:103]
	v_mfma_f32_16x16x32_bf16 v[96:99], v[240:243], v[208:211], v[96:99]
	v_mfma_f32_16x16x32_bf16 v[32:35], v[244:247], v[208:211], v[32:35]
	v_mfma_f32_16x16x32_bf16 v[28:31], v[248:251], v[208:211], v[28:31]
	ds_read_b128 v[208:211], v136 offset:0x3800
	s_waitcnt lgkmcnt(2)
	v_mfma_f32_16x16x32_bf16 v[124:127], v[236:239], v[220:223], v[124:127]
	s_add_i32 s8, s8, 0x10000
	s_add_u32 s0, s0, 0x80
	s_addc_u32 s1, s1, 0
	s_waitcnt lgkmcnt(0)
	s_waitcnt vmcnt(0)
	s_waitcnt vmcnt(0) lgkmcnt(0)
	v_mfma_f32_16x16x32_bf16 v[120:123], v[240:243], v[220:223], v[120:123]
	s_barrier
	v_mfma_f32_16x16x32_bf16 v[60:63], v[244:247], v[220:223], v[60:63]
	v_mfma_f32_16x16x32_bf16 v[56:59], v[248:251], v[220:223], v[56:59]
	v_mfma_f32_16x16x32_bf16 v[116:119], v[236:239], v[224:227], v[116:119]
	v_mfma_f32_16x16x32_bf16 v[112:115], v[240:243], v[224:227], v[112:115]
	v_mfma_f32_16x16x32_bf16 v[48:51], v[244:247], v[224:227], v[48:51]
	v_mfma_f32_16x16x32_bf16 v[44:47], v[248:251], v[224:227], v[44:47]
	v_mfma_f32_16x16x32_bf16 v[92:95], v[236:239], v[212:215], v[92:95]
	v_mfma_f32_16x16x32_bf16 v[88:91], v[240:243], v[212:215], v[88:91]
	v_mfma_f32_16x16x32_bf16 v[24:27], v[244:247], v[212:215], v[24:27]
	v_mfma_f32_16x16x32_bf16 v[20:23], v[248:251], v[212:215], v[20:23]
	v_mfma_f32_16x16x32_bf16 v[84:87], v[236:239], v[216:219], v[84:87]
	v_mfma_f32_16x16x32_bf16 v[80:83], v[240:243], v[216:219], v[80:83]
	v_mfma_f32_16x16x32_bf16 v[16:19], v[244:247], v[216:219], v[16:19]
	v_mfma_f32_16x16x32_bf16 v[12:15], v[248:251], v[216:219], v[12:15]
	v_mfma_f32_16x16x32_bf16 v[76:79], v[236:239], v[204:207], v[76:79]
	v_mfma_f32_16x16x32_bf16 v[72:75], v[240:243], v[204:207], v[72:75]
	v_mfma_f32_16x16x32_bf16 v[8:11], v[244:247], v[204:207], v[8:11]
	v_mfma_f32_16x16x32_bf16 v[4:7], v[248:251], v[204:207], v[4:7]
	v_mfma_f32_16x16x32_bf16 v[68:71], v[236:239], v[208:211], v[68:71]
	v_mfma_f32_16x16x32_bf16 v[64:67], v[240:243], v[208:211], v[64:67]
	v_mfma_f32_16x16x32_bf16 v[0:3], v[244:247], v[208:211], v[0:3]
	v_mfma_f32_16x16x32_bf16 v[52:55], v[248:251], v[208:211], v[52:55]

.LBB0_1567:
	s_or_b64 exec, exec, s[10:11]
	v_cvt_f32_u32_e32 v4, v2
	s_waitcnt vmcnt(0)
	v_readfirstlane_b32 s8, v3
	v_sub_u32_e32 v3, 0, v2
	v_rcp_iflag_f32_e32 v4, v4
	v_add_u32_e32 v5, s8, v1
	v_mul_f32_e32 v4, 0x4f7ffffe, v4
	v_cvt_u32_f32_e32 v4, v4
	v_mul_lo_u32 v1, v3, v4
	v_mul_hi_u32 v1, v4, v1
	v_add_u32_e32 v1, v4, v1
	v_mul_hi_u32 v1, v5, v1
	v_mul_lo_u32 v3, v1, v2
	v_sub_u32_e32 v3, v5, v3
	v_add_u32_e32 v4, 1, v1
	v_cmp_ge_u32_e32 vcc, v3, v2
	s_nop 1
	v_cndmask_b32_e32 v1, v1, v4, vcc
	v_sub_u32_e32 v4, v3, v2
	v_cndmask_b32_e32 v3, v3, v4, vcc
	v_add_u32_e32 v4, 1, v1
	v_cmp_ge_u32_e32 vcc, v3, v2
	v_add_u32_e32 v3, 1, v5
	s_nop 0
	v_cndmask_b32_e32 v1, v1, v4, vcc
	v_mul_lo_u32 v4, v2, v1
	v_add_u32_e32 v2, v4, v2
	v_cmp_ne_u32_e32 vcc, v3, v2
	s_and_saveexec_b64 s[8:9], vcc
	s_xor_b64 s[8:9], exec, s[8:9]
	s_cbranch_execz .LBB0_1581
	s_waitcnt lgkmcnt(0)
	buffer_inv sc1
	v_mov_b32_e32 v0, 0
	v_mov_b32_e32 v1, 10
	s_add_u32 s14, s86, 0xe7b4500
	s_addc_u32 s15, s87, 0
	global_load_dword v0, v0, s[14:15] sc1
	s_waitcnt vmcnt(0)
	v_cmp_eq_u32_e32 vcc, v0, v1
	s_and_saveexec_b64 s[10:11], vcc
	s_cbranch_execz .LBB0_1580
	s_add_u32 s12, s86, 0xe7b1200
	s_addc_u32 s13, s87, 0
	s_mov_b32 s28, 1
	s_mov_b64 s[16:17], 0
	v_mov_b32_e32 v0, 0
	s_branch .LBB0_1571

.LBB0_1629:
	s_or_b64 exec, exec, s[10:11]
	v_cvt_f32_u32_e32 v4, v2
	s_waitcnt vmcnt(0)
	v_readfirstlane_b32 s8, v3
	v_sub_u32_e32 v3, 0, v2
	v_rcp_iflag_f32_e32 v4, v4
	v_add_u32_e32 v5, s8, v1
	v_mul_f32_e32 v4, 0x4f7ffffe, v4
	v_cvt_u32_f32_e32 v4, v4
	v_mul_lo_u32 v1, v3, v4
	v_mul_hi_u32 v1, v4, v1
	v_add_u32_e32 v1, v4, v1
	v_mul_hi_u32 v1, v5, v1
	v_mul_lo_u32 v3, v1, v2
	v_sub_u32_e32 v3, v5, v3
	v_add_u32_e32 v4, 1, v1
	v_cmp_ge_u32_e32 vcc, v3, v2
	s_nop 1
	v_cndmask_b32_e32 v1, v1, v4, vcc
	v_sub_u32_e32 v4, v3, v2
	v_cndmask_b32_e32 v3, v3, v4, vcc
	v_add_u32_e32 v4, 1, v1
	v_cmp_ge_u32_e32 vcc, v3, v2
	v_add_u32_e32 v3, 1, v5
	s_nop 0
	v_cndmask_b32_e32 v1, v1, v4, vcc
	v_mul_lo_u32 v4, v2, v1
	v_add_u32_e32 v2, v4, v2
	v_cmp_ne_u32_e32 vcc, v3, v2
	s_and_saveexec_b64 s[8:9], vcc
	s_xor_b64 s[8:9], exec, s[8:9]
	s_cbranch_execz .LBB0_1643
	s_waitcnt lgkmcnt(0)
	buffer_inv sc1
	v_mov_b32_e32 v0, 0
	v_mov_b32_e32 v1, 11
	s_add_u32 s14, s86, 0xe7b4500
	s_addc_u32 s15, s87, 0
	global_load_dword v0, v0, s[14:15] sc1
	s_waitcnt vmcnt(0)
	v_cmp_eq_u32_e32 vcc, v0, v1
	s_and_saveexec_b64 s[10:11], vcc
	s_cbranch_execz .LBB0_1642
	s_add_u32 s12, s86, 0xe7b1200
	s_addc_u32 s13, s87, 0
	s_mov_b32 s28, 1
	s_mov_b64 s[16:17], 0
	v_mov_b32_e32 v0, 0
	s_branch .LBB0_1633

.LBB0_1766:
	s_or_b64 exec, exec, s[10:11]
	v_cvt_f32_u32_e32 v4, v2
	s_waitcnt vmcnt(0)
	v_readfirstlane_b32 s8, v3
	v_sub_u32_e32 v3, 0, v2
	v_rcp_iflag_f32_e32 v4, v4
	v_add_u32_e32 v5, s8, v1
	v_mul_f32_e32 v4, 0x4f7ffffe, v4
	v_cvt_u32_f32_e32 v4, v4
	v_mul_lo_u32 v1, v3, v4
	v_mul_hi_u32 v1, v4, v1
	v_add_u32_e32 v1, v4, v1
	v_mul_hi_u32 v1, v5, v1
	v_mul_lo_u32 v3, v1, v2
	v_sub_u32_e32 v3, v5, v3
	v_add_u32_e32 v4, 1, v1
	v_cmp_ge_u32_e32 vcc, v3, v2
	s_nop 1
	v_cndmask_b32_e32 v1, v1, v4, vcc
	v_sub_u32_e32 v4, v3, v2
	v_cndmask_b32_e32 v3, v3, v4, vcc
	v_add_u32_e32 v4, 1, v1
	v_cmp_ge_u32_e32 vcc, v3, v2
	v_add_u32_e32 v3, 1, v5
	s_nop 0
	v_cndmask_b32_e32 v1, v1, v4, vcc
	v_mul_lo_u32 v4, v2, v1
	v_add_u32_e32 v2, v4, v2
	v_cmp_ne_u32_e32 vcc, v3, v2
	s_and_saveexec_b64 s[8:9], vcc
	s_xor_b64 s[8:9], exec, s[8:9]
	s_cbranch_execz .LBB0_1780
	s_waitcnt lgkmcnt(0)
	buffer_inv sc1
	v_mov_b32_e32 v0, 0
	v_mov_b32_e32 v1, 12
	s_add_u32 s14, s86, 0xe7b4500
	s_addc_u32 s15, s87, 0
	global_load_dword v0, v0, s[14:15] sc1
	s_waitcnt vmcnt(0)
	v_cmp_eq_u32_e32 vcc, v0, v1
	s_and_saveexec_b64 s[10:11], vcc
	s_cbranch_execz .LBB0_1779
	s_add_u32 s12, s86, 0xe7b1200
	s_addc_u32 s13, s87, 0
	s_mov_b32 s28, 1
	s_mov_b64 s[16:17], 0
	v_mov_b32_e32 v0, 0
	s_branch .LBB0_1770

.LBB0_1821:
	s_or_b64 exec, exec, s[10:11]
	v_cvt_f32_u32_e32 v4, v2
	s_waitcnt vmcnt(0)
	v_readfirstlane_b32 s8, v3
	v_sub_u32_e32 v3, 0, v2
	v_rcp_iflag_f32_e32 v4, v4
	v_add_u32_e32 v5, s8, v1
	v_mul_f32_e32 v4, 0x4f7ffffe, v4
	v_cvt_u32_f32_e32 v4, v4
	v_mul_lo_u32 v1, v3, v4
	v_mul_hi_u32 v1, v4, v1
	v_add_u32_e32 v1, v4, v1
	v_mul_hi_u32 v1, v5, v1
	v_mul_lo_u32 v3, v1, v2
	v_sub_u32_e32 v3, v5, v3
	v_add_u32_e32 v4, 1, v1
	v_cmp_ge_u32_e32 vcc, v3, v2
	s_nop 1
	v_cndmask_b32_e32 v1, v1, v4, vcc
	v_sub_u32_e32 v4, v3, v2
	v_cndmask_b32_e32 v3, v3, v4, vcc
	v_add_u32_e32 v4, 1, v1
	v_cmp_ge_u32_e32 vcc, v3, v2
	v_add_u32_e32 v3, 1, v5
	s_nop 0
	v_cndmask_b32_e32 v1, v1, v4, vcc
	v_mul_lo_u32 v4, v2, v1
	v_add_u32_e32 v2, v4, v2
	v_cmp_ne_u32_e32 vcc, v3, v2
	s_and_saveexec_b64 s[8:9], vcc
	s_xor_b64 s[8:9], exec, s[8:9]
	s_cbranch_execz .LBB0_1835
	s_waitcnt lgkmcnt(0)
	buffer_inv sc1
	v_mov_b32_e32 v0, 0
	v_mov_b32_e32 v1, 13
	s_add_u32 s14, s86, 0xe7b4500
	s_addc_u32 s15, s87, 0
	global_load_dword v0, v0, s[14:15] sc1
	s_waitcnt vmcnt(0)
	v_cmp_eq_u32_e32 vcc, v0, v1
	s_and_saveexec_b64 s[10:11], vcc
	s_cbranch_execz .LBB0_1834
	s_add_u32 s12, s86, 0xe7b1200
	s_addc_u32 s13, s87, 0
	s_mov_b32 s28, 1
	s_mov_b64 s[16:17], 0
	v_mov_b32_e32 v0, 0
	s_branch .LBB0_1825

.LBB0_1857:
	s_ashr_i32 s0, s24, 31
	s_lshr_b32 s0, s0, 26
	s_add_i32 s0, s24, s0
	v_readfirstlane_b32 s13, v128
	s_ashr_i32 s14, s0, 6
	s_andn2_b32 s0, s0, 63
	s_lshr_b32 s15, s13, 1
	s_sub_i32 s12, s24, s0
	s_and_b32 s15, s15, 0x1ffff80
	s_lshl_b32 s0, s12, 19
	v_or_b32_e32 v5, s15, v189
	s_and_b32 s15, s13, 0xc0
	s_lshl_b32 s13, s13, 4
	v_add_u32_e32 v2, s0, v136
	v_lshlrev_b32_e32 v149, 7, v5
	v_or_b32_e32 v5, s15, v189
	s_and_b32 s13, s13, 0x7ffffc00
	v_add_u32_e32 v0, s0, v140
	v_lshl_or_b32 v153, v5, 7, v133
	v_and_b32_e32 v5, 0xfffff870, v2
	s_mov_b32 m0, s13
	v_add_u32_e32 v1, s0, v142
	global_load_lds_dwordx4 v5, s[86:87]
	v_and_b32_e32 v0, 0xfffff870, v0
	s_add_i32 m0, s13, 0x2000
	s_lshl_b32 s1, s14, 19
	v_add_u32_e32 v3, s0, v144
	global_load_lds_dwordx4 v0, s[86:87]
	v_and_b32_e32 v0, 0xfffff870, v1
	s_add_i32 m0, s13, 0x4000
	s_add_i32 s10, s1, 0x1700000
	global_load_lds_dwordx4 v0, s[86:87]
	v_and_b32_e32 v0, 0xfffff870, v3
	s_add_i32 m0, s13, 0x6000
	s_add_i32 s15, s13, 0x8000
	global_load_lds_dwordx4 v0, s[86:87]
	v_or_b32_e32 v0, s10, v146
	v_mov_b32_e32 v1, v147
	v_lshl_add_u64 v[0:1], s[86:87], 0, v[0:1]
	s_mov_b32 m0, s15
	v_add_u32_e32 v4, s1, v152
	global_load_lds_dwordx4 v[0:1], off
	v_or_b32_e32 v0, s10, v148
	v_mov_b32_e32 v1, v129
	v_lshl_add_u64 v[0:1], s[86:87], 0, v[0:1]
	s_add_i32 m0, s13, 0xa000
	v_and_b32_e32 v138, -16, v2
	global_load_lds_dwordx4 v[0:1], off
	v_or_b32_e32 v0, s10, v150
	v_mov_b32_e32 v1, v131
	v_lshl_add_u64 v[0:1], s[86:87], 0, v[0:1]
	s_add_i32 m0, s13, 0xc000
	v_lshl_add_u64 v[170:171], s[8:9], 0, v[138:139]
	global_load_lds_dwordx4 v[0:1], off
	v_and_or_b32 v0, v4, s17, v134
	v_mov_b32_e32 v1, v135
	v_lshl_add_u64 v[0:1], s[86:87], 0, v[0:1]
	s_add_i32 m0, s13, 0xe000
	v_lshl_add_u64 v[178:179], v[160:161], 0, s[10:11]
	global_load_lds_dwordx4 v[0:1], off
	v_add_u32_e32 v0, s0, v154
	v_and_b32_e32 v138, -16, v0
	v_add_u32_e32 v0, s0, v156
	v_lshl_add_u64 v[172:173], s[8:9], 0, v[138:139]
	v_and_b32_e32 v138, -16, v0
	v_add_u32_e32 v0, s0, v158
	s_waitcnt vmcnt(0)
	v_lshl_add_u64 v[174:175], s[8:9], 0, v[138:139]
	v_and_b32_e32 v138, -16, v0
	v_add_u32_e32 v0, s1, v168
	v_lshl_add_u64 v[176:177], s[8:9], 0, v[138:139]
	v_and_b32_e32 v138, 0xfffff800, v0
	v_lshl_add_u64 v[180:181], v[162:163], 0, s[10:11]
	v_lshl_add_u64 v[182:183], v[164:165], 0, s[10:11]
	v_lshl_add_u64 v[184:185], v[166:167], 0, v[138:139]
	s_mov_b64 s[0:1], 0
	s_mov_b32 s10, 0
	s_mov_b32 s15, 0
	v_mov_b32_e32 v56, 0
	v_mov_b32_e32 v57, v139
	v_mov_b32_e32 v58, v139
	v_mov_b32_e32 v59, v139
	v_mov_b32_e32 v52, 0
	v_mov_b32_e32 v53, v139
	v_mov_b32_e32 v54, v139
	v_mov_b32_e32 v55, v139
	s_waitcnt vmcnt(0)
	v_mov_b32_e32 v64, 0
	v_mov_b32_e32 v65, v139
	v_mov_b32_e32 v66, v139
	v_mov_b32_e32 v67, v139
	v_mov_b32_e32 v68, 0
	v_mov_b32_e32 v69, v139
	v_mov_b32_e32 v70, v139
	v_mov_b32_e32 v71, v139
	v_mov_b32_e32 v0, 0
	v_mov_b32_e32 v1, v139
	v_mov_b32_e32 v2, v139
	v_mov_b32_e32 v3, v139
	v_mov_b32_e32 v4, 0
	v_mov_b32_e32 v5, v139
	v_mov_b32_e32 v6, v139
	v_mov_b32_e32 v7, v139
	v_mov_b32_e32 v72, 0
	v_mov_b32_e32 v73, v139
	v_mov_b32_e32 v74, v139
	v_mov_b32_e32 v75, v139
	v_mov_b32_e32 v76, 0
	v_mov_b32_e32 v77, v139
	v_mov_b32_e32 v78, v139
	v_mov_b32_e32 v79, v139
	v_mov_b32_e32 v8, 0
	v_mov_b32_e32 v9, v139
	v_mov_b32_e32 v10, v139
	v_mov_b32_e32 v11, v139
	v_mov_b32_e32 v12, 0
	v_mov_b32_e32 v13, v139
	v_mov_b32_e32 v14, v139
	v_mov_b32_e32 v15, v139
	v_mov_b32_e32 v80, 0
	v_mov_b32_e32 v81, v139
	v_mov_b32_e32 v82, v139
	v_mov_b32_e32 v83, v139
	v_mov_b32_e32 v84, 0
	v_mov_b32_e32 v85, v139
	v_mov_b32_e32 v86, v139
	v_mov_b32_e32 v87, v139
	v_mov_b32_e32 v16, 0
	v_mov_b32_e32 v17, v139
	v_mov_b32_e32 v18, v139
	v_mov_b32_e32 v19, v139
	v_mov_b32_e32 v20, 0
	v_mov_b32_e32 v21, v139
	v_mov_b32_e32 v22, v139
	v_mov_b32_e32 v23, v139
	v_mov_b32_e32 v88, 0
	v_mov_b32_e32 v89, v139
	v_mov_b32_e32 v90, v139
	v_mov_b32_e32 v91, v139
	v_mov_b32_e32 v92, 0
	v_mov_b32_e32 v93, v139
	v_mov_b32_e32 v94, v139
	v_mov_b32_e32 v95, v139
	v_mov_b32_e32 v24, 0
	v_mov_b32_e32 v25, v139
	v_mov_b32_e32 v26, v139
	v_mov_b32_e32 v27, v139
	v_mov_b32_e32 v28, 0
	v_mov_b32_e32 v29, v139
	v_mov_b32_e32 v30, v139
	v_mov_b32_e32 v31, v139
	v_mov_b32_e32 v96, 0
	v_mov_b32_e32 v97, v139
	v_mov_b32_e32 v98, v139
	v_mov_b32_e32 v99, v139
	v_mov_b32_e32 v100, 0
	v_mov_b32_e32 v101, v139
	v_mov_b32_e32 v102, v139
	v_mov_b32_e32 v103, v139
	v_mov_b32_e32 v32, 0
	v_mov_b32_e32 v33, v139
	v_mov_b32_e32 v34, v139
	v_mov_b32_e32 v35, v139
	v_mov_b32_e32 v36, 0
	v_mov_b32_e32 v37, v139
	v_mov_b32_e32 v38, v139
	v_mov_b32_e32 v39, v139
	v_mov_b32_e32 v104, 0
	v_mov_b32_e32 v105, v139
	v_mov_b32_e32 v106, v139
	v_mov_b32_e32 v107, v139
	v_mov_b32_e32 v108, 0
	v_mov_b32_e32 v109, v139
	v_mov_b32_e32 v110, v139
	v_mov_b32_e32 v111, v139
	v_mov_b32_e32 v40, 0
	v_mov_b32_e32 v41, v139
	v_mov_b32_e32 v42, v139
	v_mov_b32_e32 v43, v139
	v_mov_b32_e32 v44, 0
	v_mov_b32_e32 v45, v139
	v_mov_b32_e32 v46, v139
	v_mov_b32_e32 v47, v139
	v_mov_b32_e32 v112, 0
	v_mov_b32_e32 v113, v139
	v_mov_b32_e32 v114, v139
	v_mov_b32_e32 v115, v139
	v_mov_b32_e32 v116, 0
	v_mov_b32_e32 v117, v139
	v_mov_b32_e32 v118, v139
	v_mov_b32_e32 v119, v139
	v_mov_b32_e32 v48, 0
	v_mov_b32_e32 v49, v139
	v_mov_b32_e32 v50, v139
	v_mov_b32_e32 v51, v139
	v_mov_b32_e32 v60, 0
	v_mov_b32_e32 v61, v139
	v_mov_b32_e32 v62, v139
	v_mov_b32_e32 v63, v139
	v_mov_b32_e32 v120, 0
	v_mov_b32_e32 v121, v139
	v_mov_b32_e32 v122, v139
	v_mov_b32_e32 v123, v139
	v_mov_b32_e32 v124, 0
	v_mov_b32_e32 v125, v139
	v_mov_b32_e32 v126, v139
	v_mov_b32_e32 v127, v139
	s_waitcnt lgkmcnt(0)
	s_barrier
	s_and_b32 s25, s10, 0x10000
	s_xor_b32 s26, s25, 0x10000
	s_add_i32 s26, s13, s26
	s_add_i32 s27, s26, 0x8000
	s_mov_b32 m0, s26
	v_lshl_add_u64 v[254:255], v[170:171], 0, s[0:1]
	global_load_lds_dwordx4 v[254:255], off
	s_add_i32 m0, s26, 0x2000
	v_lshl_add_u64 v[254:255], v[172:173], 0, s[0:1]
	global_load_lds_dwordx4 v[254:255], off
	s_add_i32 m0, s26, 0x4000
	v_lshl_add_u64 v[254:255], v[174:175], 0, s[0:1]
	global_load_lds_dwordx4 v[254:255], off
	s_add_i32 m0, s26, 0x6000
	v_lshl_add_u64 v[254:255], v[176:177], 0, s[0:1]
	global_load_lds_dwordx4 v[254:255], off
	s_mov_b32 m0, s27
	v_lshl_add_u64 v[254:255], v[178:179], 0, s[0:1]
	global_load_lds_dwordx4 v[254:255], off
	s_add_i32 m0, s26, 0xa000
	v_lshl_add_u64 v[254:255], v[180:181], 0, s[0:1]
	global_load_lds_dwordx4 v[254:255], off
	s_add_i32 m0, s26, 0xc000
	v_lshl_add_u64 v[254:255], v[182:183], 0, s[0:1]
	global_load_lds_dwordx4 v[254:255], off
	s_add_i32 m0, s26, 0xe000
	v_lshl_add_u64 v[254:255], v[184:185], 0, s[0:1]
	global_load_lds_dwordx4 v[254:255], off
	v_add3_u32 v253, s25, v149, v137
	ds_read_b128 v[224:227], v253 offset:0x1000
	ds_read_b128 v[228:231], v253 offset:0x1800
	ds_read_b128 v[216:219], v253 offset:0
	v_add3_u32 v253, s25, v153, v137
	ds_read_b128 v[200:203], v253 offset:0
	v_add3_u32 v253, s25, v149, v137
	ds_read_b128 v[220:223], v253 offset:0x800
	v_add3_u32 v253, s25, v153, v137
	ds_read_b128 v[204:207], v253 offset:0x800
	ds_read_b128 v[208:211], v253 offset:0x1000
	ds_read_b128 v[212:215], v253 offset:0x1800
.Lgout1_body:
	v_add_u32_e32 v169, s25, v153
	v_add_u32_e32 v138, s25, v149
	v_add_u32_e32 v159, v138, v137
	v_add_u32_e32 v169, v169, v145
	s_waitcnt lgkmcnt(4)
	v_add_u32_e32 v138, v138, v145
	v_mfma_f32_16x16x32_bf16 v[124:127], v[200:203], v[216:219], v[124:127]
	s_waitcnt lgkmcnt(2)
	v_mfma_f32_16x16x32_bf16 v[120:123], v[204:207], v[216:219], v[120:123]
	s_waitcnt lgkmcnt(1)
	v_mfma_f32_16x16x32_bf16 v[60:63], v[208:211], v[216:219], v[60:63]
	s_waitcnt lgkmcnt(0)
	v_mfma_f32_16x16x32_bf16 v[48:51], v[212:215], v[216:219], v[48:51]
	ds_read_b128 v[216:219], v159 offset:0x2000
	v_mfma_f32_16x16x32_bf16 v[116:119], v[200:203], v[220:223], v[116:119]
	v_mfma_f32_16x16x32_bf16 v[112:115], v[204:207], v[220:223], v[112:115]
	v_mfma_f32_16x16x32_bf16 v[44:47], v[208:211], v[220:223], v[44:47]
	v_mfma_f32_16x16x32_bf16 v[40:43], v[212:215], v[220:223], v[40:43]
	ds_read_b128 v[220:223], v159 offset:0x2800
	s_waitcnt lgkmcnt(2)
	s_nop 0
	v_mfma_f32_16x16x32_bf16 v[108:111], v[200:203], v[224:227], v[108:111]
	v_mfma_f32_16x16x32_bf16 v[104:107], v[204:207], v[224:227], v[104:107]
	v_mfma_f32_16x16x32_bf16 v[36:39], v[208:211], v[224:227], v[36:39]
	v_mfma_f32_16x16x32_bf16 v[32:35], v[212:215], v[224:227], v[32:35]
	ds_read_b128 v[224:227], v159 offset:0x3000
	v_mfma_f32_16x16x32_bf16 v[100:103], v[200:203], v[228:231], v[100:103]
	v_mfma_f32_16x16x32_bf16 v[96:99], v[204:207], v[228:231], v[96:99]
	v_mfma_f32_16x16x32_bf16 v[28:31], v[208:211], v[228:231], v[28:31]
	v_mfma_f32_16x16x32_bf16 v[24:27], v[212:215], v[228:231], v[24:27]
	ds_read_b128 v[228:231], v159 offset:0x3800
	ds_read_b128 v[232:235], v169 offset:0
	ds_read_b128 v[236:239], v169 offset:0x800
	ds_read_b128 v[240:243], v169 offset:0x1000
	ds_read_b128 v[244:247], v169 offset:0x1800
	s_waitcnt lgkmcnt(6)
	s_nop 0
	v_mfma_f32_16x16x32_bf16 v[92:95], v[200:203], v[216:219], v[92:95]
	v_mfma_f32_16x16x32_bf16 v[88:91], v[204:207], v[216:219], v[88:91]
	v_mfma_f32_16x16x32_bf16 v[20:23], v[208:211], v[216:219], v[20:23]
	v_mfma_f32_16x16x32_bf16 v[16:19], v[212:215], v[216:219], v[16:19]
	ds_read_b128 v[216:219], v138 offset:0
	v_mfma_f32_16x16x32_bf16 v[84:87], v[200:203], v[220:223], v[84:87]
	v_mfma_f32_16x16x32_bf16 v[80:83], v[204:207], v[220:223], v[80:83]
	v_mfma_f32_16x16x32_bf16 v[12:15], v[208:211], v[220:223], v[12:15]
	v_mfma_f32_16x16x32_bf16 v[8:11], v[212:215], v[220:223], v[8:11]
	ds_read_b128 v[220:223], v138 offset:0x800
	s_waitcnt lgkmcnt(6)
	s_nop 0
	v_mfma_f32_16x16x32_bf16 v[76:79], v[200:203], v[224:227], v[76:79]
	v_mfma_f32_16x16x32_bf16 v[68:71], v[200:203], v[228:231], v[68:71]
	ds_read_b128 v[200:203], v138 offset:0x1000
	v_mfma_f32_16x16x32_bf16 v[72:75], v[204:207], v[224:227], v[72:75]
	v_mfma_f32_16x16x32_bf16 v[64:67], v[204:207], v[228:231], v[64:67]
	ds_read_b128 v[204:207], v138 offset:0x1800
	s_waitcnt lgkmcnt(2)
	v_mfma_f32_16x16x32_bf16 v[4:7], v[208:211], v[224:227], v[4:7]
	v_mfma_f32_16x16x32_bf16 v[52:55], v[208:211], v[228:231], v[52:55]
	ds_read_b128 v[208:211], v138 offset:0x2000
	v_mfma_f32_16x16x32_bf16 v[0:3], v[212:215], v[224:227], v[0:3]
	v_mfma_f32_16x16x32_bf16 v[56:59], v[212:215], v[228:231], v[56:59]
	ds_read_b128 v[212:215], v138 offset:0x2800
	s_waitcnt lgkmcnt(2)
	s_nop 0
	v_mfma_f32_16x16x32_bf16 v[108:111], v[232:235], v[200:203], v[108:111]
	v_mfma_f32_16x16x32_bf16 v[104:107], v[236:239], v[200:203], v[104:107]
	v_mfma_f32_16x16x32_bf16 v[36:39], v[240:243], v[200:203], v[36:39]
	v_mfma_f32_16x16x32_bf16 v[32:35], v[244:247], v[200:203], v[32:35]
	ds_read_b128 v[200:203], v138 offset:0x3000
	v_mfma_f32_16x16x32_bf16 v[100:103], v[232:235], v[204:207], v[100:103]
	v_mfma_f32_16x16x32_bf16 v[96:99], v[236:239], v[204:207], v[96:99]
	v_mfma_f32_16x16x32_bf16 v[28:31], v[240:243], v[204:207], v[28:31]
	v_mfma_f32_16x16x32_bf16 v[24:27], v[244:247], v[204:207], v[24:27]
	ds_read_b128 v[204:207], v138 offset:0x3800
	s_waitcnt lgkmcnt(2)
	v_mfma_f32_16x16x32_bf16 v[124:127], v[232:235], v[216:219], v[124:127]
	s_add_i32 s10, s10, 0x10000
	s_add_u32 s0, s0, 0x80
	s_addc_u32 s1, s1, 0
	s_add_i32 s15, s15, 1
	s_waitcnt lgkmcnt(0)
	s_waitcnt vmcnt(0)
	s_waitcnt vmcnt(0) lgkmcnt(0)
	v_mfma_f32_16x16x32_bf16 v[120:123], v[236:239], v[216:219], v[120:123]
	s_barrier
	s_cmp_gt_u32 s15, 14
	s_cbranch_scc1 .Lgout1_nodma
	s_and_b32 s25, s10, 0x10000
	s_xor_b32 s26, s25, 0x10000
	s_add_i32 s26, s13, s26
	s_add_i32 s27, s26, 0x8000
	v_add3_u32 v253, s25, v149, v137
	ds_read_b128 v[224:227], v253 offset:0x1000
	ds_read_b128 v[228:231], v253 offset:0x1800
	v_mfma_f32_16x16x32_bf16 v[60:63], v[240:243], v[216:219], v[60:63]
	s_mov_b32 m0, s26
	v_lshl_add_u64 v[254:255], v[170:171], 0, s[0:1]
	global_load_lds_dwordx4 v[254:255], off
	v_mfma_f32_16x16x32_bf16 v[48:51], v[244:247], v[216:219], v[48:51]
	ds_read_b128 v[216:219], v253 offset:0
	v_mfma_f32_16x16x32_bf16 v[76:79], v[232:235], v[200:203], v[76:79]
	s_add_i32 m0, s26, 0x2000
	v_lshl_add_u64 v[254:255], v[172:173], 0, s[0:1]
	global_load_lds_dwordx4 v[254:255], off
	v_mfma_f32_16x16x32_bf16 v[72:75], v[236:239], v[200:203], v[72:75]
	v_mfma_f32_16x16x32_bf16 v[4:7], v[240:243], v[200:203], v[4:7]
	s_add_i32 m0, s26, 0x4000
	v_lshl_add_u64 v[254:255], v[174:175], 0, s[0:1]
	global_load_lds_dwordx4 v[254:255], off
	v_mfma_f32_16x16x32_bf16 v[0:3], v[244:247], v[200:203], v[0:3]
	v_add3_u32 v253, s25, v153, v137
	ds_read_b128 v[200:203], v253 offset:0
	v_mfma_f32_16x16x32_bf16 v[116:119], v[232:235], v[220:223], v[116:119]
	s_add_i32 m0, s26, 0x6000
	v_lshl_add_u64 v[254:255], v[176:177], 0, s[0:1]
	global_load_lds_dwordx4 v[254:255], off
	v_mfma_f32_16x16x32_bf16 v[112:115], v[236:239], v[220:223], v[112:115]
	v_mfma_f32_16x16x32_bf16 v[44:47], v[240:243], v[220:223], v[44:47]
	s_mov_b32 m0, s27
	v_lshl_add_u64 v[254:255], v[178:179], 0, s[0:1]
	global_load_lds_dwordx4 v[254:255], off
	v_mfma_f32_16x16x32_bf16 v[40:43], v[244:247], v[220:223], v[40:43]
	v_add3_u32 v253, s25, v149, v137
	ds_read_b128 v[220:223], v253 offset:0x800
	v_mfma_f32_16x16x32_bf16 v[68:71], v[232:235], v[204:207], v[68:71]
	s_add_i32 m0, s26, 0xa000
	v_lshl_add_u64 v[254:255], v[180:181], 0, s[0:1]
	global_load_lds_dwordx4 v[254:255], off
	v_mfma_f32_16x16x32_bf16 v[64:67], v[236:239], v[204:207], v[64:67]
	v_mfma_f32_16x16x32_bf16 v[52:55], v[240:243], v[204:207], v[52:55]
	s_add_i32 m0, s26, 0xc000
	v_lshl_add_u64 v[254:255], v[182:183], 0, s[0:1]
	global_load_lds_dwordx4 v[254:255], off
	v_mfma_f32_16x16x32_bf16 v[56:59], v[244:247], v[204:207], v[56:59]
	v_add3_u32 v253, s25, v153, v137
	ds_read_b128 v[204:207], v253 offset:0x800
	v_mfma_f32_16x16x32_bf16 v[92:95], v[232:235], v[208:211], v[92:95]
	s_add_i32 m0, s26, 0xe000
	v_lshl_add_u64 v[254:255], v[184:185], 0, s[0:1]
	global_load_lds_dwordx4 v[254:255], off
	v_mfma_f32_16x16x32_bf16 v[88:91], v[236:239], v[208:211], v[88:91]
	v_mfma_f32_16x16x32_bf16 v[20:23], v[240:243], v[208:211], v[20:23]
	v_mfma_f32_16x16x32_bf16 v[16:19], v[244:247], v[208:211], v[16:19]
	ds_read_b128 v[208:211], v253 offset:0x1000
	v_mfma_f32_16x16x32_bf16 v[84:87], v[232:235], v[212:215], v[84:87]
	v_mfma_f32_16x16x32_bf16 v[80:83], v[236:239], v[212:215], v[80:83]
	v_mfma_f32_16x16x32_bf16 v[12:15], v[240:243], v[212:215], v[12:15]
	v_mfma_f32_16x16x32_bf16 v[8:11], v[244:247], v[212:215], v[8:11]
	ds_read_b128 v[212:215], v253 offset:0x1800
	s_branch .Lgout1_body
.Lgout1_nodma:
	s_and_b32 s25, s10, 0x10000
	v_add3_u32 v253, s25, v149, v137
	ds_read_b128 v[224:227], v253 offset:0x1000
	ds_read_b128 v[228:231], v253 offset:0x1800
	v_mfma_f32_16x16x32_bf16 v[60:63], v[240:243], v[216:219], v[60:63]
	v_mfma_f32_16x16x32_bf16 v[48:51], v[244:247], v[216:219], v[48:51]
	ds_read_b128 v[216:219], v253 offset:0
	v_mfma_f32_16x16x32_bf16 v[76:79], v[232:235], v[200:203], v[76:79]
	v_mfma_f32_16x16x32_bf16 v[72:75], v[236:239], v[200:203], v[72:75]
	v_mfma_f32_16x16x32_bf16 v[4:7], v[240:243], v[200:203], v[4:7]
	v_mfma_f32_16x16x32_bf16 v[0:3], v[244:247], v[200:203], v[0:3]
	v_add3_u32 v253, s25, v153, v137
	ds_read_b128 v[200:203], v253 offset:0
	v_mfma_f32_16x16x32_bf16 v[116:119], v[232:235], v[220:223], v[116:119]
	v_mfma_f32_16x16x32_bf16 v[112:115], v[236:239], v[220:223], v[112:115]
	v_mfma_f32_16x16x32_bf16 v[44:47], v[240:243], v[220:223], v[44:47]
	v_mfma_f32_16x16x32_bf16 v[40:43], v[244:247], v[220:223], v[40:43]
	v_add3_u32 v253, s25, v149, v137
	ds_read_b128 v[220:223], v253 offset:0x800
	v_mfma_f32_16x16x32_bf16 v[68:71], v[232:235], v[204:207], v[68:71]
	v_mfma_f32_16x16x32_bf16 v[64:67], v[236:239], v[204:207], v[64:67]
	v_mfma_f32_16x16x32_bf16 v[52:55], v[240:243], v[204:207], v[52:55]
	v_mfma_f32_16x16x32_bf16 v[56:59], v[244:247], v[204:207], v[56:59]
	v_add3_u32 v253, s25, v153, v137
	ds_read_b128 v[204:207], v253 offset:0x800
	v_mfma_f32_16x16x32_bf16 v[92:95], v[232:235], v[208:211], v[92:95]
	v_mfma_f32_16x16x32_bf16 v[88:91], v[236:239], v[208:211], v[88:91]
	v_mfma_f32_16x16x32_bf16 v[20:23], v[240:243], v[208:211], v[20:23]
	v_mfma_f32_16x16x32_bf16 v[16:19], v[244:247], v[208:211], v[16:19]
	ds_read_b128 v[208:211], v253 offset:0x1000
	v_mfma_f32_16x16x32_bf16 v[84:87], v[232:235], v[212:215], v[84:87]
	v_mfma_f32_16x16x32_bf16 v[80:83], v[236:239], v[212:215], v[80:83]
	v_mfma_f32_16x16x32_bf16 v[12:15], v[240:243], v[212:215], v[12:15]
	v_mfma_f32_16x16x32_bf16 v[8:11], v[244:247], v[212:215], v[8:11]
	ds_read_b128 v[212:215], v253 offset:0x1800
	v_add_u32_e32 v169, s25, v153
	v_add_u32_e32 v138, s25, v149
	v_add_u32_e32 v159, v138, v137
	v_add_u32_e32 v169, v169, v145
	s_waitcnt lgkmcnt(4)
	v_add_u32_e32 v138, v138, v145
	v_mfma_f32_16x16x32_bf16 v[124:127], v[200:203], v[216:219], v[124:127]
	s_waitcnt lgkmcnt(2)
	v_mfma_f32_16x16x32_bf16 v[120:123], v[204:207], v[216:219], v[120:123]
	s_waitcnt lgkmcnt(1)
	v_mfma_f32_16x16x32_bf16 v[60:63], v[208:211], v[216:219], v[60:63]
	s_waitcnt lgkmcnt(0)
	v_mfma_f32_16x16x32_bf16 v[48:51], v[212:215], v[216:219], v[48:51]
	ds_read_b128 v[216:219], v159 offset:0x2000
	v_mfma_f32_16x16x32_bf16 v[116:119], v[200:203], v[220:223], v[116:119]
	v_mfma_f32_16x16x32_bf16 v[112:115], v[204:207], v[220:223], v[112:115]
	v_mfma_f32_16x16x32_bf16 v[44:47], v[208:211], v[220:223], v[44:47]
	v_mfma_f32_16x16x32_bf16 v[40:43], v[212:215], v[220:223], v[40:43]
	ds_read_b128 v[220:223], v159 offset:0x2800
	s_waitcnt lgkmcnt(2)
	s_nop 0
	v_mfma_f32_16x16x32_bf16 v[108:111], v[200:203], v[224:227], v[108:111]
	v_mfma_f32_16x16x32_bf16 v[104:107], v[204:207], v[224:227], v[104:107]
	v_mfma_f32_16x16x32_bf16 v[36:39], v[208:211], v[224:227], v[36:39]
	v_mfma_f32_16x16x32_bf16 v[32:35], v[212:215], v[224:227], v[32:35]
	ds_read_b128 v[224:227], v159 offset:0x3000
	v_mfma_f32_16x16x32_bf16 v[100:103], v[200:203], v[228:231], v[100:103]
	v_mfma_f32_16x16x32_bf16 v[96:99], v[204:207], v[228:231], v[96:99]
	v_mfma_f32_16x16x32_bf16 v[28:31], v[208:211], v[228:231], v[28:31]
	v_mfma_f32_16x16x32_bf16 v[24:27], v[212:215], v[228:231], v[24:27]
	ds_read_b128 v[228:231], v159 offset:0x3800
	ds_read_b128 v[232:235], v169 offset:0
	ds_read_b128 v[236:239], v169 offset:0x800
	ds_read_b128 v[240:243], v169 offset:0x1000
	ds_read_b128 v[244:247], v169 offset:0x1800
	s_waitcnt lgkmcnt(6)
	s_nop 0
	v_mfma_f32_16x16x32_bf16 v[92:95], v[200:203], v[216:219], v[92:95]
	v_mfma_f32_16x16x32_bf16 v[88:91], v[204:207], v[216:219], v[88:91]
	v_mfma_f32_16x16x32_bf16 v[20:23], v[208:211], v[216:219], v[20:23]
	v_mfma_f32_16x16x32_bf16 v[16:19], v[212:215], v[216:219], v[16:19]
	ds_read_b128 v[216:219], v138 offset:0
	v_mfma_f32_16x16x32_bf16 v[84:87], v[200:203], v[220:223], v[84:87]
	v_mfma_f32_16x16x32_bf16 v[80:83], v[204:207], v[220:223], v[80:83]
	v_mfma_f32_16x16x32_bf16 v[12:15], v[208:211], v[220:223], v[12:15]
	v_mfma_f32_16x16x32_bf16 v[8:11], v[212:215], v[220:223], v[8:11]
	ds_read_b128 v[220:223], v138 offset:0x800
	s_waitcnt lgkmcnt(6)
	s_nop 0
	v_mfma_f32_16x16x32_bf16 v[76:79], v[200:203], v[224:227], v[76:79]
	v_mfma_f32_16x16x32_bf16 v[68:71], v[200:203], v[228:231], v[68:71]
	ds_read_b128 v[200:203], v138 offset:0x1000
	v_mfma_f32_16x16x32_bf16 v[72:75], v[204:207], v[224:227], v[72:75]
	v_mfma_f32_16x16x32_bf16 v[64:67], v[204:207], v[228:231], v[64:67]
	ds_read_b128 v[204:207], v138 offset:0x1800
	s_waitcnt lgkmcnt(2)
	v_mfma_f32_16x16x32_bf16 v[4:7], v[208:211], v[224:227], v[4:7]
	v_mfma_f32_16x16x32_bf16 v[52:55], v[208:211], v[228:231], v[52:55]
	ds_read_b128 v[208:211], v138 offset:0x2000
	v_mfma_f32_16x16x32_bf16 v[0:3], v[212:215], v[224:227], v[0:3]
	v_mfma_f32_16x16x32_bf16 v[56:59], v[212:215], v[228:231], v[56:59]
	ds_read_b128 v[212:215], v138 offset:0x2800
	s_waitcnt lgkmcnt(2)
	s_nop 0
	v_mfma_f32_16x16x32_bf16 v[108:111], v[232:235], v[200:203], v[108:111]
	v_mfma_f32_16x16x32_bf16 v[104:107], v[236:239], v[200:203], v[104:107]
	v_mfma_f32_16x16x32_bf16 v[36:39], v[240:243], v[200:203], v[36:39]
	v_mfma_f32_16x16x32_bf16 v[32:35], v[244:247], v[200:203], v[32:35]
	ds_read_b128 v[200:203], v138 offset:0x3000
	v_mfma_f32_16x16x32_bf16 v[100:103], v[232:235], v[204:207], v[100:103]
	v_mfma_f32_16x16x32_bf16 v[96:99], v[236:239], v[204:207], v[96:99]
	v_mfma_f32_16x16x32_bf16 v[28:31], v[240:243], v[204:207], v[28:31]
	v_mfma_f32_16x16x32_bf16 v[24:27], v[244:247], v[204:207], v[24:27]
	ds_read_b128 v[204:207], v138 offset:0x3800
	s_waitcnt lgkmcnt(2)
	v_mfma_f32_16x16x32_bf16 v[124:127], v[232:235], v[216:219], v[124:127]
	s_add_i32 s10, s10, 0x10000
	s_add_u32 s0, s0, 0x80
	s_addc_u32 s1, s1, 0
	s_add_i32 s15, s15, 1
	s_waitcnt lgkmcnt(0)
	s_waitcnt vmcnt(0)
	s_waitcnt vmcnt(0) lgkmcnt(0)
	v_mfma_f32_16x16x32_bf16 v[120:123], v[236:239], v[216:219], v[120:123]
	s_barrier
	v_mfma_f32_16x16x32_bf16 v[60:63], v[240:243], v[216:219], v[60:63]
	v_mfma_f32_16x16x32_bf16 v[48:51], v[244:247], v[216:219], v[48:51]
	v_mfma_f32_16x16x32_bf16 v[116:119], v[232:235], v[220:223], v[116:119]
	v_mfma_f32_16x16x32_bf16 v[112:115], v[236:239], v[220:223], v[112:115]
	v_mfma_f32_16x16x32_bf16 v[44:47], v[240:243], v[220:223], v[44:47]
	v_mfma_f32_16x16x32_bf16 v[40:43], v[244:247], v[220:223], v[40:43]
	v_mfma_f32_16x16x32_bf16 v[92:95], v[232:235], v[208:211], v[92:95]
	v_mfma_f32_16x16x32_bf16 v[88:91], v[236:239], v[208:211], v[88:91]
	v_mfma_f32_16x16x32_bf16 v[20:23], v[240:243], v[208:211], v[20:23]
	v_mfma_f32_16x16x32_bf16 v[16:19], v[244:247], v[208:211], v[16:19]
	v_mfma_f32_16x16x32_bf16 v[84:87], v[232:235], v[212:215], v[84:87]
	v_mfma_f32_16x16x32_bf16 v[80:83], v[236:239], v[212:215], v[80:83]
	v_mfma_f32_16x16x32_bf16 v[12:15], v[240:243], v[212:215], v[12:15]
	v_mfma_f32_16x16x32_bf16 v[8:11], v[244:247], v[212:215], v[8:11]
	v_mfma_f32_16x16x32_bf16 v[76:79], v[232:235], v[200:203], v[76:79]
	v_mfma_f32_16x16x32_bf16 v[72:75], v[236:239], v[200:203], v[72:75]
	v_mfma_f32_16x16x32_bf16 v[4:7], v[240:243], v[200:203], v[4:7]
	v_mfma_f32_16x16x32_bf16 v[0:3], v[244:247], v[200:203], v[0:3]
	v_mfma_f32_16x16x32_bf16 v[68:71], v[232:235], v[204:207], v[68:71]
	v_mfma_f32_16x16x32_bf16 v[64:67], v[236:239], v[204:207], v[64:67]
	v_mfma_f32_16x16x32_bf16 v[52:55], v[240:243], v[204:207], v[52:55]
	v_mfma_f32_16x16x32_bf16 v[56:59], v[244:247], v[204:207], v[56:59]

.LBB0_1892:
	s_or_b64 exec, exec, s[10:11]
	v_cvt_f32_u32_e32 v4, v2
	s_waitcnt vmcnt(0)
	v_readfirstlane_b32 s8, v3
	v_sub_u32_e32 v3, 0, v2
	v_rcp_iflag_f32_e32 v4, v4
	v_add_u32_e32 v5, s8, v1
	v_mul_f32_e32 v4, 0x4f7ffffe, v4
	v_cvt_u32_f32_e32 v4, v4
	v_mul_lo_u32 v1, v3, v4
	v_mul_hi_u32 v1, v4, v1
	v_add_u32_e32 v1, v4, v1
	v_mul_hi_u32 v1, v5, v1
	v_mul_lo_u32 v3, v1, v2
	v_sub_u32_e32 v3, v5, v3
	v_add_u32_e32 v4, 1, v1
	v_cmp_ge_u32_e32 vcc, v3, v2
	s_nop 1
	v_cndmask_b32_e32 v1, v1, v4, vcc
	v_sub_u32_e32 v4, v3, v2
	v_cndmask_b32_e32 v3, v3, v4, vcc
	v_add_u32_e32 v4, 1, v1
	v_cmp_ge_u32_e32 vcc, v3, v2
	v_add_u32_e32 v3, 1, v5
	s_nop 0
	v_cndmask_b32_e32 v1, v1, v4, vcc
	v_mul_lo_u32 v4, v2, v1
	v_add_u32_e32 v2, v4, v2
	v_cmp_ne_u32_e32 vcc, v3, v2
	s_and_saveexec_b64 s[8:9], vcc
	s_xor_b64 s[8:9], exec, s[8:9]
	s_cbranch_execz .LBB0_1906
	s_waitcnt lgkmcnt(0)
	buffer_inv sc1
	v_mov_b32_e32 v0, 0
	v_mov_b32_e32 v1, 14
	s_add_u32 s14, s86, 0xe7b4500
	s_addc_u32 s15, s87, 0
	global_load_dword v0, v0, s[14:15] sc1
	s_waitcnt vmcnt(0)
	v_cmp_eq_u32_e32 vcc, v0, v1
	s_and_saveexec_b64 s[10:11], vcc
	s_cbranch_execz .LBB0_1905
	s_add_u32 s12, s86, 0xe7b1200
	s_addc_u32 s13, s87, 0
	s_mov_b32 s28, 1
	s_mov_b64 s[16:17], 0
	v_mov_b32_e32 v0, 0
	s_branch .LBB0_1896

.LBB0_1951:
	s_or_b64 exec, exec, s[10:11]
	v_cvt_f32_u32_e32 v4, v2
	s_waitcnt vmcnt(0)
	v_readfirstlane_b32 s8, v3
	v_sub_u32_e32 v3, 0, v2
	v_rcp_iflag_f32_e32 v4, v4
	v_add_u32_e32 v5, s8, v1
	v_mul_f32_e32 v4, 0x4f7ffffe, v4
	v_cvt_u32_f32_e32 v4, v4
	v_mul_lo_u32 v1, v3, v4
	v_mul_hi_u32 v1, v4, v1
	v_add_u32_e32 v1, v4, v1
	v_mul_hi_u32 v1, v5, v1
	v_mul_lo_u32 v3, v1, v2
	v_sub_u32_e32 v3, v5, v3
	v_add_u32_e32 v4, 1, v1
	v_cmp_ge_u32_e32 vcc, v3, v2
	s_nop 1
	v_cndmask_b32_e32 v1, v1, v4, vcc
	v_sub_u32_e32 v4, v3, v2
	v_cndmask_b32_e32 v3, v3, v4, vcc
	v_add_u32_e32 v4, 1, v1
	v_cmp_ge_u32_e32 vcc, v3, v2
	v_add_u32_e32 v3, 1, v5
	s_nop 0
	v_cndmask_b32_e32 v1, v1, v4, vcc
	v_mul_lo_u32 v4, v2, v1
	v_add_u32_e32 v2, v4, v2
	v_cmp_ne_u32_e32 vcc, v3, v2
	s_and_saveexec_b64 s[8:9], vcc
	s_xor_b64 s[8:9], exec, s[8:9]
	s_cbranch_execz .LBB0_1965
	s_waitcnt lgkmcnt(0)
	buffer_inv sc1
	v_mov_b32_e32 v0, 0
	v_mov_b32_e32 v1, 15
	s_add_u32 s14, s86, 0xe7b4500
	s_addc_u32 s15, s87, 0
	global_load_dword v0, v0, s[14:15] sc1
	s_waitcnt vmcnt(0)
	v_cmp_eq_u32_e32 vcc, v0, v1
	s_and_saveexec_b64 s[10:11], vcc
	s_cbranch_execz .LBB0_1964
	s_add_u32 s12, s86, 0xe7b1200
	s_addc_u32 s13, s87, 0
	s_mov_b32 s28, 1
	s_mov_b64 s[16:17], 0
	v_mov_b32_e32 v0, 0
	s_branch .LBB0_1955

.LBB0_1997:
	s_waitcnt vmcnt(4)
	v_add_u32_e32 v7, s21, v137
	v_cmp_gt_i32_e32 vcc, s25, v7
	v_mov_b32_e32 v0, 0
	v_mov_b32_e32 v4, 0x100
	v_mov_b32_e32 v5, 0x4000
	v_mov_b32_e32 v6, 0
	s_and_saveexec_b64 s[0:1], vcc
	v_mul_hi_i32 v4, v7, s16
	v_lshrrev_b32_e32 v5, 31, v4
	v_ashrrev_i32_e32 v4, 3, v4
	v_add_u32_e32 v4, v4, v5
	v_lshlrev_b32_e32 v5, 11, v4
	v_lshl_add_u32 v4, v4, 4, v4
	v_sub_u32_e32 v4, v7, v4
	v_mul_lo_u32 v6, v4, s26
	v_mov_b32_e32 v4, 0x800
	s_or_b64 exec, exec, s[0:1]
	s_mul_i32 s0, s7, 0x7e
	v_add_u32_e32 v7, s0, v129
	s_waitcnt vmcnt(2)
	v_add_u32_e32 v8, s33, v7
	v_lshl_add_u32 v10, v8, 11, v134
	v_mad_u64_u32 v[8:9], s[0:1], v3, s26, v[136:137]
	s_mul_i32 s1, s21, 0x7879
	s_lshr_b32 s7, s1, 31
	s_ashr_i32 s1, s1, 19
	s_add_i32 s1, s1, s7
	s_mul_i32 s7, s1, 17
	s_sub_i32 s7, s21, s7
	s_mulk_i32 s7, 0x7e
	s_sext_i32_i16 s7, s7
	v_add_u32_e32 v3, s7, v129
	v_lshl_add_u32 v9, s1, 11, v3
	v_add_u32_e32 v1, v8, v1
	v_lshl_add_u32 v9, v9, 11, v134
	v_cmp_gt_u32_e32 vcc, s27, v3
	v_lshl_add_u32 v1, v1, 11, v138
	v_readfirstlane_b32 s1, v128
	v_cndmask_b32_e32 v3, v147, v9, vcc
	v_cmp_lt_u32_e32 vcc, v8, v2
	v_subrev_u32_e32 v132, s86, v3
	v_add_u32_e32 v11, v139, v6
	v_cndmask_b32_e32 v1, v147, v1, vcc
	v_cmp_gt_u32_e32 vcc, s6, v7
	s_lshr_b32 s6, s1, 1
	s_and_b32 s6, s6, 0x1ffff80
	v_or_b32_e32 v3, s6, v189
	s_and_b32 s6, s1, 0xc0
	s_lshl_b32 s1, s1, 4
	s_and_b32 s33, s1, 0x7ffffc00
	v_add_u32_e32 v5, v11, v5
	s_mov_b32 m0, s33
	v_lshl_add_u32 v5, v5, 11, v142
	v_subrev_u32_e32 v2, s86, v1
	v_cndmask_b32_e32 v1, v147, v10, vcc
	v_cmp_lt_u32_e32 vcc, v11, v4
	global_load_lds_dwordx4 v132, s[86:87]
	s_add_i32 m0, s33, 0x2000
	s_lshl_b32 s0, s20, 19
	v_subrev_u32_e32 v6, s86, v1
	v_cndmask_b32_e32 v1, v147, v5, vcc
	global_load_lds_dwordx4 v2, s[86:87]
	s_add_i32 m0, s33, 0x4000
	v_subrev_u32_e32 v4, s86, v1
	v_lshlrev_b32_e32 v178, 7, v3
	v_or_b32_e32 v3, s6, v189
	s_add_i32 s6, s33, 0x8000
	global_load_lds_dwordx4 v6, s[86:87]
	s_add_i32 m0, s33, 0x6000
	v_or_b32_e32 v8, s0, v146
	v_mov_b32_e32 v9, v133
	global_load_lds_dwordx4 v4, s[86:87]
	v_lshl_add_u64 v[8:9], s[86:87], 0, v[8:9]
	s_mov_b32 m0, s6
	v_add_u32_e32 v1, s0, v150
	global_load_lds_dwordx4 v[8:9], off
	v_or_b32_e32 v8, s0, v148
	v_mov_b32_e32 v9, v133
	v_add_u32_e32 v10, s0, v144
	v_lshl_add_u64 v[8:9], s[86:87], 0, v[8:9]
	s_add_i32 m0, s33, 0xa000
	v_and_b32_e32 v1, 0xfffff870, v1
	global_load_lds_dwordx4 v[8:9], off
	s_add_i32 m0, s33, 0xc000
	v_and_or_b32 v8, v10, s28, v140
	v_mov_b32_e32 v9, v141
	global_load_lds_dwordx4 v1, s[86:87]
	v_lshl_add_u64 v[8:9], s[86:87], 0, v[8:9]
	s_add_i32 m0, s33, 0xe000
	v_add_u32_e32 v1, s0, v154
	global_load_lds_dwordx4 v[8:9], off
	s_waitcnt vmcnt(0)
	v_lshl_add_u64 v[160:161], s[18:19], 0, v[132:133]
	v_and_b32_e32 v132, -16, v1
	v_add_u32_e32 v1, s0, v158
	v_lshl_or_b32 v179, v3, 7, v149
	v_mov_b32_e32 v3, v133
	v_mov_b32_e32 v7, v133
	v_mov_b32_e32 v5, v133
	s_mov_b32 s1, 0
	v_lshl_add_u64 v[172:173], s[18:19], 0, v[132:133]
	v_and_b32_e32 v132, 0xfffff800, v1
	v_lshl_add_u64 v[162:163], s[18:19], 0, v[2:3]
	v_lshl_add_u64 v[164:165], s[18:19], 0, v[6:7]
	v_lshl_add_u64 v[166:167], s[18:19], 0, v[4:5]
	v_lshl_add_u64 v[168:169], v[152:153], 0, s[0:1]
	v_lshl_add_u64 v[170:171], v[130:131], 0, s[0:1]
	v_lshl_add_u64 v[174:175], v[156:157], 0, v[132:133]
	s_mov_b64 s[6:7], 0
	v_mov_b32_e32 v1, v0
	v_mov_b32_e32 v2, v0
	v_mov_b32_e32 v3, v0
	v_mov_b32_e32 v4, v0
	v_mov_b32_e32 v5, v0
	v_mov_b32_e32 v6, v0
	v_mov_b32_e32 v7, v0
	s_waitcnt vmcnt(0)
	v_mov_b32_e32 v64, v0
	v_mov_b32_e32 v65, v0
	v_mov_b32_e32 v66, v0
	v_mov_b32_e32 v67, v0
	v_mov_b32_e32 v68, v0
	v_mov_b32_e32 v69, v0
	v_mov_b32_e32 v70, v0
	v_mov_b32_e32 v71, v0
	v_mov_b32_e32 v8, v0
	v_mov_b32_e32 v9, v0
	v_mov_b32_e32 v10, v0
	v_mov_b32_e32 v11, v0
	v_mov_b32_e32 v12, v0
	v_mov_b32_e32 v13, v0
	v_mov_b32_e32 v14, v0
	v_mov_b32_e32 v15, v0
	v_mov_b32_e32 v72, v0
	v_mov_b32_e32 v73, v0
	v_mov_b32_e32 v74, v0
	v_mov_b32_e32 v75, v0
	v_mov_b32_e32 v76, v0
	v_mov_b32_e32 v77, v0
	v_mov_b32_e32 v78, v0
	v_mov_b32_e32 v79, v0
	v_mov_b32_e32 v16, v0
	v_mov_b32_e32 v17, v0
	v_mov_b32_e32 v18, v0
	v_mov_b32_e32 v19, v0
	v_mov_b32_e32 v20, v0
	v_mov_b32_e32 v21, v0
	v_mov_b32_e32 v22, v0
	v_mov_b32_e32 v23, v0
	v_mov_b32_e32 v80, v0
	v_mov_b32_e32 v81, v0
	v_mov_b32_e32 v82, v0
	v_mov_b32_e32 v83, v0
	v_mov_b32_e32 v84, v0
	v_mov_b32_e32 v85, v0
	v_mov_b32_e32 v86, v0
	v_mov_b32_e32 v87, v0
	v_mov_b32_e32 v24, v0
	v_mov_b32_e32 v25, v0
	v_mov_b32_e32 v26, v0
	v_mov_b32_e32 v27, v0
	v_mov_b32_e32 v28, v0
	v_mov_b32_e32 v29, v0
	v_mov_b32_e32 v30, v0
	v_mov_b32_e32 v31, v0
	v_mov_b32_e32 v88, v0
	v_mov_b32_e32 v89, v0
	v_mov_b32_e32 v90, v0
	v_mov_b32_e32 v91, v0
	v_mov_b32_e32 v92, v0
	v_mov_b32_e32 v93, v0
	v_mov_b32_e32 v94, v0
	v_mov_b32_e32 v95, v0
	v_mov_b32_e32 v32, v0
	v_mov_b32_e32 v33, v0
	v_mov_b32_e32 v34, v0
	v_mov_b32_e32 v35, v0
	v_mov_b32_e32 v36, v0
	v_mov_b32_e32 v37, v0
	v_mov_b32_e32 v38, v0
	v_mov_b32_e32 v39, v0
	v_mov_b32_e32 v96, v0
	v_mov_b32_e32 v97, v0
	v_mov_b32_e32 v98, v0
	v_mov_b32_e32 v99, v0
	v_mov_b32_e32 v100, v0
	v_mov_b32_e32 v101, v0
	v_mov_b32_e32 v102, v0
	v_mov_b32_e32 v103, v0
	v_mov_b32_e32 v40, v0
	v_mov_b32_e32 v41, v0
	v_mov_b32_e32 v42, v0
	v_mov_b32_e32 v43, v0
	v_mov_b32_e32 v44, v0
	v_mov_b32_e32 v45, v0
	v_mov_b32_e32 v46, v0
	v_mov_b32_e32 v47, v0
	v_mov_b32_e32 v104, v0
	v_mov_b32_e32 v105, v0
	v_mov_b32_e32 v106, v0
	v_mov_b32_e32 v107, v0
	v_mov_b32_e32 v108, v0
	v_mov_b32_e32 v109, v0
	v_mov_b32_e32 v110, v0
	v_mov_b32_e32 v111, v0
	v_mov_b32_e32 v48, v0
	v_mov_b32_e32 v49, v0
	v_mov_b32_e32 v50, v0
	v_mov_b32_e32 v51, v0
	v_mov_b32_e32 v52, v0
	v_mov_b32_e32 v53, v0
	v_mov_b32_e32 v54, v0
	v_mov_b32_e32 v55, v0
	v_mov_b32_e32 v112, v0
	v_mov_b32_e32 v113, v0
	v_mov_b32_e32 v114, v0
	v_mov_b32_e32 v115, v0
	v_mov_b32_e32 v116, v0
	v_mov_b32_e32 v117, v0
	v_mov_b32_e32 v118, v0
	v_mov_b32_e32 v119, v0
	v_mov_b32_e32 v56, v0
	v_mov_b32_e32 v57, v0
	v_mov_b32_e32 v58, v0
	v_mov_b32_e32 v59, v0
	v_mov_b32_e32 v60, v0
	v_mov_b32_e32 v61, v0
	v_mov_b32_e32 v62, v0
	v_mov_b32_e32 v63, v0
	v_mov_b32_e32 v120, v0
	v_mov_b32_e32 v121, v0
	v_mov_b32_e32 v122, v0
	v_mov_b32_e32 v123, v0
	v_mov_b32_e32 v124, v0
	v_mov_b32_e32 v125, v0
	v_mov_b32_e32 v126, v0
	v_mov_b32_e32 v127, v0
	s_waitcnt lgkmcnt(0)
	s_barrier
	s_mov_b32 s0, 0x10000
	s_and_b32 s0, s1, 0x10000
	s_xor_b32 s34, s0, 0x10000
	s_add_i32 s34, s33, s34
	s_add_i32 s35, s34, 0x8000
	s_mov_b32 m0, s34
	v_lshl_add_u64 v[254:255], v[160:161], 0, s[6:7]
	global_load_lds_dwordx4 v[254:255], off
	s_add_i32 m0, s34, 0x2000
	v_lshl_add_u64 v[254:255], v[162:163], 0, s[6:7]
	global_load_lds_dwordx4 v[254:255], off
	s_add_i32 m0, s34, 0x4000
	v_lshl_add_u64 v[254:255], v[164:165], 0, s[6:7]
	global_load_lds_dwordx4 v[254:255], off
	s_add_i32 m0, s34, 0x6000
	v_lshl_add_u64 v[254:255], v[166:167], 0, s[6:7]
	global_load_lds_dwordx4 v[254:255], off
	s_mov_b32 m0, s35
	v_lshl_add_u64 v[254:255], v[168:169], 0, s[6:7]
	global_load_lds_dwordx4 v[254:255], off
	s_add_i32 m0, s34, 0xa000
	v_lshl_add_u64 v[254:255], v[170:171], 0, s[6:7]
	global_load_lds_dwordx4 v[254:255], off
	s_add_i32 m0, s34, 0xc000
	v_lshl_add_u64 v[254:255], v[172:173], 0, s[6:7]
	global_load_lds_dwordx4 v[254:255], off
	s_add_i32 m0, s34, 0xe000
	v_lshl_add_u64 v[254:255], v[174:175], 0, s[6:7]
	global_load_lds_dwordx4 v[254:255], off
	v_add3_u32 v253, s0, v178, v143
	ds_read_b128 v[220:223], v253 offset:0x1000
	ds_read_b128 v[224:227], v253 offset:0x1800
	ds_read_b128 v[212:215], v253 offset:0
	v_add3_u32 v253, s0, v179, v143
	ds_read_b128 v[180:183], v253 offset:0
	v_add3_u32 v253, s0, v178, v143
	ds_read_b128 v[216:219], v253 offset:0x800
	v_add3_u32 v253, s0, v179, v143
	ds_read_b128 v[200:203], v253 offset:0x800
	ds_read_b128 v[204:207], v253 offset:0x1000
	ds_read_b128 v[208:211], v253 offset:0x1800
.Lgffu1_body:
	v_add_u32_e32 v185, s0, v179
	v_add_u32_e32 v132, s0, v178
	v_add_u32_e32 v184, v132, v143
	v_add_u32_e32 v185, v185, v145
	s_waitcnt lgkmcnt(4)
	v_add_u32_e32 v132, v132, v145
	v_mfma_f32_16x16x32_bf16 v[124:127], v[180:183], v[212:215], v[124:127]
	s_waitcnt lgkmcnt(2)
	v_mfma_f32_16x16x32_bf16 v[120:123], v[200:203], v[212:215], v[120:123]
	s_waitcnt lgkmcnt(1)
	v_mfma_f32_16x16x32_bf16 v[60:63], v[204:207], v[212:215], v[60:63]
	s_waitcnt lgkmcnt(0)
	v_mfma_f32_16x16x32_bf16 v[56:59], v[208:211], v[212:215], v[56:59]
	ds_read_b128 v[212:215], v184 offset:0x2000
	v_mfma_f32_16x16x32_bf16 v[116:119], v[180:183], v[216:219], v[116:119]
	v_mfma_f32_16x16x32_bf16 v[112:115], v[200:203], v[216:219], v[112:115]
	v_mfma_f32_16x16x32_bf16 v[52:55], v[204:207], v[216:219], v[52:55]
	v_mfma_f32_16x16x32_bf16 v[48:51], v[208:211], v[216:219], v[48:51]
	ds_read_b128 v[216:219], v184 offset:0x2800
	s_waitcnt lgkmcnt(2)
	s_nop 0
	v_mfma_f32_16x16x32_bf16 v[108:111], v[180:183], v[220:223], v[108:111]
	v_mfma_f32_16x16x32_bf16 v[104:107], v[200:203], v[220:223], v[104:107]
	v_mfma_f32_16x16x32_bf16 v[44:47], v[204:207], v[220:223], v[44:47]
	v_mfma_f32_16x16x32_bf16 v[40:43], v[208:211], v[220:223], v[40:43]
	ds_read_b128 v[220:223], v184 offset:0x3000
	v_mfma_f32_16x16x32_bf16 v[100:103], v[180:183], v[224:227], v[100:103]
	v_mfma_f32_16x16x32_bf16 v[96:99], v[200:203], v[224:227], v[96:99]
	v_mfma_f32_16x16x32_bf16 v[36:39], v[204:207], v[224:227], v[36:39]
	v_mfma_f32_16x16x32_bf16 v[32:35], v[208:211], v[224:227], v[32:35]
	ds_read_b128 v[224:227], v184 offset:0x3800
	ds_read_b128 v[228:231], v185 offset:0
	ds_read_b128 v[232:235], v185 offset:0x800
	ds_read_b128 v[236:239], v185 offset:0x1000
	ds_read_b128 v[240:243], v185 offset:0x1800
	s_waitcnt lgkmcnt(6)
	s_nop 0
	v_mfma_f32_16x16x32_bf16 v[92:95], v[180:183], v[212:215], v[92:95]
	v_mfma_f32_16x16x32_bf16 v[88:91], v[200:203], v[212:215], v[88:91]
	v_mfma_f32_16x16x32_bf16 v[28:31], v[204:207], v[212:215], v[28:31]
	v_mfma_f32_16x16x32_bf16 v[24:27], v[208:211], v[212:215], v[24:27]
	ds_read_b128 v[212:215], v132 offset:0
	v_mfma_f32_16x16x32_bf16 v[84:87], v[180:183], v[216:219], v[84:87]
	v_mfma_f32_16x16x32_bf16 v[80:83], v[200:203], v[216:219], v[80:83]
	v_mfma_f32_16x16x32_bf16 v[20:23], v[204:207], v[216:219], v[20:23]
	v_mfma_f32_16x16x32_bf16 v[16:19], v[208:211], v[216:219], v[16:19]
	ds_read_b128 v[216:219], v132 offset:0x800
	s_waitcnt lgkmcnt(6)
	s_nop 0
	v_mfma_f32_16x16x32_bf16 v[76:79], v[180:183], v[220:223], v[76:79]
	v_mfma_f32_16x16x32_bf16 v[68:71], v[180:183], v[224:227], v[68:71]
	ds_read_b128 v[180:183], v132 offset:0x1000
	v_mfma_f32_16x16x32_bf16 v[72:75], v[200:203], v[220:223], v[72:75]
	v_mfma_f32_16x16x32_bf16 v[64:67], v[200:203], v[224:227], v[64:67]
	ds_read_b128 v[200:203], v132 offset:0x1800
	s_waitcnt lgkmcnt(2)
	v_mfma_f32_16x16x32_bf16 v[12:15], v[204:207], v[220:223], v[12:15]
	v_mfma_f32_16x16x32_bf16 v[4:7], v[204:207], v[224:227], v[4:7]
	ds_read_b128 v[204:207], v132 offset:0x2000
	v_mfma_f32_16x16x32_bf16 v[8:11], v[208:211], v[220:223], v[8:11]
	v_mfma_f32_16x16x32_bf16 v[0:3], v[208:211], v[224:227], v[0:3]
	ds_read_b128 v[208:211], v132 offset:0x2800
	s_waitcnt lgkmcnt(2)
	s_nop 0
	v_mfma_f32_16x16x32_bf16 v[108:111], v[228:231], v[180:183], v[108:111]
	v_mfma_f32_16x16x32_bf16 v[104:107], v[232:235], v[180:183], v[104:107]
	v_mfma_f32_16x16x32_bf16 v[44:47], v[236:239], v[180:183], v[44:47]
	v_mfma_f32_16x16x32_bf16 v[40:43], v[240:243], v[180:183], v[40:43]
	ds_read_b128 v[180:183], v132 offset:0x3000
	v_mfma_f32_16x16x32_bf16 v[100:103], v[228:231], v[200:203], v[100:103]
	v_mfma_f32_16x16x32_bf16 v[96:99], v[232:235], v[200:203], v[96:99]
	v_mfma_f32_16x16x32_bf16 v[36:39], v[236:239], v[200:203], v[36:39]
	v_mfma_f32_16x16x32_bf16 v[32:35], v[240:243], v[200:203], v[32:35]
	ds_read_b128 v[200:203], v132 offset:0x3800
	s_waitcnt lgkmcnt(2)
	v_mfma_f32_16x16x32_bf16 v[124:127], v[228:231], v[212:215], v[124:127]
	s_add_i32 s1, s1, 0x10000
	s_add_u32 s6, s6, 0x80
	s_addc_u32 s7, s7, 0
	s_waitcnt lgkmcnt(0)
	s_waitcnt vmcnt(0)
	s_waitcnt vmcnt(0) lgkmcnt(0)
	v_mfma_f32_16x16x32_bf16 v[120:123], v[232:235], v[212:215], v[120:123]
	s_barrier
	s_cmpk_eq_i32 s6, 0x780
	s_cbranch_scc1 .Lgffu1_nodma
	s_mov_b32 s0, 0x10000
	s_and_b32 s0, s1, 0x10000
	s_xor_b32 s34, s0, 0x10000
	s_add_i32 s34, s33, s34
	s_add_i32 s35, s34, 0x8000
	v_add3_u32 v253, s0, v178, v143
	ds_read_b128 v[220:223], v253 offset:0x1000
	ds_read_b128 v[224:227], v253 offset:0x1800
	v_mfma_f32_16x16x32_bf16 v[60:63], v[236:239], v[212:215], v[60:63]
	s_mov_b32 m0, s34
	v_lshl_add_u64 v[254:255], v[160:161], 0, s[6:7]
	global_load_lds_dwordx4 v[254:255], off
	v_mfma_f32_16x16x32_bf16 v[56:59], v[240:243], v[212:215], v[56:59]
	ds_read_b128 v[212:215], v253 offset:0
	v_mfma_f32_16x16x32_bf16 v[76:79], v[228:231], v[180:183], v[76:79]
	s_add_i32 m0, s34, 0x2000
	v_lshl_add_u64 v[254:255], v[162:163], 0, s[6:7]
	global_load_lds_dwordx4 v[254:255], off
	v_mfma_f32_16x16x32_bf16 v[72:75], v[232:235], v[180:183], v[72:75]
	v_mfma_f32_16x16x32_bf16 v[12:15], v[236:239], v[180:183], v[12:15]
	s_add_i32 m0, s34, 0x4000
	v_lshl_add_u64 v[254:255], v[164:165], 0, s[6:7]
	global_load_lds_dwordx4 v[254:255], off
	v_mfma_f32_16x16x32_bf16 v[8:11], v[240:243], v[180:183], v[8:11]
	v_add3_u32 v253, s0, v179, v143
	ds_read_b128 v[180:183], v253 offset:0
	v_mfma_f32_16x16x32_bf16 v[116:119], v[228:231], v[216:219], v[116:119]
	s_add_i32 m0, s34, 0x6000
	v_lshl_add_u64 v[254:255], v[166:167], 0, s[6:7]
	global_load_lds_dwordx4 v[254:255], off
	v_mfma_f32_16x16x32_bf16 v[112:115], v[232:235], v[216:219], v[112:115]
	v_mfma_f32_16x16x32_bf16 v[52:55], v[236:239], v[216:219], v[52:55]
	s_mov_b32 m0, s35
	v_lshl_add_u64 v[254:255], v[168:169], 0, s[6:7]
	global_load_lds_dwordx4 v[254:255], off
	v_mfma_f32_16x16x32_bf16 v[48:51], v[240:243], v[216:219], v[48:51]
	v_add3_u32 v253, s0, v178, v143
	ds_read_b128 v[216:219], v253 offset:0x800
	v_mfma_f32_16x16x32_bf16 v[68:71], v[228:231], v[200:203], v[68:71]
	s_add_i32 m0, s34, 0xa000
	v_lshl_add_u64 v[254:255], v[170:171], 0, s[6:7]
	global_load_lds_dwordx4 v[254:255], off
	v_mfma_f32_16x16x32_bf16 v[64:67], v[232:235], v[200:203], v[64:67]
	v_mfma_f32_16x16x32_bf16 v[4:7], v[236:239], v[200:203], v[4:7]
	s_add_i32 m0, s34, 0xc000
	v_lshl_add_u64 v[254:255], v[172:173], 0, s[6:7]
	global_load_lds_dwordx4 v[254:255], off
	v_mfma_f32_16x16x32_bf16 v[0:3], v[240:243], v[200:203], v[0:3]
	v_add3_u32 v253, s0, v179, v143
	ds_read_b128 v[200:203], v253 offset:0x800
	v_mfma_f32_16x16x32_bf16 v[92:95], v[228:231], v[204:207], v[92:95]
	s_add_i32 m0, s34, 0xe000
	v_lshl_add_u64 v[254:255], v[174:175], 0, s[6:7]
	global_load_lds_dwordx4 v[254:255], off
	v_mfma_f32_16x16x32_bf16 v[88:91], v[232:235], v[204:207], v[88:91]
	v_mfma_f32_16x16x32_bf16 v[28:31], v[236:239], v[204:207], v[28:31]
	v_mfma_f32_16x16x32_bf16 v[24:27], v[240:243], v[204:207], v[24:27]
	ds_read_b128 v[204:207], v253 offset:0x1000
	v_mfma_f32_16x16x32_bf16 v[84:87], v[228:231], v[208:211], v[84:87]
	v_mfma_f32_16x16x32_bf16 v[80:83], v[232:235], v[208:211], v[80:83]
	v_mfma_f32_16x16x32_bf16 v[20:23], v[236:239], v[208:211], v[20:23]
	v_mfma_f32_16x16x32_bf16 v[16:19], v[240:243], v[208:211], v[16:19]
	ds_read_b128 v[208:211], v253 offset:0x1800
	s_branch .Lgffu1_body
.Lgffu1_nodma:
	s_mov_b32 s0, 0x10000
	v_add3_u32 v253, s0, v178, v143
	ds_read_b128 v[220:223], v253 offset:0x1000
	ds_read_b128 v[224:227], v253 offset:0x1800
	v_mfma_f32_16x16x32_bf16 v[60:63], v[236:239], v[212:215], v[60:63]
	v_mfma_f32_16x16x32_bf16 v[56:59], v[240:243], v[212:215], v[56:59]
	ds_read_b128 v[212:215], v253 offset:0
	v_mfma_f32_16x16x32_bf16 v[76:79], v[228:231], v[180:183], v[76:79]
	v_mfma_f32_16x16x32_bf16 v[72:75], v[232:235], v[180:183], v[72:75]
	v_mfma_f32_16x16x32_bf16 v[12:15], v[236:239], v[180:183], v[12:15]
	v_mfma_f32_16x16x32_bf16 v[8:11], v[240:243], v[180:183], v[8:11]
	v_add3_u32 v253, s0, v179, v143
	ds_read_b128 v[180:183], v253 offset:0
	v_mfma_f32_16x16x32_bf16 v[116:119], v[228:231], v[216:219], v[116:119]
	v_mfma_f32_16x16x32_bf16 v[112:115], v[232:235], v[216:219], v[112:115]
	v_mfma_f32_16x16x32_bf16 v[52:55], v[236:239], v[216:219], v[52:55]
	v_mfma_f32_16x16x32_bf16 v[48:51], v[240:243], v[216:219], v[48:51]
	v_add3_u32 v253, s0, v178, v143
	ds_read_b128 v[216:219], v253 offset:0x800
	v_mfma_f32_16x16x32_bf16 v[68:71], v[228:231], v[200:203], v[68:71]
	v_mfma_f32_16x16x32_bf16 v[64:67], v[232:235], v[200:203], v[64:67]
	v_mfma_f32_16x16x32_bf16 v[4:7], v[236:239], v[200:203], v[4:7]
	v_mfma_f32_16x16x32_bf16 v[0:3], v[240:243], v[200:203], v[0:3]
	v_add3_u32 v253, s0, v179, v143
	ds_read_b128 v[200:203], v253 offset:0x800
	v_mfma_f32_16x16x32_bf16 v[92:95], v[228:231], v[204:207], v[92:95]
	v_mfma_f32_16x16x32_bf16 v[88:91], v[232:235], v[204:207], v[88:91]
	v_mfma_f32_16x16x32_bf16 v[28:31], v[236:239], v[204:207], v[28:31]
	v_mfma_f32_16x16x32_bf16 v[24:27], v[240:243], v[204:207], v[24:27]
	ds_read_b128 v[204:207], v253 offset:0x1000
	v_mfma_f32_16x16x32_bf16 v[84:87], v[228:231], v[208:211], v[84:87]
	v_mfma_f32_16x16x32_bf16 v[80:83], v[232:235], v[208:211], v[80:83]
	v_mfma_f32_16x16x32_bf16 v[20:23], v[236:239], v[208:211], v[20:23]
	v_mfma_f32_16x16x32_bf16 v[16:19], v[240:243], v[208:211], v[16:19]
	ds_read_b128 v[208:211], v253 offset:0x1800
	v_add_u32_e32 v185, s0, v179
	v_add_u32_e32 v132, s0, v178
	v_add_u32_e32 v184, v132, v143
	v_add_u32_e32 v185, v185, v145
	s_waitcnt lgkmcnt(4)
	v_add_u32_e32 v132, v132, v145
	v_mfma_f32_16x16x32_bf16 v[124:127], v[180:183], v[212:215], v[124:127]
	s_waitcnt lgkmcnt(2)
	v_mfma_f32_16x16x32_bf16 v[120:123], v[200:203], v[212:215], v[120:123]
	s_waitcnt lgkmcnt(1)
	v_mfma_f32_16x16x32_bf16 v[60:63], v[204:207], v[212:215], v[60:63]
	s_waitcnt lgkmcnt(0)
	v_mfma_f32_16x16x32_bf16 v[56:59], v[208:211], v[212:215], v[56:59]
	ds_read_b128 v[212:215], v184 offset:0x2000
	v_mfma_f32_16x16x32_bf16 v[116:119], v[180:183], v[216:219], v[116:119]
	v_mfma_f32_16x16x32_bf16 v[112:115], v[200:203], v[216:219], v[112:115]
	v_mfma_f32_16x16x32_bf16 v[52:55], v[204:207], v[216:219], v[52:55]
	v_mfma_f32_16x16x32_bf16 v[48:51], v[208:211], v[216:219], v[48:51]
	ds_read_b128 v[216:219], v184 offset:0x2800
	s_waitcnt lgkmcnt(2)
	s_nop 0
	v_mfma_f32_16x16x32_bf16 v[108:111], v[180:183], v[220:223], v[108:111]
	v_mfma_f32_16x16x32_bf16 v[104:107], v[200:203], v[220:223], v[104:107]
	v_mfma_f32_16x16x32_bf16 v[44:47], v[204:207], v[220:223], v[44:47]
	v_mfma_f32_16x16x32_bf16 v[40:43], v[208:211], v[220:223], v[40:43]
	ds_read_b128 v[220:223], v184 offset:0x3000
	v_mfma_f32_16x16x32_bf16 v[100:103], v[180:183], v[224:227], v[100:103]
	v_mfma_f32_16x16x32_bf16 v[96:99], v[200:203], v[224:227], v[96:99]
	v_mfma_f32_16x16x32_bf16 v[36:39], v[204:207], v[224:227], v[36:39]
	v_mfma_f32_16x16x32_bf16 v[32:35], v[208:211], v[224:227], v[32:35]
	ds_read_b128 v[224:227], v184 offset:0x3800
	ds_read_b128 v[228:231], v185 offset:0
	ds_read_b128 v[232:235], v185 offset:0x800
	ds_read_b128 v[236:239], v185 offset:0x1000
	ds_read_b128 v[240:243], v185 offset:0x1800
	s_waitcnt lgkmcnt(6)
	s_nop 0
	v_mfma_f32_16x16x32_bf16 v[92:95], v[180:183], v[212:215], v[92:95]
	v_mfma_f32_16x16x32_bf16 v[88:91], v[200:203], v[212:215], v[88:91]
	v_mfma_f32_16x16x32_bf16 v[28:31], v[204:207], v[212:215], v[28:31]
	v_mfma_f32_16x16x32_bf16 v[24:27], v[208:211], v[212:215], v[24:27]
	ds_read_b128 v[212:215], v132 offset:0
	v_mfma_f32_16x16x32_bf16 v[84:87], v[180:183], v[216:219], v[84:87]
	v_mfma_f32_16x16x32_bf16 v[80:83], v[200:203], v[216:219], v[80:83]
	v_mfma_f32_16x16x32_bf16 v[20:23], v[204:207], v[216:219], v[20:23]
	v_mfma_f32_16x16x32_bf16 v[16:19], v[208:211], v[216:219], v[16:19]
	ds_read_b128 v[216:219], v132 offset:0x800
	s_waitcnt lgkmcnt(6)
	s_nop 0
	v_mfma_f32_16x16x32_bf16 v[76:79], v[180:183], v[220:223], v[76:79]
	v_mfma_f32_16x16x32_bf16 v[68:71], v[180:183], v[224:227], v[68:71]
	ds_read_b128 v[180:183], v132 offset:0x1000
	v_mfma_f32_16x16x32_bf16 v[72:75], v[200:203], v[220:223], v[72:75]
	v_mfma_f32_16x16x32_bf16 v[64:67], v[200:203], v[224:227], v[64:67]
	ds_read_b128 v[200:203], v132 offset:0x1800
	s_waitcnt lgkmcnt(2)
	v_mfma_f32_16x16x32_bf16 v[12:15], v[204:207], v[220:223], v[12:15]
	v_mfma_f32_16x16x32_bf16 v[4:7], v[204:207], v[224:227], v[4:7]
	ds_read_b128 v[204:207], v132 offset:0x2000
	v_mfma_f32_16x16x32_bf16 v[8:11], v[208:211], v[220:223], v[8:11]
	v_mfma_f32_16x16x32_bf16 v[0:3], v[208:211], v[224:227], v[0:3]
	ds_read_b128 v[208:211], v132 offset:0x2800
	s_waitcnt lgkmcnt(2)
	s_nop 0
	v_mfma_f32_16x16x32_bf16 v[108:111], v[228:231], v[180:183], v[108:111]
	v_mfma_f32_16x16x32_bf16 v[104:107], v[232:235], v[180:183], v[104:107]
	v_mfma_f32_16x16x32_bf16 v[44:47], v[236:239], v[180:183], v[44:47]
	v_mfma_f32_16x16x32_bf16 v[40:43], v[240:243], v[180:183], v[40:43]
	ds_read_b128 v[180:183], v132 offset:0x3000
	v_mfma_f32_16x16x32_bf16 v[100:103], v[228:231], v[200:203], v[100:103]
	v_mfma_f32_16x16x32_bf16 v[96:99], v[232:235], v[200:203], v[96:99]
	v_mfma_f32_16x16x32_bf16 v[36:39], v[236:239], v[200:203], v[36:39]
	v_mfma_f32_16x16x32_bf16 v[32:35], v[240:243], v[200:203], v[32:35]
	ds_read_b128 v[200:203], v132 offset:0x3800
	s_waitcnt lgkmcnt(2)
	v_mfma_f32_16x16x32_bf16 v[124:127], v[228:231], v[212:215], v[124:127]
	s_add_i32 s1, s1, 0x10000
	s_add_u32 s6, s6, 0x80
	s_addc_u32 s7, s7, 0
	s_waitcnt lgkmcnt(0)
	s_waitcnt vmcnt(0)
	s_waitcnt vmcnt(0) lgkmcnt(0)
	v_mfma_f32_16x16x32_bf16 v[120:123], v[232:235], v[212:215], v[120:123]
	s_barrier
	v_mfma_f32_16x16x32_bf16 v[60:63], v[236:239], v[212:215], v[60:63]
	v_mfma_f32_16x16x32_bf16 v[56:59], v[240:243], v[212:215], v[56:59]
	v_mfma_f32_16x16x32_bf16 v[116:119], v[228:231], v[216:219], v[116:119]
	v_mfma_f32_16x16x32_bf16 v[112:115], v[232:235], v[216:219], v[112:115]
	v_mfma_f32_16x16x32_bf16 v[52:55], v[236:239], v[216:219], v[52:55]
	v_mfma_f32_16x16x32_bf16 v[48:51], v[240:243], v[216:219], v[48:51]
	v_mfma_f32_16x16x32_bf16 v[92:95], v[228:231], v[204:207], v[92:95]
	v_mfma_f32_16x16x32_bf16 v[88:91], v[232:235], v[204:207], v[88:91]
	v_mfma_f32_16x16x32_bf16 v[28:31], v[236:239], v[204:207], v[28:31]
	v_mfma_f32_16x16x32_bf16 v[24:27], v[240:243], v[204:207], v[24:27]
	v_mfma_f32_16x16x32_bf16 v[84:87], v[228:231], v[208:211], v[84:87]
	v_mfma_f32_16x16x32_bf16 v[80:83], v[232:235], v[208:211], v[80:83]
	v_mfma_f32_16x16x32_bf16 v[20:23], v[236:239], v[208:211], v[20:23]
	v_mfma_f32_16x16x32_bf16 v[16:19], v[240:243], v[208:211], v[16:19]
	v_mfma_f32_16x16x32_bf16 v[76:79], v[228:231], v[180:183], v[76:79]
	v_mfma_f32_16x16x32_bf16 v[72:75], v[232:235], v[180:183], v[72:75]
	v_mfma_f32_16x16x32_bf16 v[12:15], v[236:239], v[180:183], v[12:15]
	v_mfma_f32_16x16x32_bf16 v[8:11], v[240:243], v[180:183], v[8:11]
	v_mfma_f32_16x16x32_bf16 v[68:71], v[228:231], v[200:203], v[68:71]
	v_mfma_f32_16x16x32_bf16 v[64:67], v[232:235], v[200:203], v[64:67]
	v_mfma_f32_16x16x32_bf16 v[4:7], v[236:239], v[200:203], v[4:7]
	v_mfma_f32_16x16x32_bf16 v[0:3], v[240:243], v[200:203], v[0:3]

.LBB0_2045:
	s_or_b64 exec, exec, s[10:11]
	v_cvt_f32_u32_e32 v4, v2
	s_waitcnt vmcnt(0)
	v_readfirstlane_b32 s3, v3
	v_sub_u32_e32 v3, 0, v2
	v_rcp_iflag_f32_e32 v4, v4
	v_add_u32_e32 v5, s3, v1
	v_mul_f32_e32 v4, 0x4f7ffffe, v4
	v_cvt_u32_f32_e32 v4, v4
	v_mul_lo_u32 v1, v3, v4
	v_mul_hi_u32 v1, v4, v1
	v_add_u32_e32 v1, v4, v1
	v_mul_hi_u32 v1, v5, v1
	v_mul_lo_u32 v3, v1, v2
	v_sub_u32_e32 v3, v5, v3
	v_add_u32_e32 v4, 1, v1
	v_cmp_ge_u32_e32 vcc, v3, v2
	s_nop 1
	v_cndmask_b32_e32 v1, v1, v4, vcc
	v_sub_u32_e32 v4, v3, v2
	v_cndmask_b32_e32 v3, v3, v4, vcc
	v_add_u32_e32 v4, 1, v1
	v_cmp_ge_u32_e32 vcc, v3, v2
	v_add_u32_e32 v3, 1, v5
	s_nop 0
	v_cndmask_b32_e32 v1, v1, v4, vcc
	v_mul_lo_u32 v4, v2, v1
	v_add_u32_e32 v2, v4, v2
	v_cmp_ne_u32_e32 vcc, v3, v2
	s_and_saveexec_b64 s[8:9], vcc
	s_xor_b64 s[8:9], exec, s[8:9]
	s_cbranch_execz .LBB0_2059
	s_waitcnt lgkmcnt(0)
	buffer_inv sc1
	v_mov_b32_e32 v0, 0
	v_mov_b32_e32 v1, 16
	s_add_u32 s14, s86, 0xe7b4500
	s_addc_u32 s15, s87, 0
	global_load_dword v0, v0, s[14:15] sc1
	s_waitcnt vmcnt(0)
	v_cmp_eq_u32_e32 vcc, v0, v1
	s_and_saveexec_b64 s[10:11], vcc
	s_cbranch_execz .LBB0_2058
	s_add_u32 s12, s86, 0xe7b1200
	s_addc_u32 s13, s87, 0
	s_mov_b32 s3, 1
	s_mov_b64 s[16:17], 0
	v_mov_b32_e32 v0, 0
	s_branch .LBB0_2049

.LBB0_2081:
	s_ashr_i32 s0, s2, 31
	s_lshr_b32 s0, s0, 26
	s_add_i32 s0, s2, s0
	s_ashr_i32 s10, s0, 6
	s_andn2_b32 s0, s0, 63
	s_sub_i32 s8, s2, s0
	s_mul_i32 s0, s8, 0xb0000
	v_readfirstlane_b32 s9, v128
	s_lshl_b32 s11, s0, 1
	v_or_b32_e32 v3, s0, v130
	s_lshr_b32 s0, s9, 1
	s_and_b32 s0, s0, 0x1ffff80
	v_lshl_add_u32 v4, v3, 1, v140
	v_or_b32_e32 v3, s0, v189
	s_and_b32 s0, s9, 0xc0
	v_lshlrev_b32_e32 v137, 7, v3
	v_or_b32_e32 v3, s0, v189
	s_lshl_b32 s0, s9, 4
	v_add_u32_e32 v0, s11, v134
	s_and_b32 s9, s0, 0x7ffffc00
	v_add_u32_e32 v1, s11, v136
	v_and_b32_e32 v132, 0xfffffe70, v0
	s_mov_b32 m0, s9
	v_add_u32_e32 v2, s11, v138
	global_load_lds_dwordx4 v132, s[86:87]
	v_and_b32_e32 v0, 0xfffffe70, v1
	s_add_i32 m0, s9, 0x2000
	s_mul_i32 s1, s10, 0x160000
	global_load_lds_dwordx4 v0, s[86:87]
	v_and_b32_e32 v2, 0xfffffe70, v2
	s_add_i32 m0, s9, 0x4000
	v_add_u32_e32 v6, s1, v142
	s_add_i32 s0, s9, 0x8000
	global_load_lds_dwordx4 v2, s[86:87]
	v_and_b32_e32 v4, 0xfffffe70, v4
	s_add_i32 m0, s9, 0x6000
	v_add_u32_e32 v8, s1, v144
	s_waitcnt vmcnt(0)
	v_add_u32_e32 v12, s1, v148
	global_load_lds_dwordx4 v4, s[86:87]
	v_and_b32_e32 v6, 0xfffffe70, v6
	s_mov_b32 m0, s0
	v_add_u32_e32 v10, s1, v146
	global_load_lds_dwordx4 v6, s[86:87]
	v_and_b32_e32 v8, 0xfffffe70, v8
	s_add_i32 m0, s9, 0xa000
	v_and_b32_e32 v12, 0xfffffe00, v12
	global_load_lds_dwordx4 v8, s[86:87]
	v_and_b32_e32 v10, 0xfffffe70, v10
	s_add_i32 m0, s9, 0xc000
	v_or_b32_e32 v14, v150, v12
	v_mov_b32_e32 v15, v151
	global_load_lds_dwordx4 v10, s[86:87]
	v_lshl_add_u64 v[14:15], s[86:87], 0, v[14:15]
	s_add_i32 m0, s9, 0xe000
	v_lshl_or_b32 v139, v3, 7, v135
	global_load_lds_dwordx4 v[14:15], off
	s_waitcnt vmcnt(0)
	v_mov_b32_e32 v1, v133
	v_mov_b32_e32 v3, v133
	v_mov_b32_e32 v5, v133
	v_mov_b32_e32 v7, v133
	v_mov_b32_e32 v9, v133
	v_mov_b32_e32 v11, v133
	v_mov_b32_e32 v13, v133
	v_lshl_add_u64 v[154:155], s[6:7], 0, v[132:133]
	v_lshl_add_u64 v[156:157], s[6:7], 0, v[0:1]
	v_lshl_add_u64 v[158:159], s[6:7], 0, v[2:3]
	v_lshl_add_u64 v[160:161], s[6:7], 0, v[4:5]
	v_lshl_add_u64 v[162:163], s[6:7], 0, v[6:7]
	v_lshl_add_u64 v[164:165], s[6:7], 0, v[8:9]
	v_lshl_add_u64 v[166:167], s[6:7], 0, v[10:11]
	v_lshl_add_u64 v[168:169], v[152:153], 0, v[12:13]
	s_mov_b64 s[0:1], 0
	s_mov_b32 s11, 0
	s_mov_b32 s16, 0
	v_mov_b32_e32 v56, 0
	v_mov_b32_e32 v57, v133
	v_mov_b32_e32 v58, v133
	v_mov_b32_e32 v59, v133
	v_mov_b32_e32 v52, 0
	v_mov_b32_e32 v53, v133
	v_mov_b32_e32 v54, v133
	v_mov_b32_e32 v55, v133
	v_mov_b32_e32 v64, 0
	v_mov_b32_e32 v65, v133
	v_mov_b32_e32 v66, v133
	v_mov_b32_e32 v67, v133
	v_mov_b32_e32 v68, 0
	v_mov_b32_e32 v69, v133
	v_mov_b32_e32 v70, v133
	v_mov_b32_e32 v71, v133
	v_mov_b32_e32 v0, 0
	v_mov_b32_e32 v2, v133
	v_mov_b32_e32 v4, 0
	v_mov_b32_e32 v6, v133
	v_mov_b32_e32 v72, 0
	v_mov_b32_e32 v73, v133
	v_mov_b32_e32 v74, v133
	v_mov_b32_e32 v75, v133
	v_mov_b32_e32 v76, 0
	v_mov_b32_e32 v77, v133
	v_mov_b32_e32 v78, v133
	v_mov_b32_e32 v79, v133
	v_mov_b32_e32 v8, 0
	v_mov_b32_e32 v10, v133
	v_mov_b32_e32 v12, 0
	v_mov_b32_e32 v14, v133
	v_mov_b32_e32 v15, v133
	v_mov_b32_e32 v80, 0
	v_mov_b32_e32 v81, v133
	v_mov_b32_e32 v82, v133
	v_mov_b32_e32 v83, v133
	v_mov_b32_e32 v84, 0
	v_mov_b32_e32 v85, v133
	v_mov_b32_e32 v86, v133
	v_mov_b32_e32 v87, v133
	v_mov_b32_e32 v16, 0
	v_mov_b32_e32 v17, v133
	v_mov_b32_e32 v18, v133
	v_mov_b32_e32 v19, v133
	v_mov_b32_e32 v20, 0
	v_mov_b32_e32 v21, v133
	v_mov_b32_e32 v22, v133
	v_mov_b32_e32 v23, v133
	v_mov_b32_e32 v88, 0
	v_mov_b32_e32 v89, v133
	v_mov_b32_e32 v90, v133
	v_mov_b32_e32 v91, v133
	v_mov_b32_e32 v92, 0
	v_mov_b32_e32 v93, v133
	v_mov_b32_e32 v94, v133
	v_mov_b32_e32 v95, v133
	v_mov_b32_e32 v24, 0
	v_mov_b32_e32 v25, v133
	v_mov_b32_e32 v26, v133
	v_mov_b32_e32 v27, v133
	v_mov_b32_e32 v28, 0
	v_mov_b32_e32 v29, v133
	v_mov_b32_e32 v30, v133
	v_mov_b32_e32 v31, v133
	v_mov_b32_e32 v96, 0
	v_mov_b32_e32 v97, v133
	v_mov_b32_e32 v98, v133
	v_mov_b32_e32 v99, v133
	v_mov_b32_e32 v100, 0
	v_mov_b32_e32 v101, v133
	v_mov_b32_e32 v102, v133
	v_mov_b32_e32 v103, v133
	v_mov_b32_e32 v32, 0
	v_mov_b32_e32 v33, v133
	v_mov_b32_e32 v34, v133
	v_mov_b32_e32 v35, v133
	v_mov_b32_e32 v36, 0
	v_mov_b32_e32 v37, v133
	v_mov_b32_e32 v38, v133
	v_mov_b32_e32 v39, v133
	v_mov_b32_e32 v104, 0
	v_mov_b32_e32 v105, v133
	v_mov_b32_e32 v106, v133
	v_mov_b32_e32 v107, v133
	v_mov_b32_e32 v108, 0
	v_mov_b32_e32 v109, v133
	v_mov_b32_e32 v110, v133
	v_mov_b32_e32 v111, v133
	v_mov_b32_e32 v40, 0
	v_mov_b32_e32 v41, v133
	v_mov_b32_e32 v42, v133
	v_mov_b32_e32 v43, v133
	v_mov_b32_e32 v44, 0
	v_mov_b32_e32 v45, v133
	v_mov_b32_e32 v46, v133
	v_mov_b32_e32 v47, v133
	v_mov_b32_e32 v112, 0
	v_mov_b32_e32 v113, v133
	v_mov_b32_e32 v114, v133
	v_mov_b32_e32 v115, v133
	v_mov_b32_e32 v116, 0
	v_mov_b32_e32 v117, v133
	v_mov_b32_e32 v118, v133
	v_mov_b32_e32 v119, v133
	v_mov_b32_e32 v48, 0
	v_mov_b32_e32 v49, v133
	v_mov_b32_e32 v50, v133
	v_mov_b32_e32 v51, v133
	v_mov_b32_e32 v60, 0
	v_mov_b32_e32 v61, v133
	v_mov_b32_e32 v62, v133
	v_mov_b32_e32 v63, v133
	v_mov_b32_e32 v120, 0
	v_mov_b32_e32 v121, v133
	v_mov_b32_e32 v122, v133
	v_mov_b32_e32 v123, v133
	v_mov_b32_e32 v124, 0
	v_mov_b32_e32 v125, v133
	v_mov_b32_e32 v126, v133
	v_mov_b32_e32 v127, v133
	s_waitcnt vmcnt(0) lgkmcnt(0)
	s_barrier
	s_and_b32 s17, s11, 0x10000
	s_xor_b32 s18, s17, 0x10000
	s_add_i32 s18, s9, s18
	s_add_i32 s19, s18, 0x8000
	s_mov_b32 m0, s18
	v_lshl_add_u64 v[254:255], v[154:155], 0, s[0:1]
	global_load_lds_dwordx4 v[254:255], off
	s_add_i32 m0, s18, 0x2000
	v_lshl_add_u64 v[254:255], v[156:157], 0, s[0:1]
	global_load_lds_dwordx4 v[254:255], off
	s_add_i32 m0, s18, 0x4000
	v_lshl_add_u64 v[254:255], v[158:159], 0, s[0:1]
	global_load_lds_dwordx4 v[254:255], off
	s_add_i32 m0, s18, 0x6000
	v_lshl_add_u64 v[254:255], v[160:161], 0, s[0:1]
	global_load_lds_dwordx4 v[254:255], off
	s_mov_b32 m0, s19
	v_lshl_add_u64 v[254:255], v[162:163], 0, s[0:1]
	global_load_lds_dwordx4 v[254:255], off
	s_add_i32 m0, s18, 0xa000
	v_lshl_add_u64 v[254:255], v[164:165], 0, s[0:1]
	global_load_lds_dwordx4 v[254:255], off
	s_add_i32 m0, s18, 0xc000
	v_lshl_add_u64 v[254:255], v[166:167], 0, s[0:1]
	global_load_lds_dwordx4 v[254:255], off
	s_add_i32 m0, s18, 0xe000
	v_lshl_add_u64 v[254:255], v[168:169], 0, s[0:1]
	global_load_lds_dwordx4 v[254:255], off
	v_add3_u32 v253, s17, v137, v129
	ds_read_b128 v[198:201], v253 offset:0x1000
	ds_read_b128 v[202:205], v253 offset:0x1800
	ds_read_b128 v[190:193], v253 offset:0
	v_add3_u32 v253, s17, v139, v129
	ds_read_b128 v[170:173], v253 offset:0
	v_add3_u32 v253, s17, v137, v129
	ds_read_b128 v[194:197], v253 offset:0x800
	v_add3_u32 v253, s17, v139, v129
	ds_read_b128 v[174:177], v253 offset:0x800
	ds_read_b128 v[178:181], v253 offset:0x1000
	ds_read_b128 v[182:185], v253 offset:0x1800
.Lgdwn1_body:
	v_add_u32_e32 v143, s17, v139
	v_add_u32_e32 v132, s17, v137
	v_add_u32_e32 v141, v132, v129
	v_add_u32_e32 v143, v143, v131
	s_waitcnt lgkmcnt(4)
	v_add_u32_e32 v132, v132, v131
	v_mfma_f32_16x16x32_bf16 v[124:127], v[170:173], v[190:193], v[124:127]
	s_waitcnt lgkmcnt(2)
	v_mfma_f32_16x16x32_bf16 v[120:123], v[174:177], v[190:193], v[120:123]
	s_waitcnt lgkmcnt(1)
	v_mfma_f32_16x16x32_bf16 v[60:63], v[178:181], v[190:193], v[60:63]
	s_waitcnt lgkmcnt(0)
	v_mfma_f32_16x16x32_bf16 v[48:51], v[182:185], v[190:193], v[48:51]
	ds_read_b128 v[190:193], v141 offset:0x2000
	v_mfma_f32_16x16x32_bf16 v[116:119], v[170:173], v[194:197], v[116:119]
	v_mfma_f32_16x16x32_bf16 v[112:115], v[174:177], v[194:197], v[112:115]
	v_mfma_f32_16x16x32_bf16 v[44:47], v[178:181], v[194:197], v[44:47]
	v_mfma_f32_16x16x32_bf16 v[40:43], v[182:185], v[194:197], v[40:43]
	ds_read_b128 v[194:197], v141 offset:0x2800
	s_waitcnt lgkmcnt(2)
	s_nop 0
	v_mfma_f32_16x16x32_bf16 v[108:111], v[170:173], v[198:201], v[108:111]
	v_mfma_f32_16x16x32_bf16 v[104:107], v[174:177], v[198:201], v[104:107]
	v_mfma_f32_16x16x32_bf16 v[36:39], v[178:181], v[198:201], v[36:39]
	v_mfma_f32_16x16x32_bf16 v[32:35], v[182:185], v[198:201], v[32:35]
	ds_read_b128 v[198:201], v141 offset:0x3000
	v_mfma_f32_16x16x32_bf16 v[100:103], v[170:173], v[202:205], v[100:103]
	v_mfma_f32_16x16x32_bf16 v[96:99], v[174:177], v[202:205], v[96:99]
	v_mfma_f32_16x16x32_bf16 v[28:31], v[178:181], v[202:205], v[28:31]
	v_mfma_f32_16x16x32_bf16 v[24:27], v[182:185], v[202:205], v[24:27]
	ds_read_b128 v[202:205], v141 offset:0x3800
	ds_read_b128 v[206:209], v143 offset:0
	ds_read_b128 v[210:213], v143 offset:0x800
	ds_read_b128 v[214:217], v143 offset:0x1000
	ds_read_b128 v[218:221], v143 offset:0x1800
	s_waitcnt lgkmcnt(6)
	s_nop 0
	v_mfma_f32_16x16x32_bf16 v[92:95], v[170:173], v[190:193], v[92:95]
	v_mfma_f32_16x16x32_bf16 v[88:91], v[174:177], v[190:193], v[88:91]
	v_mfma_f32_16x16x32_bf16 v[20:23], v[178:181], v[190:193], v[20:23]
	v_mfma_f32_16x16x32_bf16 v[16:19], v[182:185], v[190:193], v[16:19]
	ds_read_b128 v[190:193], v132 offset:0
	v_mfma_f32_16x16x32_bf16 v[84:87], v[170:173], v[194:197], v[84:87]
	v_mfma_f32_16x16x32_bf16 v[80:83], v[174:177], v[194:197], v[80:83]
	v_mfma_f32_16x16x32_bf16 v[12:15], v[178:181], v[194:197], v[12:15]
	v_mfma_f32_16x16x32_bf16 v[8:11], v[182:185], v[194:197], v[8:11]
	ds_read_b128 v[194:197], v132 offset:0x800
	s_waitcnt lgkmcnt(6)
	s_nop 0
	v_mfma_f32_16x16x32_bf16 v[76:79], v[170:173], v[198:201], v[76:79]
	v_mfma_f32_16x16x32_bf16 v[68:71], v[170:173], v[202:205], v[68:71]
	ds_read_b128 v[170:173], v132 offset:0x1000
	v_mfma_f32_16x16x32_bf16 v[72:75], v[174:177], v[198:201], v[72:75]
	v_mfma_f32_16x16x32_bf16 v[64:67], v[174:177], v[202:205], v[64:67]
	ds_read_b128 v[174:177], v132 offset:0x1800
	s_waitcnt lgkmcnt(2)
	v_mfma_f32_16x16x32_bf16 v[4:7], v[178:181], v[198:201], v[4:7]
	v_mfma_f32_16x16x32_bf16 v[52:55], v[178:181], v[202:205], v[52:55]
	ds_read_b128 v[178:181], v132 offset:0x2000
	v_mfma_f32_16x16x32_bf16 v[0:3], v[182:185], v[198:201], v[0:3]
	v_mfma_f32_16x16x32_bf16 v[56:59], v[182:185], v[202:205], v[56:59]
	ds_read_b128 v[182:185], v132 offset:0x2800
	s_waitcnt lgkmcnt(2)
	s_nop 0
	v_mfma_f32_16x16x32_bf16 v[108:111], v[206:209], v[170:173], v[108:111]
	v_mfma_f32_16x16x32_bf16 v[104:107], v[210:213], v[170:173], v[104:107]
	v_mfma_f32_16x16x32_bf16 v[36:39], v[214:217], v[170:173], v[36:39]
	v_mfma_f32_16x16x32_bf16 v[32:35], v[218:221], v[170:173], v[32:35]
	ds_read_b128 v[170:173], v132 offset:0x3000
	v_mfma_f32_16x16x32_bf16 v[100:103], v[206:209], v[174:177], v[100:103]
	v_mfma_f32_16x16x32_bf16 v[96:99], v[210:213], v[174:177], v[96:99]
	v_mfma_f32_16x16x32_bf16 v[28:31], v[214:217], v[174:177], v[28:31]
	v_mfma_f32_16x16x32_bf16 v[24:27], v[218:221], v[174:177], v[24:27]
	ds_read_b128 v[174:177], v132 offset:0x3800
	s_waitcnt lgkmcnt(2)
	v_mfma_f32_16x16x32_bf16 v[124:127], v[206:209], v[190:193], v[124:127]
	s_add_i32 s11, s11, 0x10000
	s_add_u32 s0, s0, 0x80
	s_addc_u32 s1, s1, 0
	s_add_i32 s16, s16, 1
	s_waitcnt lgkmcnt(0)
	s_waitcnt vmcnt(0)
	s_waitcnt vmcnt(0) lgkmcnt(0)
	v_mfma_f32_16x16x32_bf16 v[120:123], v[210:213], v[190:193], v[120:123]
	s_barrier
	s_cmp_gt_u32 s16, 42
	s_cbranch_scc1 .Lgdwn1_nodma
	s_and_b32 s17, s11, 0x10000
	s_xor_b32 s18, s17, 0x10000
	s_add_i32 s18, s9, s18
	s_add_i32 s19, s18, 0x8000
	v_add3_u32 v253, s17, v137, v129
	ds_read_b128 v[198:201], v253 offset:0x1000
	ds_read_b128 v[202:205], v253 offset:0x1800
	v_mfma_f32_16x16x32_bf16 v[60:63], v[214:217], v[190:193], v[60:63]
	s_mov_b32 m0, s18
	v_lshl_add_u64 v[254:255], v[154:155], 0, s[0:1]
	global_load_lds_dwordx4 v[254:255], off
	v_mfma_f32_16x16x32_bf16 v[48:51], v[218:221], v[190:193], v[48:51]
	ds_read_b128 v[190:193], v253 offset:0
	v_mfma_f32_16x16x32_bf16 v[76:79], v[206:209], v[170:173], v[76:79]
	s_add_i32 m0, s18, 0x2000
	v_lshl_add_u64 v[254:255], v[156:157], 0, s[0:1]
	global_load_lds_dwordx4 v[254:255], off
	v_mfma_f32_16x16x32_bf16 v[72:75], v[210:213], v[170:173], v[72:75]
	v_mfma_f32_16x16x32_bf16 v[4:7], v[214:217], v[170:173], v[4:7]
	s_add_i32 m0, s18, 0x4000
	v_lshl_add_u64 v[254:255], v[158:159], 0, s[0:1]
	global_load_lds_dwordx4 v[254:255], off
	v_mfma_f32_16x16x32_bf16 v[0:3], v[218:221], v[170:173], v[0:3]
	v_add3_u32 v253, s17, v139, v129
	ds_read_b128 v[170:173], v253 offset:0
	v_mfma_f32_16x16x32_bf16 v[116:119], v[206:209], v[194:197], v[116:119]
	s_add_i32 m0, s18, 0x6000
	v_lshl_add_u64 v[254:255], v[160:161], 0, s[0:1]
	global_load_lds_dwordx4 v[254:255], off
	v_mfma_f32_16x16x32_bf16 v[112:115], v[210:213], v[194:197], v[112:115]
	v_mfma_f32_16x16x32_bf16 v[44:47], v[214:217], v[194:197], v[44:47]
	s_mov_b32 m0, s19
	v_lshl_add_u64 v[254:255], v[162:163], 0, s[0:1]
	global_load_lds_dwordx4 v[254:255], off
	v_mfma_f32_16x16x32_bf16 v[40:43], v[218:221], v[194:197], v[40:43]
	v_add3_u32 v253, s17, v137, v129
	ds_read_b128 v[194:197], v253 offset:0x800
	v_mfma_f32_16x16x32_bf16 v[68:71], v[206:209], v[174:177], v[68:71]
	s_add_i32 m0, s18, 0xa000
	v_lshl_add_u64 v[254:255], v[164:165], 0, s[0:1]
	global_load_lds_dwordx4 v[254:255], off
	v_mfma_f32_16x16x32_bf16 v[64:67], v[210:213], v[174:177], v[64:67]
	v_mfma_f32_16x16x32_bf16 v[52:55], v[214:217], v[174:177], v[52:55]
	s_add_i32 m0, s18, 0xc000
	v_lshl_add_u64 v[254:255], v[166:167], 0, s[0:1]
	global_load_lds_dwordx4 v[254:255], off
	v_mfma_f32_16x16x32_bf16 v[56:59], v[218:221], v[174:177], v[56:59]
	v_add3_u32 v253, s17, v139, v129
	ds_read_b128 v[174:177], v253 offset:0x800
	v_mfma_f32_16x16x32_bf16 v[92:95], v[206:209], v[178:181], v[92:95]
	s_add_i32 m0, s18, 0xe000
	v_lshl_add_u64 v[254:255], v[168:169], 0, s[0:1]
	global_load_lds_dwordx4 v[254:255], off
	v_mfma_f32_16x16x32_bf16 v[88:91], v[210:213], v[178:181], v[88:91]
	v_mfma_f32_16x16x32_bf16 v[20:23], v[214:217], v[178:181], v[20:23]
	v_mfma_f32_16x16x32_bf16 v[16:19], v[218:221], v[178:181], v[16:19]
	ds_read_b128 v[178:181], v253 offset:0x1000
	v_mfma_f32_16x16x32_bf16 v[84:87], v[206:209], v[182:185], v[84:87]
	v_mfma_f32_16x16x32_bf16 v[80:83], v[210:213], v[182:185], v[80:83]
	v_mfma_f32_16x16x32_bf16 v[12:15], v[214:217], v[182:185], v[12:15]
	v_mfma_f32_16x16x32_bf16 v[8:11], v[218:221], v[182:185], v[8:11]
	ds_read_b128 v[182:185], v253 offset:0x1800
	s_branch .Lgdwn1_body
.Lgdwn1_nodma:
	s_and_b32 s17, s11, 0x10000
	v_add3_u32 v253, s17, v137, v129
	ds_read_b128 v[198:201], v253 offset:0x1000
	ds_read_b128 v[202:205], v253 offset:0x1800
	v_mfma_f32_16x16x32_bf16 v[60:63], v[214:217], v[190:193], v[60:63]
	v_mfma_f32_16x16x32_bf16 v[48:51], v[218:221], v[190:193], v[48:51]
	ds_read_b128 v[190:193], v253 offset:0
	v_mfma_f32_16x16x32_bf16 v[76:79], v[206:209], v[170:173], v[76:79]
	v_mfma_f32_16x16x32_bf16 v[72:75], v[210:213], v[170:173], v[72:75]
	v_mfma_f32_16x16x32_bf16 v[4:7], v[214:217], v[170:173], v[4:7]
	v_mfma_f32_16x16x32_bf16 v[0:3], v[218:221], v[170:173], v[0:3]
	v_add3_u32 v253, s17, v139, v129
	ds_read_b128 v[170:173], v253 offset:0
	v_mfma_f32_16x16x32_bf16 v[116:119], v[206:209], v[194:197], v[116:119]
	v_mfma_f32_16x16x32_bf16 v[112:115], v[210:213], v[194:197], v[112:115]
	v_mfma_f32_16x16x32_bf16 v[44:47], v[214:217], v[194:197], v[44:47]
	v_mfma_f32_16x16x32_bf16 v[40:43], v[218:221], v[194:197], v[40:43]
	v_add3_u32 v253, s17, v137, v129
	ds_read_b128 v[194:197], v253 offset:0x800
	v_mfma_f32_16x16x32_bf16 v[68:71], v[206:209], v[174:177], v[68:71]
	v_mfma_f32_16x16x32_bf16 v[64:67], v[210:213], v[174:177], v[64:67]
	v_mfma_f32_16x16x32_bf16 v[52:55], v[214:217], v[174:177], v[52:55]
	v_mfma_f32_16x16x32_bf16 v[56:59], v[218:221], v[174:177], v[56:59]
	v_add3_u32 v253, s17, v139, v129
	ds_read_b128 v[174:177], v253 offset:0x800
	v_mfma_f32_16x16x32_bf16 v[92:95], v[206:209], v[178:181], v[92:95]
	v_mfma_f32_16x16x32_bf16 v[88:91], v[210:213], v[178:181], v[88:91]
	v_mfma_f32_16x16x32_bf16 v[20:23], v[214:217], v[178:181], v[20:23]
	v_mfma_f32_16x16x32_bf16 v[16:19], v[218:221], v[178:181], v[16:19]
	ds_read_b128 v[178:181], v253 offset:0x1000
	v_mfma_f32_16x16x32_bf16 v[84:87], v[206:209], v[182:185], v[84:87]
	v_mfma_f32_16x16x32_bf16 v[80:83], v[210:213], v[182:185], v[80:83]
	v_mfma_f32_16x16x32_bf16 v[12:15], v[214:217], v[182:185], v[12:15]
	v_mfma_f32_16x16x32_bf16 v[8:11], v[218:221], v[182:185], v[8:11]
	ds_read_b128 v[182:185], v253 offset:0x1800
	v_add_u32_e32 v143, s17, v139
	v_add_u32_e32 v132, s17, v137
	v_add_u32_e32 v141, v132, v129
	v_add_u32_e32 v143, v143, v131
	s_waitcnt lgkmcnt(4)
	v_add_u32_e32 v132, v132, v131
	v_mfma_f32_16x16x32_bf16 v[124:127], v[170:173], v[190:193], v[124:127]
	s_waitcnt lgkmcnt(2)
	v_mfma_f32_16x16x32_bf16 v[120:123], v[174:177], v[190:193], v[120:123]
	s_waitcnt lgkmcnt(1)
	v_mfma_f32_16x16x32_bf16 v[60:63], v[178:181], v[190:193], v[60:63]
	s_waitcnt lgkmcnt(0)
	v_mfma_f32_16x16x32_bf16 v[48:51], v[182:185], v[190:193], v[48:51]
	ds_read_b128 v[190:193], v141 offset:0x2000
	v_mfma_f32_16x16x32_bf16 v[116:119], v[170:173], v[194:197], v[116:119]
	v_mfma_f32_16x16x32_bf16 v[112:115], v[174:177], v[194:197], v[112:115]
	v_mfma_f32_16x16x32_bf16 v[44:47], v[178:181], v[194:197], v[44:47]
	v_mfma_f32_16x16x32_bf16 v[40:43], v[182:185], v[194:197], v[40:43]
	ds_read_b128 v[194:197], v141 offset:0x2800
	s_waitcnt lgkmcnt(2)
	s_nop 0
	v_mfma_f32_16x16x32_bf16 v[108:111], v[170:173], v[198:201], v[108:111]
	v_mfma_f32_16x16x32_bf16 v[104:107], v[174:177], v[198:201], v[104:107]
	v_mfma_f32_16x16x32_bf16 v[36:39], v[178:181], v[198:201], v[36:39]
	v_mfma_f32_16x16x32_bf16 v[32:35], v[182:185], v[198:201], v[32:35]
	ds_read_b128 v[198:201], v141 offset:0x3000
	v_mfma_f32_16x16x32_bf16 v[100:103], v[170:173], v[202:205], v[100:103]
	v_mfma_f32_16x16x32_bf16 v[96:99], v[174:177], v[202:205], v[96:99]
	v_mfma_f32_16x16x32_bf16 v[28:31], v[178:181], v[202:205], v[28:31]
	v_mfma_f32_16x16x32_bf16 v[24:27], v[182:185], v[202:205], v[24:27]
	ds_read_b128 v[202:205], v141 offset:0x3800
	ds_read_b128 v[206:209], v143 offset:0
	ds_read_b128 v[210:213], v143 offset:0x800
	ds_read_b128 v[214:217], v143 offset:0x1000
	ds_read_b128 v[218:221], v143 offset:0x1800
	s_waitcnt lgkmcnt(6)
	s_nop 0
	v_mfma_f32_16x16x32_bf16 v[92:95], v[170:173], v[190:193], v[92:95]
	v_mfma_f32_16x16x32_bf16 v[88:91], v[174:177], v[190:193], v[88:91]
	v_mfma_f32_16x16x32_bf16 v[20:23], v[178:181], v[190:193], v[20:23]
	v_mfma_f32_16x16x32_bf16 v[16:19], v[182:185], v[190:193], v[16:19]
	ds_read_b128 v[190:193], v132 offset:0
	v_mfma_f32_16x16x32_bf16 v[84:87], v[170:173], v[194:197], v[84:87]
	v_mfma_f32_16x16x32_bf16 v[80:83], v[174:177], v[194:197], v[80:83]
	v_mfma_f32_16x16x32_bf16 v[12:15], v[178:181], v[194:197], v[12:15]
	v_mfma_f32_16x16x32_bf16 v[8:11], v[182:185], v[194:197], v[8:11]
	ds_read_b128 v[194:197], v132 offset:0x800
	s_waitcnt lgkmcnt(6)
	s_nop 0
	v_mfma_f32_16x16x32_bf16 v[76:79], v[170:173], v[198:201], v[76:79]
	v_mfma_f32_16x16x32_bf16 v[68:71], v[170:173], v[202:205], v[68:71]
	ds_read_b128 v[170:173], v132 offset:0x1000
	v_mfma_f32_16x16x32_bf16 v[72:75], v[174:177], v[198:201], v[72:75]
	v_mfma_f32_16x16x32_bf16 v[64:67], v[174:177], v[202:205], v[64:67]
	ds_read_b128 v[174:177], v132 offset:0x1800
	s_waitcnt lgkmcnt(2)
	v_mfma_f32_16x16x32_bf16 v[4:7], v[178:181], v[198:201], v[4:7]
	v_mfma_f32_16x16x32_bf16 v[52:55], v[178:181], v[202:205], v[52:55]
	ds_read_b128 v[178:181], v132 offset:0x2000
	v_mfma_f32_16x16x32_bf16 v[0:3], v[182:185], v[198:201], v[0:3]
	v_mfma_f32_16x16x32_bf16 v[56:59], v[182:185], v[202:205], v[56:59]
	ds_read_b128 v[182:185], v132 offset:0x2800
	s_waitcnt lgkmcnt(2)
	s_nop 0
	v_mfma_f32_16x16x32_bf16 v[108:111], v[206:209], v[170:173], v[108:111]
	v_mfma_f32_16x16x32_bf16 v[104:107], v[210:213], v[170:173], v[104:107]
	v_mfma_f32_16x16x32_bf16 v[36:39], v[214:217], v[170:173], v[36:39]
	v_mfma_f32_16x16x32_bf16 v[32:35], v[218:221], v[170:173], v[32:35]
	ds_read_b128 v[170:173], v132 offset:0x3000
	v_mfma_f32_16x16x32_bf16 v[100:103], v[206:209], v[174:177], v[100:103]
	v_mfma_f32_16x16x32_bf16 v[96:99], v[210:213], v[174:177], v[96:99]
	v_mfma_f32_16x16x32_bf16 v[28:31], v[214:217], v[174:177], v[28:31]
	v_mfma_f32_16x16x32_bf16 v[24:27], v[218:221], v[174:177], v[24:27]
	ds_read_b128 v[174:177], v132 offset:0x3800
	s_waitcnt lgkmcnt(2)
	v_mfma_f32_16x16x32_bf16 v[124:127], v[206:209], v[190:193], v[124:127]
	s_add_i32 s11, s11, 0x10000
	s_add_u32 s0, s0, 0x80
	s_addc_u32 s1, s1, 0
	s_add_i32 s16, s16, 1
	s_waitcnt lgkmcnt(0)
	s_waitcnt vmcnt(0)
	s_waitcnt vmcnt(0) lgkmcnt(0)
	v_mfma_f32_16x16x32_bf16 v[120:123], v[210:213], v[190:193], v[120:123]
	s_barrier
	v_mfma_f32_16x16x32_bf16 v[60:63], v[214:217], v[190:193], v[60:63]
	v_mfma_f32_16x16x32_bf16 v[48:51], v[218:221], v[190:193], v[48:51]
	v_mfma_f32_16x16x32_bf16 v[116:119], v[206:209], v[194:197], v[116:119]
	v_mfma_f32_16x16x32_bf16 v[112:115], v[210:213], v[194:197], v[112:115]
	v_mfma_f32_16x16x32_bf16 v[44:47], v[214:217], v[194:197], v[44:47]
	v_mfma_f32_16x16x32_bf16 v[40:43], v[218:221], v[194:197], v[40:43]
	v_mfma_f32_16x16x32_bf16 v[92:95], v[206:209], v[178:181], v[92:95]
	v_mfma_f32_16x16x32_bf16 v[88:91], v[210:213], v[178:181], v[88:91]
	v_mfma_f32_16x16x32_bf16 v[20:23], v[214:217], v[178:181], v[20:23]
	v_mfma_f32_16x16x32_bf16 v[16:19], v[218:221], v[178:181], v[16:19]
	v_mfma_f32_16x16x32_bf16 v[84:87], v[206:209], v[182:185], v[84:87]
	v_mfma_f32_16x16x32_bf16 v[80:83], v[210:213], v[182:185], v[80:83]
	v_mfma_f32_16x16x32_bf16 v[12:15], v[214:217], v[182:185], v[12:15]
	v_mfma_f32_16x16x32_bf16 v[8:11], v[218:221], v[182:185], v[8:11]
	v_mfma_f32_16x16x32_bf16 v[76:79], v[206:209], v[170:173], v[76:79]
	v_mfma_f32_16x16x32_bf16 v[72:75], v[210:213], v[170:173], v[72:75]
	v_mfma_f32_16x16x32_bf16 v[4:7], v[214:217], v[170:173], v[4:7]
	v_mfma_f32_16x16x32_bf16 v[0:3], v[218:221], v[170:173], v[0:3]
	v_mfma_f32_16x16x32_bf16 v[68:71], v[206:209], v[174:177], v[68:71]
	v_mfma_f32_16x16x32_bf16 v[64:67], v[210:213], v[174:177], v[64:67]
	v_mfma_f32_16x16x32_bf16 v[52:55], v[214:217], v[174:177], v[52:55]
	v_mfma_f32_16x16x32_bf16 v[56:59], v[218:221], v[174:177], v[56:59]
